# GDN scan rewrite + nt (streaming) hint on the prologue's read-once f32 weight loads
# baseline (speedup 1.0000x reference)
.LBB0_18:
	s_ashr_i32 s0, s14, 6
	s_mul_hi_i32 s1, s0, 0x2aaaaaab
	s_lshr_b32 s12, s1, 31
	s_ashr_i32 s1, s1, 2
	s_add_i32 s1, s1, s12
	s_mul_i32 s12, s1, 24
	s_sub_i32 s0, s0, s12
	s_lshl_b32 s1, s1, 9
	s_and_b32 s12, s17, 0x1c0
	s_or_b32 s12, s1, s12
	s_lshl_b32 s0, s0, 8
	s_and_b32 s1, s15, 0xe0
	s_or_b32 s24, s0, s1
	v_or_b32_e32 v2, s24, v1
	s_ashr_i32 s13, s12, 31
	s_mul_i32 s0, s12, 0xd140
	v_cmp_gt_i32_e32 vcc, s19, v2
	s_mul_hi_i32 s1, s12, 0xd140
	s_add_u32 s0, s4, s0
	v_cndmask_b32_e32 v2, 0, v2, vcc
	s_addc_u32 s1, s5, s1
	v_ashrrev_i32_e32 v3, 31, v2
	v_lshl_add_u64 v[2:3], v[2:3], 2, s[0:1]
	v_lshl_add_u64 v[4:5], v[2:3], 0, v[26:27]
	v_lshl_add_u64 v[6:7], v[2:3], 0, v[28:29]
	v_lshl_add_u64 v[8:9], v[2:3], 0, v[30:31]
	v_lshl_add_u64 v[78:79], v[2:3], 0, v[32:33]
	v_lshl_add_u64 v[80:81], v[2:3], 0, v[34:35]
	v_lshl_add_u64 v[82:83], v[2:3], 0, v[36:37]
	v_lshl_add_u64 v[84:85], v[2:3], 0, v[38:39]
	v_lshl_add_u64 v[86:87], v[2:3], 0, v[40:41]
	global_load_dword v88, v[4:5], off nt
	global_load_dword v89, v[6:7], off nt
	global_load_dword v90, v[8:9], off nt
	global_load_dword v91, v[78:79], off nt
	global_load_dword v92, v[80:81], off nt
	global_load_dword v93, v[82:83], off nt
	global_load_dword v94, v[84:85], off nt
	global_load_dword v95, v[86:87], off nt
	v_lshl_add_u64 v[4:5], v[2:3], 0, v[42:43]
	v_mov_b32_e32 v53, v11
	v_mov_b32_e32 v55, v11
	v_lshl_add_u64 v[6:7], v[2:3], 0, v[44:45]
	v_lshl_add_u64 v[8:9], v[2:3], 0, v[46:47]
	v_lshl_add_u64 v[78:79], v[2:3], 0, v[48:49]
	v_lshl_add_u64 v[80:81], v[2:3], 0, v[50:51]
	v_lshl_add_u64 v[82:83], v[2:3], 0, v[10:11]
	v_lshl_add_u64 v[84:85], v[2:3], 0, v[52:53]
	v_lshl_add_u64 v[86:87], v[2:3], 0, v[54:55]
	global_load_dword v53, v[4:5], off nt
	global_load_dword v55, v[6:7], off nt
	global_load_dword v96, v[8:9], off nt
	global_load_dword v97, v[78:79], off nt
	global_load_dword v98, v[80:81], off nt
	global_load_dword v99, v[82:83], off nt
	global_load_dword v100, v[84:85], off nt
	global_load_dword v101, v[86:87], off nt
	v_lshl_add_u64 v[4:5], v[2:3], 0, v[18:19]
	v_lshl_add_u64 v[6:7], v[2:3], 0, v[20:21]
	v_lshl_add_u64 v[8:9], v[2:3], 0, v[22:23]
	v_lshl_add_u64 v[78:79], v[2:3], 0, v[24:25]
	global_load_dword v102, v[4:5], off nt
	global_load_dword v103, v[6:7], off nt
	global_load_dword v104, v[8:9], off nt
	global_load_dword v105, v[78:79], off nt
	v_mov_b32_e32 v57, v11
	v_mov_b32_e32 v59, v11
	v_mov_b32_e32 v61, v11
	v_mov_b32_e32 v63, v11
	v_mov_b32_e32 v65, v11
	v_mov_b32_e32 v67, v11
	v_mov_b32_e32 v69, v11
	v_mov_b32_e32 v71, v11
	v_lshl_add_u64 v[4:5], v[2:3], 0, v[56:57]
	v_lshl_add_u64 v[6:7], v[2:3], 0, v[58:59]
	v_lshl_add_u64 v[8:9], v[2:3], 0, v[60:61]
	v_lshl_add_u64 v[78:79], v[2:3], 0, v[62:63]
	v_lshl_add_u64 v[80:81], v[2:3], 0, v[64:65]
	v_lshl_add_u64 v[82:83], v[2:3], 0, v[66:67]
	v_lshl_add_u64 v[84:85], v[2:3], 0, v[68:69]
	v_lshl_add_u64 v[86:87], v[2:3], 0, v[70:71]
	v_lshl_add_u64 v[2:3], v[2:3], 0, v[16:17]
	global_load_dword v57, v[4:5], off nt
	global_load_dword v59, v[6:7], off nt
	s_nop 0
	global_load_dword v8, v[8:9], off nt
	s_nop 0
	global_load_dword v9, v[78:79], off nt
	global_load_dword v61, v[80:81], off nt
	global_load_dword v63, v[82:83], off nt
	global_load_dword v65, v[84:85], off nt
	global_load_dword v67, v[86:87], off nt
	v_add_co_u32_e64 v4, s[0:1], s20, v2
	s_nop 1
	v_addc_co_u32_e64 v5, s[0:1], 0, v3, s[0:1]
	v_add_co_u32_e64 v6, s[0:1], s21, v2
	global_load_dword v69, v[2:3], off nt
	s_nop 0
	global_load_dword v4, v[4:5], off offset:640
	v_addc_co_u32_e64 v7, s[0:1], 0, v3, s[0:1]
	v_add_co_u32_e64 v2, s[0:1], s22, v2
	s_waitcnt vmcnt(0)
	v_cndmask_b32_e32 v4, 0, v4, vcc
	v_addc_co_u32_e64 v3, s[0:1], 0, v3, s[0:1]
	global_load_dword v5, v[6:7], off offset:1280
	s_nop 0
	global_load_dword v2, v[2:3], off offset:1920
	v_cndmask_b32_e32 v3, 0, v88, vcc
	v_cndmask_b32_e32 v6, 0, v89, vcc
	v_add_u32_e32 v7, 0x800, v74
	ds_write2_b32 v7, v3, v6 offset0:16 offset1:82
	v_cndmask_b32_e32 v3, 0, v90, vcc
	v_cndmask_b32_e32 v6, 0, v91, vcc
	ds_write2_b32 v7, v3, v6 offset0:148 offset1:214
	v_cndmask_b32_e32 v3, 0, v92, vcc
	v_cndmask_b32_e32 v6, 0, v93, vcc
	v_add_u32_e32 v7, 0xc00, v74
	ds_write2_b32 v7, v3, v6 offset0:24 offset1:90
	v_cndmask_b32_e32 v3, 0, v94, vcc
	v_cndmask_b32_e32 v6, 0, v95, vcc
	ds_write2_b32 v7, v3, v6 offset0:156 offset1:222
	v_cndmask_b32_e32 v3, 0, v53, vcc
	v_cndmask_b32_e32 v6, 0, v55, vcc
	v_add_u32_e32 v7, 0x1000, v74
	ds_write2_b32 v7, v3, v6 offset0:32 offset1:98
	v_cndmask_b32_e32 v3, 0, v96, vcc
	v_cndmask_b32_e32 v6, 0, v97, vcc
	ds_write2_b32 v7, v3, v6 offset0:164 offset1:230
	v_cndmask_b32_e32 v3, 0, v102, vcc
	v_cndmask_b32_e32 v6, 0, v103, vcc
	v_add_u32_e32 v7, 0x400, v74
	ds_write2_b32 v7, v3, v6 offset0:8 offset1:74
	v_cndmask_b32_e32 v3, 0, v104, vcc
	v_cndmask_b32_e32 v6, 0, v105, vcc
	ds_write2_b32 v7, v3, v6 offset0:140 offset1:206
	v_cndmask_b32_e32 v3, 0, v98, vcc
	v_cndmask_b32_e32 v6, 0, v99, vcc
	v_add_u32_e32 v7, 0x1400, v74
	ds_write2_b32 v7, v3, v6 offset0:40 offset1:106
	v_cndmask_b32_e32 v3, 0, v100, vcc
	v_cndmask_b32_e32 v6, 0, v101, vcc
	ds_write2_b32 v7, v3, v6 offset0:172 offset1:238
	v_cndmask_b32_e32 v3, 0, v57, vcc
	v_cndmask_b32_e32 v6, 0, v59, vcc
	v_add_u32_e32 v7, 0x1800, v74
	ds_write2_b32 v7, v3, v6 offset0:48 offset1:114
	v_cndmask_b32_e32 v3, 0, v8, vcc
	v_cndmask_b32_e32 v6, 0, v9, vcc
	ds_write2_b32 v7, v3, v6 offset0:180 offset1:246
	v_cndmask_b32_e32 v3, 0, v61, vcc
	v_cndmask_b32_e32 v6, 0, v63, vcc
	v_add_u32_e32 v7, 0x1c00, v74
	ds_write2_b32 v7, v3, v6 offset0:56 offset1:122
	v_cndmask_b32_e32 v3, 0, v65, vcc
	v_cndmask_b32_e32 v6, 0, v67, vcc
	ds_write2_b32 v7, v3, v6 offset0:188 offset1:254
	v_cndmask_b32_e32 v3, 0, v69, vcc
	ds_write2_b32 v74, v3, v4 offset1:66
	s_waitcnt vmcnt(1)
	v_cndmask_b32_e32 v3, 0, v5, vcc
	s_waitcnt vmcnt(0)
	v_cndmask_b32_e32 v2, 0, v2, vcc
	ds_write2_b32 v74, v3, v2 offset0:132 offset1:198
	s_waitcnt lgkmcnt(0)
	s_andn2_b64 vcc, exec, s[10:11]
	s_cbranch_vccz .LBB0_16
	v_mov_b32_e32 v2, 1.0
	v_mov_b32_e32 v3, v2
	v_mov_b32_e32 v4, v2
	v_mov_b32_e32 v5, v2
	v_mov_b32_e32 v6, v2
	v_mov_b32_e32 v7, v2
	v_mov_b32_e32 v8, v2
	v_mov_b32_e32 v9, v2
	s_branch .LBB0_17

.LBB0_24:
	s_ashr_i32 s0, s15, 6
	s_mul_hi_i32 s1, s0, 0x92492493
	s_add_i32 s1, s1, s0
	s_lshr_b32 s12, s1, 31
	s_ashr_i32 s1, s1, 4
	s_add_i32 s1, s1, s12
	s_mul_i32 s12, s1, 28
	s_sub_i32 s0, s0, s12
	s_lshl_b32 s1, s1, 9
	s_and_b32 s12, s20, 0x1c0
	s_or_b32 s12, s1, s12
	s_lshl_b32 s0, s0, 8
	s_and_b32 s1, s18, 0xe0
	s_or_b32 s30, s0, s1
	v_or_b32_e32 v2, s30, v1
	s_ashr_i32 s13, s12, 31
	s_mul_i32 s0, s12, 0xd140
	v_cmp_gt_i32_e32 vcc, s22, v2
	s_mul_hi_i32 s1, s12, 0xd140
	s_add_u32 s0, s16, s0
	v_cndmask_b32_e32 v2, 0, v2, vcc
	s_addc_u32 s1, s17, s1
	v_ashrrev_i32_e32 v3, 31, v2
	v_lshl_add_u64 v[2:3], v[2:3], 2, s[0:1]
	v_lshl_add_u64 v[4:5], v[2:3], 0, v[16:17]
	v_add_co_u32_e64 v6, s[0:1], s24, v4
	v_lshl_add_u64 v[80:81], v[2:3], 0, v[18:19]
	s_nop 0
	v_addc_co_u32_e64 v7, s[0:1], 0, v5, s[0:1]
	v_add_co_u32_e64 v8, s[0:1], s25, v4
	v_lshl_add_u64 v[82:83], v[2:3], 0, v[20:21]
	s_nop 0
	v_addc_co_u32_e64 v9, s[0:1], 0, v5, s[0:1]
	v_add_co_u32_e64 v78, s[0:1], s29, v4
	v_lshl_add_u64 v[84:85], v[2:3], 0, v[22:23]
	s_nop 0
	v_addc_co_u32_e64 v79, s[0:1], 0, v5, s[0:1]
	v_lshl_add_u64 v[86:87], v[2:3], 0, v[24:25]
	global_load_dword v88, v[4:5], off nt
	global_load_dword v89, v[6:7], off offset:640
	global_load_dword v90, v[8:9], off offset:1280
	global_load_dword v91, v[78:79], off offset:1920
	global_load_dword v92, v[80:81], off nt
	global_load_dword v93, v[82:83], off nt
	global_load_dword v94, v[84:85], off nt
	global_load_dword v95, v[86:87], off nt
	v_lshl_add_u64 v[4:5], v[2:3], 0, v[26:27]
	v_lshl_add_u64 v[6:7], v[2:3], 0, v[28:29]
	v_lshl_add_u64 v[8:9], v[2:3], 0, v[30:31]
	v_lshl_add_u64 v[78:79], v[2:3], 0, v[32:33]
	v_lshl_add_u64 v[80:81], v[2:3], 0, v[34:35]
	v_lshl_add_u64 v[82:83], v[2:3], 0, v[36:37]
	v_lshl_add_u64 v[84:85], v[2:3], 0, v[38:39]
	v_lshl_add_u64 v[86:87], v[2:3], 0, v[40:41]
	global_load_dword v96, v[4:5], off nt
	global_load_dword v97, v[6:7], off nt
	global_load_dword v98, v[8:9], off nt
	global_load_dword v99, v[78:79], off nt
	global_load_dword v100, v[80:81], off nt
	global_load_dword v101, v[82:83], off nt
	global_load_dword v102, v[84:85], off nt
	global_load_dword v103, v[86:87], off nt
	v_lshl_add_u64 v[4:5], v[2:3], 0, v[42:43]
	v_lshl_add_u64 v[80:81], v[2:3], 0, v[50:51]
	v_lshl_add_u64 v[82:83], v[2:3], 0, v[10:11]
	v_mov_b32_e32 v53, v11
	v_mov_b32_e32 v55, v11
	v_mov_b32_e32 v57, v11
	v_lshl_add_u64 v[6:7], v[2:3], 0, v[44:45]
	v_lshl_add_u64 v[8:9], v[2:3], 0, v[46:47]
	v_lshl_add_u64 v[78:79], v[2:3], 0, v[48:49]
	v_lshl_add_u64 v[84:85], v[2:3], 0, v[52:53]
	v_lshl_add_u64 v[86:87], v[2:3], 0, v[54:55]
	global_load_dword v53, v[4:5], off nt
	global_load_dword v55, v[6:7], off nt
	global_load_dword v104, v[8:9], off nt
	global_load_dword v105, v[78:79], off nt
	s_nop 0
	global_load_dword v80, v[80:81], off nt
	s_nop 0
	global_load_dword v81, v[82:83], off nt
	s_nop 0
	global_load_dword v82, v[84:85], off nt
	global_load_dword v83, v[86:87], off nt
	v_lshl_add_u64 v[4:5], v[2:3], 0, v[56:57]
	v_mov_b32_e32 v59, v11
	v_lshl_add_u64 v[6:7], v[2:3], 0, v[58:59]
	global_load_dword v57, v[4:5], off nt
	global_load_dword v59, v[6:7], off nt
	v_mov_b32_e32 v61, v11
	v_mov_b32_e32 v63, v11
	v_mov_b32_e32 v65, v11
	v_lshl_add_u64 v[4:5], v[2:3], 0, v[60:61]
	v_lshl_add_u64 v[6:7], v[2:3], 0, v[62:63]
	v_lshl_add_u64 v[8:9], v[2:3], 0, v[64:65]
	v_mov_b32_e32 v67, v11
	v_mov_b32_e32 v69, v11
	v_mov_b32_e32 v71, v11
	v_lshl_add_u64 v[78:79], v[2:3], 0, v[66:67]
	global_load_dword v61, v[4:5], off nt
	s_nop 0
	global_load_dword v6, v[6:7], off nt
	s_nop 0
	global_load_dword v7, v[8:9], off nt
	s_nop 0
	global_load_dword v8, v[78:79], off nt
	v_lshl_add_u64 v[4:5], v[2:3], 0, v[68:69]
	v_lshl_add_u64 v[2:3], v[2:3], 0, v[70:71]
	global_load_dword v4, v[4:5], off nt
	s_nop 0
	global_load_dword v2, v[2:3], off nt
	v_add_u32_e32 v9, 0x400, v77
	s_waitcnt vmcnt(31)
	v_cndmask_b32_e32 v3, 0, v88, vcc
	s_waitcnt vmcnt(30)
	v_cndmask_b32_e32 v5, 0, v89, vcc
	ds_write2_b32 v77, v3, v5 offset1:66
	s_waitcnt vmcnt(29)
	v_cndmask_b32_e32 v3, 0, v90, vcc
	s_waitcnt vmcnt(28)
	v_cndmask_b32_e32 v5, 0, v91, vcc
	ds_write2_b32 v77, v3, v5 offset0:132 offset1:198
	s_waitcnt vmcnt(27)
	v_cndmask_b32_e32 v3, 0, v92, vcc
	s_waitcnt vmcnt(26)
	v_cndmask_b32_e32 v5, 0, v93, vcc
	ds_write2_b32 v9, v3, v5 offset0:8 offset1:74
	s_waitcnt vmcnt(25)
	v_cndmask_b32_e32 v3, 0, v94, vcc
	s_waitcnt vmcnt(24)
	v_cndmask_b32_e32 v5, 0, v95, vcc
	ds_write2_b32 v9, v3, v5 offset0:140 offset1:206
	s_waitcnt vmcnt(23)
	v_cndmask_b32_e32 v3, 0, v96, vcc
	s_waitcnt vmcnt(22)
	v_cndmask_b32_e32 v5, 0, v97, vcc
	v_add_u32_e32 v9, 0x800, v77
	ds_write2_b32 v9, v3, v5 offset0:16 offset1:82
	s_waitcnt vmcnt(21)
	v_cndmask_b32_e32 v3, 0, v98, vcc
	s_waitcnt vmcnt(20)
	v_cndmask_b32_e32 v5, 0, v99, vcc
	ds_write2_b32 v9, v3, v5 offset0:148 offset1:214
	s_waitcnt vmcnt(19)
	v_cndmask_b32_e32 v3, 0, v100, vcc
	s_waitcnt vmcnt(18)
	v_cndmask_b32_e32 v5, 0, v101, vcc
	v_add_u32_e32 v9, 0xc00, v77
	ds_write2_b32 v9, v3, v5 offset0:24 offset1:90
	s_waitcnt vmcnt(17)
	v_cndmask_b32_e32 v3, 0, v102, vcc
	s_waitcnt vmcnt(16)
	v_cndmask_b32_e32 v5, 0, v103, vcc
	ds_write2_b32 v9, v3, v5 offset0:156 offset1:222
	s_waitcnt vmcnt(15)
	v_cndmask_b32_e32 v3, 0, v53, vcc
	s_waitcnt vmcnt(14)
	v_cndmask_b32_e32 v5, 0, v55, vcc
	v_add_u32_e32 v9, 0x1000, v77
	ds_write2_b32 v9, v3, v5 offset0:32 offset1:98
	s_waitcnt vmcnt(13)
	v_cndmask_b32_e32 v3, 0, v104, vcc
	s_waitcnt vmcnt(12)
	v_cndmask_b32_e32 v5, 0, v105, vcc
	ds_write2_b32 v9, v3, v5 offset0:164 offset1:230
	s_waitcnt vmcnt(11)
	v_cndmask_b32_e32 v3, 0, v80, vcc
	s_waitcnt vmcnt(10)
	v_cndmask_b32_e32 v5, 0, v81, vcc
	v_add_u32_e32 v9, 0x1400, v77
	ds_write2_b32 v9, v3, v5 offset0:40 offset1:106
	s_waitcnt vmcnt(9)
	v_cndmask_b32_e32 v3, 0, v82, vcc
	s_waitcnt vmcnt(8)
	v_cndmask_b32_e32 v5, 0, v83, vcc
	ds_write2_b32 v9, v3, v5 offset0:172 offset1:238
	s_waitcnt vmcnt(7)
	v_cndmask_b32_e32 v3, 0, v57, vcc
	s_waitcnt vmcnt(6)
	v_cndmask_b32_e32 v5, 0, v59, vcc
	v_add_u32_e32 v9, 0x1800, v77
	ds_write2_b32 v9, v3, v5 offset0:48 offset1:114
	s_waitcnt vmcnt(5)
	v_cndmask_b32_e32 v3, 0, v61, vcc
	s_waitcnt vmcnt(4)
	v_cndmask_b32_e32 v5, 0, v6, vcc
	ds_write2_b32 v9, v3, v5 offset0:180 offset1:246
	s_waitcnt vmcnt(3)
	v_cndmask_b32_e32 v3, 0, v7, vcc
	s_waitcnt vmcnt(2)
	v_cndmask_b32_e32 v5, 0, v8, vcc
	v_add_u32_e32 v6, 0x1c00, v77
	ds_write2_b32 v6, v3, v5 offset0:56 offset1:122
	s_waitcnt vmcnt(1)
	v_cndmask_b32_e32 v3, 0, v4, vcc
	s_waitcnt vmcnt(0)
	v_cndmask_b32_e32 v2, 0, v2, vcc
	ds_write2_b32 v6, v3, v2 offset0:188 offset1:254
	s_waitcnt lgkmcnt(0)
	s_andn2_b64 vcc, exec, s[10:11]
	s_cbranch_vccz .LBB0_22
	v_mov_b32_e32 v2, 1.0
	v_mov_b32_e32 v3, v2
	v_mov_b32_e32 v4, v2
	v_mov_b32_e32 v5, v2
	v_mov_b32_e32 v6, v2
	v_mov_b32_e32 v7, v2
	v_mov_b32_e32 v8, v2
	v_mov_b32_e32 v9, v2
	s_branch .LBB0_23

.LBB0_30:
	v_mad_i64_i32 v[2:3], s[18:19], s10, v75, v[14:15]
	v_lshl_add_u64 v[4:5], v[2:3], 0, v[18:19]
	v_add_co_u32_e32 v6, vcc, 0x1a000, v4
	v_lshl_add_u64 v[78:79], v[2:3], 0, v[20:21]
	s_nop 0
	v_addc_co_u32_e32 v7, vcc, 0, v5, vcc
	v_add_co_u32_e32 v8, vcc, 0x34000, v4
	v_lshl_add_u64 v[80:81], v[2:3], 0, v[22:23]
	s_nop 0
	v_addc_co_u32_e32 v9, vcc, 0, v5, vcc
	v_add_co_u32_e32 v76, vcc, 0x4e000, v4
	v_lshl_add_u64 v[82:83], v[2:3], 0, v[24:25]
	s_nop 0
	v_addc_co_u32_e32 v77, vcc, 0, v5, vcc
	v_lshl_add_u64 v[84:85], v[2:3], 0, v[26:27]
	global_load_dword v86, v[4:5], off nt
	global_load_dword v87, v[6:7], off offset:640
	global_load_dword v88, v[8:9], off offset:1280
	global_load_dword v89, v[76:77], off offset:1920
	global_load_dword v90, v[78:79], off nt
	global_load_dword v91, v[80:81], off nt
	global_load_dword v92, v[82:83], off nt
	global_load_dword v93, v[84:85], off nt
	v_lshl_add_u64 v[4:5], v[2:3], 0, v[28:29]
	v_lshl_add_u64 v[6:7], v[2:3], 0, v[30:31]
	v_lshl_add_u64 v[8:9], v[2:3], 0, v[32:33]
	v_lshl_add_u64 v[76:77], v[2:3], 0, v[34:35]
	v_lshl_add_u64 v[78:79], v[2:3], 0, v[36:37]
	v_lshl_add_u64 v[80:81], v[2:3], 0, v[38:39]
	v_lshl_add_u64 v[82:83], v[2:3], 0, v[40:41]
	v_lshl_add_u64 v[84:85], v[2:3], 0, v[42:43]
	global_load_dword v94, v[4:5], off nt
	global_load_dword v95, v[6:7], off nt
	global_load_dword v96, v[8:9], off nt
	global_load_dword v97, v[76:77], off nt
	global_load_dword v98, v[78:79], off nt
	global_load_dword v99, v[80:81], off nt
	global_load_dword v100, v[82:83], off nt
	global_load_dword v101, v[84:85], off nt
	v_mov_b32_e32 v57, v11
	v_lshl_add_u64 v[4:5], v[2:3], 0, v[44:45]
	v_mov_b32_e32 v55, v11
	v_lshl_add_u64 v[84:85], v[2:3], 0, v[56:57]
	v_lshl_add_u64 v[6:7], v[2:3], 0, v[46:47]
	v_lshl_add_u64 v[8:9], v[2:3], 0, v[48:49]
	v_lshl_add_u64 v[76:77], v[2:3], 0, v[50:51]
	v_lshl_add_u64 v[78:79], v[2:3], 0, v[52:53]
	v_lshl_add_u64 v[80:81], v[2:3], 0, v[10:11]
	v_lshl_add_u64 v[82:83], v[2:3], 0, v[54:55]
	global_load_dword v55, v[4:5], off nt
	global_load_dword v57, v[6:7], off nt
	global_load_dword v102, v[8:9], off nt
	global_load_dword v103, v[76:77], off nt
	global_load_dword v104, v[78:79], off nt
	global_load_dword v105, v[80:81], off nt
	global_load_dword v106, v[82:83], off nt
	s_nop 0
	global_load_dword v84, v[84:85], off nt
	v_mov_b32_e32 v59, v11
	v_mov_b32_e32 v61, v11
	v_mov_b32_e32 v63, v11
	v_mov_b32_e32 v65, v11
	v_mov_b32_e32 v67, v11
	v_mov_b32_e32 v69, v11
	v_mov_b32_e32 v71, v11
	v_mov_b32_e32 v73, v11
	v_lshl_add_u64 v[4:5], v[2:3], 0, v[58:59]
	v_lshl_add_u64 v[6:7], v[2:3], 0, v[60:61]
	v_lshl_add_u64 v[8:9], v[2:3], 0, v[62:63]
	v_lshl_add_u64 v[76:77], v[2:3], 0, v[64:65]
	v_lshl_add_u64 v[78:79], v[2:3], 0, v[66:67]
	v_lshl_add_u64 v[80:81], v[2:3], 0, v[68:69]
	v_lshl_add_u64 v[82:83], v[2:3], 0, v[70:71]
	v_lshl_add_u64 v[2:3], v[2:3], 0, v[72:73]
	global_load_dword v4, v[4:5], off nt
	s_nop 0
	global_load_dword v5, v[6:7], off nt
	s_nop 0
	global_load_dword v6, v[8:9], off nt
	global_load_dword v7, v[76:77], off nt
	s_nop 0
	global_load_dword v8, v[78:79], off nt
	global_load_dword v9, v[80:81], off nt
	global_load_dword v59, v[82:83], off nt
	s_nop 0
	global_load_dword v2, v[2:3], off nt
	v_add_u32_e32 v3, 0x400, v74
	s_ashr_i32 s11, s10, 31
	s_andn2_b64 vcc, exec, s[0:1]
	s_waitcnt vmcnt(30)
	ds_write2_b32 v74, v86, v87 offset1:66
	s_waitcnt vmcnt(28)
	ds_write2_b32 v74, v88, v89 offset0:132 offset1:198
	s_waitcnt vmcnt(26)
	ds_write2_b32 v3, v90, v91 offset0:8 offset1:74
	s_waitcnt vmcnt(24)
	ds_write2_b32 v3, v92, v93 offset0:140 offset1:206
	v_add_u32_e32 v3, 0x800, v74
	s_waitcnt vmcnt(22)
	ds_write2_b32 v3, v94, v95 offset0:16 offset1:82
	s_waitcnt vmcnt(20)
	ds_write2_b32 v3, v96, v97 offset0:148 offset1:214
	v_add_u32_e32 v3, 0xc00, v74
	s_waitcnt vmcnt(18)
	ds_write2_b32 v3, v98, v99 offset0:24 offset1:90
	s_waitcnt vmcnt(16)
	ds_write2_b32 v3, v100, v101 offset0:156 offset1:222
	v_add_u32_e32 v3, 0x1000, v74
	s_waitcnt vmcnt(14)
	ds_write2_b32 v3, v55, v57 offset0:32 offset1:98
	s_waitcnt vmcnt(12)
	ds_write2_b32 v3, v102, v103 offset0:164 offset1:230
	v_add_u32_e32 v3, 0x1400, v74
	s_waitcnt vmcnt(10)
	ds_write2_b32 v3, v104, v105 offset0:40 offset1:106
	s_waitcnt vmcnt(8)
	ds_write2_b32 v3, v106, v84 offset0:172 offset1:238
	v_add_u32_e32 v3, 0x1800, v74
	s_waitcnt vmcnt(6)
	ds_write2_b32 v3, v4, v5 offset0:48 offset1:114
	s_waitcnt vmcnt(4)
	ds_write2_b32 v3, v6, v7 offset0:180 offset1:246
	v_add_u32_e32 v3, 0x1c00, v74
	s_waitcnt vmcnt(2)
	ds_write2_b32 v3, v8, v9 offset0:56 offset1:122
	s_waitcnt vmcnt(0)
	ds_write2_b32 v3, v59, v2 offset0:188 offset1:254
	s_waitcnt lgkmcnt(0)
	s_cbranch_vccz .LBB0_28
	v_mov_b32_e32 v2, 1.0
	v_mov_b32_e32 v3, v2
	v_mov_b32_e32 v4, v2
	v_mov_b32_e32 v5, v2
	v_mov_b32_e32 v6, v2
	v_mov_b32_e32 v7, v2
	v_mov_b32_e32 v8, v2
	v_mov_b32_e32 v9, v2
	s_branch .LBB0_29

.LBB0_36:
	s_lshr_b32 s0, s13, 31
	s_add_i32 s0, s13, s0
	s_lshl_b32 s0, s0, 5
	s_and_b32 s8, s0, 0xffffffc0
	s_sub_i32 s0, s16, s8
	v_add_u32_e32 v2, s0, v1
	s_ashr_i32 s9, s8, 31
	s_mul_i32 s0, s8, 0xd140
	v_cmp_gt_i32_e32 vcc, 48, v2
	s_mul_hi_i32 s1, s8, 0xd140
	s_add_u32 s0, s14, s0
	v_cndmask_b32_e32 v2, 0, v2, vcc
	s_addc_u32 s1, s15, s1
	v_ashrrev_i32_e32 v3, 31, v2
	v_lshl_add_u64 v[2:3], v[2:3], 2, s[0:1]
	v_lshl_add_u64 v[4:5], v[2:3], 0, v[16:17]
	v_add_co_u32_e64 v6, s[0:1], s18, v4
	v_lshl_add_u64 v[78:79], v[2:3], 0, v[18:19]
	s_nop 0
	v_addc_co_u32_e64 v7, s[0:1], 0, v5, s[0:1]
	v_add_co_u32_e64 v8, s[0:1], s19, v4
	v_lshl_add_u64 v[80:81], v[2:3], 0, v[20:21]
	s_nop 0
	v_addc_co_u32_e64 v9, s[0:1], 0, v5, s[0:1]
	v_add_co_u32_e64 v76, s[0:1], s20, v4
	v_lshl_add_u64 v[82:83], v[2:3], 0, v[22:23]
	s_nop 0
	v_addc_co_u32_e64 v77, s[0:1], 0, v5, s[0:1]
	v_lshl_add_u64 v[84:85], v[2:3], 0, v[24:25]
	global_load_dword v75, v[4:5], off nt
	global_load_dword v86, v[6:7], off offset:640
	global_load_dword v87, v[8:9], off offset:1280
	global_load_dword v88, v[76:77], off offset:1920
	global_load_dword v89, v[78:79], off nt
	global_load_dword v90, v[80:81], off nt
	global_load_dword v91, v[82:83], off nt
	global_load_dword v92, v[84:85], off nt
	v_lshl_add_u64 v[4:5], v[2:3], 0, v[26:27]
	v_lshl_add_u64 v[6:7], v[2:3], 0, v[28:29]
	v_lshl_add_u64 v[8:9], v[2:3], 0, v[30:31]
	v_lshl_add_u64 v[76:77], v[2:3], 0, v[32:33]
	v_lshl_add_u64 v[78:79], v[2:3], 0, v[34:35]
	v_lshl_add_u64 v[80:81], v[2:3], 0, v[36:37]
	v_lshl_add_u64 v[82:83], v[2:3], 0, v[38:39]
	v_lshl_add_u64 v[84:85], v[2:3], 0, v[40:41]
	global_load_dword v93, v[4:5], off nt
	global_load_dword v94, v[6:7], off nt
	global_load_dword v95, v[8:9], off nt
	global_load_dword v96, v[76:77], off nt
	global_load_dword v97, v[78:79], off nt
	global_load_dword v98, v[80:81], off nt
	global_load_dword v99, v[82:83], off nt
	global_load_dword v100, v[84:85], off nt
	v_lshl_add_u64 v[4:5], v[2:3], 0, v[42:43]
	v_lshl_add_u64 v[78:79], v[2:3], 0, v[50:51]
	v_lshl_add_u64 v[80:81], v[2:3], 0, v[52:53]
	v_lshl_add_u64 v[6:7], v[2:3], 0, v[44:45]
	v_lshl_add_u64 v[8:9], v[2:3], 0, v[46:47]
	v_lshl_add_u64 v[76:77], v[2:3], 0, v[48:49]
	v_lshl_add_u64 v[82:83], v[2:3], 0, v[54:55]
	v_lshl_add_u64 v[84:85], v[2:3], 0, v[56:57]
	global_load_dword v101, v[4:5], off nt
	global_load_dword v102, v[6:7], off nt
	global_load_dword v103, v[8:9], off nt
	global_load_dword v104, v[76:77], off nt
	s_nop 0
	global_load_dword v78, v[78:79], off nt
	s_nop 0
	global_load_dword v79, v[80:81], off nt
	s_nop 0
	global_load_dword v80, v[82:83], off nt
	global_load_dword v81, v[84:85], off nt
	v_lshl_add_u64 v[4:5], v[2:3], 0, v[10:11]
	v_mov_b32_e32 v59, v11
	v_lshl_add_u64 v[6:7], v[2:3], 0, v[58:59]
	global_load_dword v59, v[4:5], off nt
	global_load_dword v82, v[6:7], off nt
	v_mov_b32_e32 v61, v11
	v_mov_b32_e32 v63, v11
	v_mov_b32_e32 v65, v11
	v_lshl_add_u64 v[4:5], v[2:3], 0, v[60:61]
	v_lshl_add_u64 v[6:7], v[2:3], 0, v[62:63]
	v_lshl_add_u64 v[8:9], v[2:3], 0, v[64:65]
	v_mov_b32_e32 v67, v11
	v_mov_b32_e32 v69, v11
	v_mov_b32_e32 v71, v11
	v_lshl_add_u64 v[76:77], v[2:3], 0, v[66:67]
	global_load_dword v61, v[4:5], off nt
	s_nop 0
	global_load_dword v6, v[6:7], off nt
	s_nop 0
	global_load_dword v7, v[8:9], off nt
	s_nop 0
	global_load_dword v8, v[76:77], off nt
	v_lshl_add_u64 v[4:5], v[2:3], 0, v[68:69]
	v_lshl_add_u64 v[2:3], v[2:3], 0, v[70:71]
	global_load_dword v4, v[4:5], off nt
	s_nop 0
	global_load_dword v2, v[2:3], off nt
	v_add_u32_e32 v9, 0x400, v74
	s_waitcnt vmcnt(31)
	v_cndmask_b32_e32 v3, 0, v75, vcc
	s_waitcnt vmcnt(30)
	v_cndmask_b32_e32 v5, 0, v86, vcc
	ds_write2_b32 v74, v3, v5 offset1:66
	s_waitcnt vmcnt(29)
	v_cndmask_b32_e32 v3, 0, v87, vcc
	s_waitcnt vmcnt(28)
	v_cndmask_b32_e32 v5, 0, v88, vcc
	ds_write2_b32 v74, v3, v5 offset0:132 offset1:198
	s_waitcnt vmcnt(27)
	v_cndmask_b32_e32 v3, 0, v89, vcc
	s_waitcnt vmcnt(26)
	v_cndmask_b32_e32 v5, 0, v90, vcc
	ds_write2_b32 v9, v3, v5 offset0:8 offset1:74
	s_waitcnt vmcnt(25)
	v_cndmask_b32_e32 v3, 0, v91, vcc
	s_waitcnt vmcnt(24)
	v_cndmask_b32_e32 v5, 0, v92, vcc
	ds_write2_b32 v9, v3, v5 offset0:140 offset1:206
	s_waitcnt vmcnt(23)
	v_cndmask_b32_e32 v3, 0, v93, vcc
	s_waitcnt vmcnt(22)
	v_cndmask_b32_e32 v5, 0, v94, vcc
	v_add_u32_e32 v9, 0x800, v74
	ds_write2_b32 v9, v3, v5 offset0:16 offset1:82
	s_waitcnt vmcnt(21)
	v_cndmask_b32_e32 v3, 0, v95, vcc
	s_waitcnt vmcnt(20)
	v_cndmask_b32_e32 v5, 0, v96, vcc
	ds_write2_b32 v9, v3, v5 offset0:148 offset1:214
	s_waitcnt vmcnt(19)
	v_cndmask_b32_e32 v3, 0, v97, vcc
	s_waitcnt vmcnt(18)
	v_cndmask_b32_e32 v5, 0, v98, vcc
	v_add_u32_e32 v9, 0xc00, v74
	ds_write2_b32 v9, v3, v5 offset0:24 offset1:90
	s_waitcnt vmcnt(17)
	v_cndmask_b32_e32 v3, 0, v99, vcc
	s_waitcnt vmcnt(16)
	v_cndmask_b32_e32 v5, 0, v100, vcc
	ds_write2_b32 v9, v3, v5 offset0:156 offset1:222
	s_waitcnt vmcnt(15)
	v_cndmask_b32_e32 v3, 0, v101, vcc
	s_waitcnt vmcnt(14)
	v_cndmask_b32_e32 v5, 0, v102, vcc
	v_add_u32_e32 v9, 0x1000, v74
	ds_write2_b32 v9, v3, v5 offset0:32 offset1:98
	s_waitcnt vmcnt(13)
	v_cndmask_b32_e32 v3, 0, v103, vcc
	s_waitcnt vmcnt(12)
	v_cndmask_b32_e32 v5, 0, v104, vcc
	ds_write2_b32 v9, v3, v5 offset0:164 offset1:230
	s_waitcnt vmcnt(11)
	v_cndmask_b32_e32 v3, 0, v78, vcc
	s_waitcnt vmcnt(10)
	v_cndmask_b32_e32 v5, 0, v79, vcc
	v_add_u32_e32 v9, 0x1400, v74
	ds_write2_b32 v9, v3, v5 offset0:40 offset1:106
	s_waitcnt vmcnt(9)
	v_cndmask_b32_e32 v3, 0, v80, vcc
	s_waitcnt vmcnt(8)
	v_cndmask_b32_e32 v5, 0, v81, vcc
	ds_write2_b32 v9, v3, v5 offset0:172 offset1:238
	s_waitcnt vmcnt(7)
	v_cndmask_b32_e32 v3, 0, v59, vcc
	s_waitcnt vmcnt(6)
	v_cndmask_b32_e32 v5, 0, v82, vcc
	v_add_u32_e32 v9, 0x1800, v74
	ds_write2_b32 v9, v3, v5 offset0:48 offset1:114
	s_waitcnt vmcnt(5)
	v_cndmask_b32_e32 v3, 0, v61, vcc
	s_waitcnt vmcnt(4)
	v_cndmask_b32_e32 v5, 0, v6, vcc
	ds_write2_b32 v9, v3, v5 offset0:180 offset1:246
	s_waitcnt vmcnt(3)
	v_cndmask_b32_e32 v3, 0, v7, vcc
	s_waitcnt vmcnt(2)
	v_cndmask_b32_e32 v5, 0, v8, vcc
	v_add_u32_e32 v6, 0x1c00, v74
	ds_write2_b32 v6, v3, v5 offset0:56 offset1:122
	s_waitcnt vmcnt(1)
	v_cndmask_b32_e32 v3, 0, v4, vcc
	s_waitcnt vmcnt(0)
	v_cndmask_b32_e32 v2, 0, v2, vcc
	ds_write2_b32 v6, v3, v2 offset0:188 offset1:254
	s_waitcnt lgkmcnt(0)
	s_andn2_b64 vcc, exec, s[10:11]
	s_cbranch_vccz .LBB0_34
	v_mov_b32_e32 v2, 1.0
	v_mov_b32_e32 v3, v2
	v_mov_b32_e32 v4, v2
	v_mov_b32_e32 v5, v2
	v_mov_b32_e32 v6, v2
	v_mov_b32_e32 v7, v2
	v_mov_b32_e32 v8, v2
	v_mov_b32_e32 v9, v2
	s_branch .LBB0_35

.LBB0_40:
	s_mul_hi_i32 s0, s9, 0x66666667
	s_lshr_b32 s1, s0, 31
	s_ashr_i32 s0, s0, 1
	s_add_i32 s1, s0, s1
	s_mul_i32 s15, s1, -5
	s_mul_i32 s16, s1, 0xffffff60
	s_lshl_b32 s0, s1, 6
	s_add_i32 s15, s9, s15
	s_add_i32 s16, s16, s10
	s_cmp_lt_i32 s15, 0
	s_mul_i32 s17, s1, 0x345000
	s_cselect_b64 vcc, -1, 0
	s_ashr_i32 s1, s0, 31
	s_mul_hi_i32 s18, s0, 0xd140
	v_add_u32_e32 v76, s16, v1
	v_add_u32_e32 v72, s16, v62
	s_add_u32 s16, s4, s17
	v_lshl_add_u64 v[74:75], s[0:1], 1, v[4:5]
	s_addc_u32 s17, s5, s18
	s_ashr_i32 s0, s15, 31
	v_and_b32_e32 v76, s0, v76
	v_ashrrev_i32_e32 v77, 31, v76
	v_lshl_add_u64 v[76:77], v[76:77], 2, s[16:17]
	v_lshl_add_u64 v[78:79], v[76:77], 0, v[6:7]
	v_add_co_u32_e64 v134, s[0:1], s12, v78
	v_mov_b32_e32 v53, v3
	s_nop 0
	v_addc_co_u32_e64 v135, s[0:1], 0, v79, s[0:1]
	v_add_co_u32_e64 v136, s[0:1], s13, v78
	v_mov_b32_e32 v55, v3
	s_nop 0
	v_addc_co_u32_e64 v137, s[0:1], 0, v79, s[0:1]
	v_mov_b32_e32 v57, v3
	v_mov_b32_e32 v59, v3
	v_mov_b32_e32 v61, v3
	v_lshl_add_u64 v[126:127], v[76:77], 0, v[52:53]
	global_load_dword v53, v[78:79], off nt
	v_add_co_u32_e64 v78, s[0:1], s14, v78
	v_lshl_add_u64 v[80:81], v[76:77], 0, v[8:9]
	v_lshl_add_u64 v[82:83], v[76:77], 0, v[10:11]
	v_lshl_add_u64 v[84:85], v[76:77], 0, v[12:13]
	v_lshl_add_u64 v[86:87], v[76:77], 0, v[14:15]
	v_lshl_add_u64 v[88:89], v[76:77], 0, v[16:17]
	v_lshl_add_u64 v[90:91], v[76:77], 0, v[18:19]
	v_lshl_add_u64 v[92:93], v[76:77], 0, v[20:21]
	v_lshl_add_u64 v[94:95], v[76:77], 0, v[22:23]
	v_lshl_add_u64 v[96:97], v[76:77], 0, v[24:25]
	v_lshl_add_u64 v[98:99], v[76:77], 0, v[26:27]
	v_lshl_add_u64 v[100:101], v[76:77], 0, v[28:29]
	v_lshl_add_u64 v[102:103], v[76:77], 0, v[30:31]
	v_lshl_add_u64 v[104:105], v[76:77], 0, v[32:33]
	v_lshl_add_u64 v[106:107], v[76:77], 0, v[34:35]
	v_lshl_add_u64 v[108:109], v[76:77], 0, v[36:37]
	v_lshl_add_u64 v[110:111], v[76:77], 0, v[38:39]
	v_lshl_add_u64 v[112:113], v[76:77], 0, v[40:41]
	v_lshl_add_u64 v[114:115], v[76:77], 0, v[42:43]
	v_lshl_add_u64 v[116:117], v[76:77], 0, v[44:45]
	v_lshl_add_u64 v[118:119], v[76:77], 0, v[46:47]
	v_lshl_add_u64 v[120:121], v[76:77], 0, v[48:49]
	v_lshl_add_u64 v[122:123], v[76:77], 0, v[50:51]
	v_lshl_add_u64 v[124:125], v[76:77], 0, v[2:3]
	v_lshl_add_u64 v[128:129], v[76:77], 0, v[54:55]
	v_lshl_add_u64 v[130:131], v[76:77], 0, v[56:57]
	v_lshl_add_u64 v[132:133], v[76:77], 0, v[58:59]
	v_lshl_add_u64 v[76:77], v[76:77], 0, v[60:61]
	v_addc_co_u32_e64 v79, s[0:1], 0, v79, s[0:1]
	global_load_dword v55, v[88:89], off nt
	global_load_dword v57, v[90:91], off nt
	global_load_dword v59, v[92:93], off nt
	global_load_dword v61, v[94:95], off nt
	s_nop 0
	global_load_dword v90, v[96:97], off nt
	global_load_dword v91, v[98:99], off nt
	global_load_dword v92, v[100:101], off nt
	global_load_dword v93, v[102:103], off nt
	global_load_dword v94, v[104:105], off nt
	global_load_dword v95, v[106:107], off nt
	global_load_dword v96, v[108:109], off nt
	global_load_dword v97, v[110:111], off nt
	global_load_dword v98, v[112:113], off nt
	global_load_dword v99, v[114:115], off nt
	global_load_dword v100, v[116:117], off nt
	global_load_dword v101, v[118:119], off nt
	global_load_dword v102, v[120:121], off nt
	global_load_dword v103, v[122:123], off nt
	global_load_dword v104, v[124:125], off nt
	global_load_dword v105, v[126:127], off nt
	global_load_dword v106, v[128:129], off nt
	global_load_dword v107, v[130:131], off nt
	global_load_dword v108, v[132:133], off nt
	s_nop 0
	global_load_dword v76, v[76:77], off nt
	s_nop 0
	global_load_dword v77, v[134:135], off offset:640
	global_load_dword v109, v[136:137], off offset:1280
	s_nop 0
	global_load_dword v78, v[78:79], off offset:1920
	s_nop 0
	global_load_dword v79, v[80:81], off nt
	s_nop 0
	global_load_dword v80, v[82:83], off nt
	global_load_dword v81, v[84:85], off nt
	global_load_dword v110, v[86:87], off nt
	v_mov_b32_e32 v67, v3
	v_mov_b32_e32 v69, v3
	v_mov_b32_e32 v71, v3
	v_mov_b32_e32 v73, v3
	v_add_u32_e32 v66, 0x3460, v72
	v_add_u32_e32 v68, 0x3468, v72
	v_add_u32_e32 v70, 0x3470, v72
	v_add_u32_e32 v72, 0x3478, v72
	v_add_u32_e32 v138, 0x800, v64
	v_lshlrev_b64 v[66:67], 13, v[66:67]
	v_lshlrev_b64 v[68:69], 13, v[68:69]
	v_lshlrev_b64 v[70:71], 13, v[70:71]
	v_lshlrev_b64 v[72:73], 13, v[72:73]
	v_add_u32_e32 v65, 0x400, v64
	v_add_u32_e32 v139, 0xc00, v64
	v_add_u32_e32 v140, 0x1000, v64
	v_add_u32_e32 v141, 0x1400, v64
	v_add_u32_e32 v142, 0x1800, v64
	v_add_u32_e32 v143, 0x1c00, v64
	v_lshl_add_u64 v[82:83], v[74:75], 0, v[66:67]
	v_lshl_add_u64 v[84:85], v[74:75], 0, v[68:69]
	v_lshl_add_u64 v[86:87], v[74:75], 0, v[70:71]
	v_lshl_add_u64 v[88:89], v[74:75], 0, v[72:73]
	s_add_i32 s9, s9, s84
	v_add_u32_e32 v62, s11, v62
	s_cmpk_lt_i32 s9, 0x140
	v_add_u32_e32 v1, s11, v1
	s_waitcnt vmcnt(31)
	v_cndmask_b32_e32 v53, 0, v53, vcc
	s_waitcnt vmcnt(30)
	v_cndmask_b32_e32 v55, 0, v55, vcc
	s_waitcnt vmcnt(29)
	v_cndmask_b32_e32 v57, 0, v57, vcc
	s_waitcnt vmcnt(28)
	v_cndmask_b32_e32 v59, 0, v59, vcc
	s_waitcnt vmcnt(27)
	v_cndmask_b32_e32 v61, 0, v61, vcc
	s_waitcnt vmcnt(26)
	v_cndmask_b32_e32 v66, 0, v90, vcc
	s_waitcnt vmcnt(25)
	v_cndmask_b32_e32 v67, 0, v91, vcc
	s_waitcnt vmcnt(24)
	v_cndmask_b32_e32 v68, 0, v92, vcc
	s_waitcnt vmcnt(23)
	v_cndmask_b32_e32 v69, 0, v93, vcc
	s_waitcnt vmcnt(22)
	v_cndmask_b32_e32 v70, 0, v94, vcc
	s_waitcnt vmcnt(21)
	v_cndmask_b32_e32 v71, 0, v95, vcc
	s_waitcnt vmcnt(20)
	v_cndmask_b32_e32 v72, 0, v96, vcc
	s_waitcnt vmcnt(19)
	v_cndmask_b32_e32 v73, 0, v97, vcc
	s_waitcnt vmcnt(18)
	v_cndmask_b32_e32 v74, 0, v98, vcc
	s_waitcnt vmcnt(17)
	v_cndmask_b32_e32 v75, 0, v99, vcc
	s_waitcnt vmcnt(16)
	v_cndmask_b32_e32 v90, 0, v100, vcc
	s_waitcnt vmcnt(15)
	v_cndmask_b32_e32 v91, 0, v101, vcc
	s_waitcnt vmcnt(14)
	v_cndmask_b32_e32 v92, 0, v102, vcc
	s_waitcnt vmcnt(13)
	v_cndmask_b32_e32 v93, 0, v103, vcc
	s_waitcnt vmcnt(12)
	v_cndmask_b32_e32 v94, 0, v104, vcc
	s_waitcnt vmcnt(11)
	v_cndmask_b32_e32 v95, 0, v105, vcc
	s_waitcnt vmcnt(10)
	v_cndmask_b32_e32 v96, 0, v106, vcc
	s_waitcnt vmcnt(9)
	v_cndmask_b32_e32 v97, 0, v107, vcc
	s_waitcnt vmcnt(8)
	v_cndmask_b32_e32 v98, 0, v108, vcc
	s_waitcnt vmcnt(7)
	v_cndmask_b32_e32 v76, 0, v76, vcc
	s_waitcnt vmcnt(6)
	v_cndmask_b32_e32 v77, 0, v77, vcc
	s_waitcnt vmcnt(5)
	v_cndmask_b32_e32 v99, 0, v109, vcc
	s_waitcnt vmcnt(4)
	v_cndmask_b32_e32 v78, 0, v78, vcc
	s_waitcnt vmcnt(3)
	v_cndmask_b32_e32 v79, 0, v79, vcc
	s_waitcnt vmcnt(2)
	v_cndmask_b32_e32 v80, 0, v80, vcc
	s_waitcnt vmcnt(1)
	v_cndmask_b32_e32 v81, 0, v81, vcc
	s_waitcnt vmcnt(0)
	v_cndmask_b32_e32 v100, 0, v110, vcc
	ds_write2_b32 v138, v55, v57 offset0:16 offset1:82
	ds_write2_b32 v138, v59, v61 offset0:148 offset1:214
	ds_write2_b32 v139, v66, v67 offset0:24 offset1:90
	ds_write2_b32 v139, v68, v69 offset0:156 offset1:222
	ds_write2_b32 v140, v70, v71 offset0:32 offset1:98
	ds_write2_b32 v140, v72, v73 offset0:164 offset1:230
	ds_write2_b32 v141, v74, v75 offset0:40 offset1:106
	ds_write2_b32 v141, v90, v91 offset0:172 offset1:238
	ds_write2_b32 v142, v92, v93 offset0:48 offset1:114
	ds_write2_b32 v142, v94, v95 offset0:180 offset1:246
	ds_write2_b32 v143, v96, v97 offset0:56 offset1:122
	ds_write2_b32 v143, v98, v76 offset0:188 offset1:254
	ds_write2_b32 v64, v53, v77 offset1:66
	ds_write2_b32 v64, v99, v78 offset0:132 offset1:198
	ds_write2_b32 v65, v79, v80 offset0:8 offset1:74
	ds_write2_b32 v65, v81, v100 offset0:140 offset1:206
	s_waitcnt lgkmcnt(0)
	ds_read2_b32 v[70:71], v63 offset0:33 offset1:41
	ds_read2_b32 v[72:73], v63 offset1:8
	ds_read2_b32 v[74:75], v63 offset0:66 offset1:74
	ds_read2_b32 v[76:77], v63 offset0:99 offset1:107
	ds_read2_b32 v[78:79], v63 offset0:132 offset1:140
	ds_read2_b32 v[80:81], v63 offset0:165 offset1:173
	ds_read2_b32 v[90:91], v63 offset0:198 offset1:206
	ds_read2_b32 v[92:93], v63 offset0:231 offset1:239
	ds_read2_b32 v[94:95], v63 offset0:49 offset1:57
	ds_read2_b32 v[96:97], v63 offset0:16 offset1:24
	ds_read2_b32 v[98:99], v63 offset0:82 offset1:90
	ds_read2_b32 v[100:101], v63 offset0:115 offset1:123
	ds_read2_b32 v[102:103], v63 offset0:148 offset1:156
	ds_read2_b32 v[104:105], v63 offset0:181 offset1:189
	ds_read2_b32 v[106:107], v63 offset0:214 offset1:222
	ds_read2_b32 v[108:109], v63 offset0:247 offset1:255
	s_waitcnt lgkmcnt(14)
	v_cvt_pk_bf16_f32 v66, v72, v70
	s_waitcnt lgkmcnt(12)
	v_cvt_pk_bf16_f32 v67, v74, v76
	s_waitcnt lgkmcnt(10)
	v_cvt_pk_bf16_f32 v68, v78, v80
	s_waitcnt lgkmcnt(8)
	v_cvt_pk_bf16_f32 v69, v90, v92
	v_cvt_pk_bf16_f32 v70, v73, v71
	v_cvt_pk_bf16_f32 v71, v75, v77
	v_cvt_pk_bf16_f32 v72, v79, v81
	v_cvt_pk_bf16_f32 v73, v91, v93
	s_waitcnt lgkmcnt(6)
	v_cvt_pk_bf16_f32 v74, v96, v94
	s_waitcnt lgkmcnt(4)
	v_cvt_pk_bf16_f32 v75, v98, v100
	s_waitcnt lgkmcnt(2)
	v_cvt_pk_bf16_f32 v76, v102, v104
	s_waitcnt lgkmcnt(0)
	v_cvt_pk_bf16_f32 v77, v106, v108
	v_cvt_pk_bf16_f32 v78, v97, v95
	v_cvt_pk_bf16_f32 v79, v99, v101
	v_cvt_pk_bf16_f32 v80, v103, v105
	v_cvt_pk_bf16_f32 v81, v107, v109
	global_store_dwordx4 v[82:83], v[66:69], off
	global_store_dwordx4 v[84:85], v[70:73], off
	global_store_dwordx4 v[86:87], v[74:77], off
	global_store_dwordx4 v[88:89], v[78:81], off
	s_waitcnt lgkmcnt(0)
	s_cbranch_scc1 .LBB0_40

.LBB0_43:
	s_ashr_i32 s13, s5, 6
	s_lshr_b32 s16, s13, 28
	s_add_i32 s16, s13, s16
	s_and_b32 s17, s16, 0xfffff0
	s_lshl_b32 s16, s16, 5
	s_sub_i32 s13, s13, s17
	s_and_b32 s14, s10, 0x1c0
	s_and_b32 s15, s8, 0xe0
	s_and_b32 s16, s16, 0xfffffe00
	s_lshl_b32 s13, s13, 8
	s_or_b32 s14, s16, s14
	s_or_b32 s13, s13, s15
	s_ashr_i32 s15, s14, 31
	v_or_b32_e32 v77, s13, v1
	s_lshl_b64 s[16:17], s[14:15], 14
	v_cmp_gt_i32_e32 vcc, s12, v77
	v_lshl_add_u64 v[74:75], s[14:15], 1, v[4:5]
	s_waitcnt lgkmcnt(0)
	s_add_u32 s14, s0, s16
	v_cndmask_b32_e32 v84, 0, v77, vcc
	s_addc_u32 s15, s1, s17
	v_ashrrev_i32_e32 v85, 31, v84
	v_mov_b32_e32 v39, v3
	v_mov_b32_e32 v41, v3
	v_mov_b32_e32 v43, v3
	v_mov_b32_e32 v45, v3
	v_mov_b32_e32 v47, v3
	v_mov_b32_e32 v49, v3
	v_mov_b32_e32 v51, v3
	v_mov_b32_e32 v53, v3
	v_mov_b32_e32 v55, v3
	v_mov_b32_e32 v57, v3
	v_mov_b32_e32 v59, v3
	v_mov_b32_e32 v61, v3
	v_mov_b32_e32 v63, v3
	v_mov_b32_e32 v65, v3
	v_mov_b32_e32 v67, v3
	v_lshl_add_u64 v[84:85], v[84:85], 2, s[14:15]
	v_lshl_add_u64 v[86:87], v[84:85], 0, v[6:7]
	v_lshl_add_u64 v[88:89], v[84:85], 0, v[8:9]
	v_lshl_add_u64 v[90:91], v[84:85], 0, v[10:11]
	v_lshl_add_u64 v[92:93], v[84:85], 0, v[12:13]
	v_lshl_add_u64 v[94:95], v[84:85], 0, v[14:15]
	v_lshl_add_u64 v[96:97], v[84:85], 0, v[16:17]
	v_lshl_add_u64 v[98:99], v[84:85], 0, v[18:19]
	v_lshl_add_u64 v[100:101], v[84:85], 0, v[20:21]
	v_lshl_add_u64 v[102:103], v[84:85], 0, v[22:23]
	v_lshl_add_u64 v[104:105], v[84:85], 0, v[24:25]
	v_lshl_add_u64 v[106:107], v[84:85], 0, v[26:27]
	v_lshl_add_u64 v[108:109], v[84:85], 0, v[28:29]
	v_lshl_add_u64 v[110:111], v[84:85], 0, v[30:31]
	v_lshl_add_u64 v[112:113], v[84:85], 0, v[32:33]
	v_lshl_add_u64 v[114:115], v[84:85], 0, v[34:35]
	v_lshl_add_u64 v[116:117], v[84:85], 0, v[36:37]
	v_lshl_add_u64 v[118:119], v[84:85], 0, v[2:3]
	v_lshl_add_u64 v[120:121], v[84:85], 0, v[38:39]
	v_lshl_add_u64 v[122:123], v[84:85], 0, v[40:41]
	v_lshl_add_u64 v[124:125], v[84:85], 0, v[42:43]
	v_lshl_add_u64 v[126:127], v[84:85], 0, v[44:45]
	v_lshl_add_u64 v[128:129], v[84:85], 0, v[46:47]
	v_lshl_add_u64 v[130:131], v[84:85], 0, v[48:49]
	v_lshl_add_u64 v[132:133], v[84:85], 0, v[50:51]
	v_lshl_add_u64 v[134:135], v[84:85], 0, v[52:53]
	v_lshl_add_u64 v[136:137], v[84:85], 0, v[54:55]
	v_lshl_add_u64 v[138:139], v[84:85], 0, v[56:57]
	v_lshl_add_u64 v[140:141], v[84:85], 0, v[58:59]
	v_lshl_add_u64 v[142:143], v[84:85], 0, v[60:61]
	v_lshl_add_u64 v[144:145], v[84:85], 0, v[62:63]
	v_lshl_add_u64 v[146:147], v[84:85], 0, v[64:65]
	v_lshl_add_u64 v[84:85], v[84:85], 0, v[66:67]
	global_load_dword v39, v[86:87], off nt
	global_load_dword v41, v[88:89], off nt
	global_load_dword v43, v[90:91], off nt
	global_load_dword v45, v[92:93], off nt
	global_load_dword v47, v[94:95], off nt
	global_load_dword v49, v[96:97], off nt
	global_load_dword v51, v[98:99], off nt
	global_load_dword v53, v[100:101], off nt
	global_load_dword v55, v[102:103], off nt
	global_load_dword v57, v[104:105], off nt
	global_load_dword v59, v[106:107], off nt
	global_load_dword v61, v[108:109], off nt
	global_load_dword v63, v[110:111], off nt
	global_load_dword v65, v[112:113], off nt
	global_load_dword v67, v[114:115], off nt
	global_load_dword v86, v[116:117], off nt
	global_load_dword v87, v[118:119], off nt
	global_load_dword v88, v[120:121], off nt
	global_load_dword v89, v[122:123], off nt
	global_load_dword v98, v[124:125], off nt
	global_load_dword v99, v[126:127], off nt
	global_load_dword v100, v[128:129], off nt
	global_load_dword v101, v[130:131], off nt
	global_load_dword v102, v[132:133], off nt
	global_load_dword v103, v[134:135], off nt
	global_load_dword v104, v[136:137], off nt
	global_load_dword v105, v[138:139], off nt
	global_load_dword v106, v[140:141], off nt
	global_load_dword v107, v[142:143], off nt
	global_load_dword v108, v[144:145], off nt
	global_load_dword v109, v[146:147], off nt
	s_nop 0
	global_load_dword v84, v[84:85], off nt
	v_or_b32_e32 v76, s13, v68
	v_or_b32_e32 v78, s13, v70
	v_or_b32_e32 v80, s13, v71
	v_or_b32_e32 v82, s13, v72
	v_ashrrev_i32_e32 v77, 31, v76
	v_ashrrev_i32_e32 v79, 31, v78
	v_ashrrev_i32_e32 v81, 31, v80
	v_ashrrev_i32_e32 v83, 31, v82
	v_lshlrev_b64 v[76:77], 13, v[76:77]
	v_lshlrev_b64 v[78:79], 13, v[78:79]
	v_lshlrev_b64 v[80:81], 13, v[80:81]
	v_lshlrev_b64 v[82:83], 13, v[82:83]
	v_add_u32_e32 v148, 0x400, v73
	v_add_u32_e32 v149, 0x800, v73
	v_add_u32_e32 v150, 0xc00, v73
	v_add_u32_e32 v151, 0x1000, v73
	v_add_u32_e32 v152, 0x1400, v73
	v_add_u32_e32 v153, 0x1800, v73
	v_add_u32_e32 v154, 0x1c00, v73
	v_lshl_add_u64 v[90:91], v[74:75], 0, v[76:77]
	v_lshl_add_u64 v[92:93], v[74:75], 0, v[78:79]
	v_lshl_add_u64 v[94:95], v[74:75], 0, v[80:81]
	v_lshl_add_u64 v[96:97], v[74:75], 0, v[82:83]
	s_add_i32 s5, s5, s84
	s_add_i32 s8, s8, s9
	s_add_i32 s10, s10, s11
	s_cmpk_lt_i32 s5, 0x2000
	s_waitcnt vmcnt(31)
	v_cndmask_b32_e32 v39, 0, v39, vcc
	s_waitcnt vmcnt(30)
	v_cndmask_b32_e32 v41, 0, v41, vcc
	s_waitcnt vmcnt(29)
	v_cndmask_b32_e32 v43, 0, v43, vcc
	s_waitcnt vmcnt(28)
	v_cndmask_b32_e32 v45, 0, v45, vcc
	s_waitcnt vmcnt(27)
	v_cndmask_b32_e32 v47, 0, v47, vcc
	s_waitcnt vmcnt(26)
	v_cndmask_b32_e32 v49, 0, v49, vcc
	s_waitcnt vmcnt(25)
	v_cndmask_b32_e32 v51, 0, v51, vcc
	s_waitcnt vmcnt(24)
	v_cndmask_b32_e32 v53, 0, v53, vcc
	s_waitcnt vmcnt(23)
	v_cndmask_b32_e32 v55, 0, v55, vcc
	s_waitcnt vmcnt(22)
	v_cndmask_b32_e32 v57, 0, v57, vcc
	s_waitcnt vmcnt(21)
	v_cndmask_b32_e32 v59, 0, v59, vcc
	s_waitcnt vmcnt(20)
	v_cndmask_b32_e32 v61, 0, v61, vcc
	s_waitcnt vmcnt(19)
	v_cndmask_b32_e32 v63, 0, v63, vcc
	s_waitcnt vmcnt(18)
	v_cndmask_b32_e32 v65, 0, v65, vcc
	s_waitcnt vmcnt(17)
	v_cndmask_b32_e32 v67, 0, v67, vcc
	s_waitcnt vmcnt(16)
	v_cndmask_b32_e32 v74, 0, v86, vcc
	s_waitcnt vmcnt(15)
	v_cndmask_b32_e32 v75, 0, v87, vcc
	s_waitcnt vmcnt(14)
	v_cndmask_b32_e32 v76, 0, v88, vcc
	s_waitcnt vmcnt(13)
	v_cndmask_b32_e32 v77, 0, v89, vcc
	s_waitcnt vmcnt(12)
	v_cndmask_b32_e32 v78, 0, v98, vcc
	s_waitcnt vmcnt(11)
	v_cndmask_b32_e32 v79, 0, v99, vcc
	s_waitcnt vmcnt(10)
	v_cndmask_b32_e32 v80, 0, v100, vcc
	s_waitcnt vmcnt(9)
	v_cndmask_b32_e32 v81, 0, v101, vcc
	s_waitcnt vmcnt(8)
	v_cndmask_b32_e32 v82, 0, v102, vcc
	s_waitcnt vmcnt(7)
	v_cndmask_b32_e32 v83, 0, v103, vcc
	s_waitcnt vmcnt(6)
	v_cndmask_b32_e32 v85, 0, v104, vcc
	s_waitcnt vmcnt(5)
	v_cndmask_b32_e32 v86, 0, v105, vcc
	s_waitcnt vmcnt(4)
	v_cndmask_b32_e32 v87, 0, v106, vcc
	s_waitcnt vmcnt(3)
	v_cndmask_b32_e32 v88, 0, v107, vcc
	s_waitcnt vmcnt(2)
	v_cndmask_b32_e32 v89, 0, v108, vcc
	s_waitcnt vmcnt(1)
	v_cndmask_b32_e32 v98, 0, v109, vcc
	s_waitcnt vmcnt(0)
	v_cndmask_b32_e32 v84, 0, v84, vcc
	ds_write2_b32 v73, v39, v41 offset1:66
	ds_write2_b32 v73, v43, v45 offset0:132 offset1:198
	ds_write2_b32 v148, v47, v49 offset0:8 offset1:74
	ds_write2_b32 v148, v51, v53 offset0:140 offset1:206
	ds_write2_b32 v149, v55, v57 offset0:16 offset1:82
	ds_write2_b32 v149, v59, v61 offset0:148 offset1:214
	ds_write2_b32 v150, v63, v65 offset0:24 offset1:90
	ds_write2_b32 v150, v67, v74 offset0:156 offset1:222
	ds_write2_b32 v151, v75, v76 offset0:32 offset1:98
	ds_write2_b32 v151, v77, v78 offset0:164 offset1:230
	ds_write2_b32 v152, v79, v80 offset0:40 offset1:106
	ds_write2_b32 v152, v81, v82 offset0:172 offset1:238
	ds_write2_b32 v153, v83, v85 offset0:48 offset1:114
	ds_write2_b32 v153, v86, v87 offset0:180 offset1:246
	ds_write2_b32 v154, v88, v89 offset0:56 offset1:122
	ds_write2_b32 v154, v98, v84 offset0:188 offset1:254
	s_waitcnt lgkmcnt(0)
	ds_read2_b32 v[78:79], v69 offset0:33 offset1:41
	ds_read2_b32 v[80:81], v69 offset1:8
	ds_read2_b32 v[82:83], v69 offset0:66 offset1:74
	ds_read2_b32 v[84:85], v69 offset0:99 offset1:107
	ds_read2_b32 v[86:87], v69 offset0:132 offset1:140
	ds_read2_b32 v[88:89], v69 offset0:165 offset1:173
	ds_read2_b32 v[98:99], v69 offset0:198 offset1:206
	ds_read2_b32 v[100:101], v69 offset0:231 offset1:239
	ds_read2_b32 v[102:103], v69 offset0:49 offset1:57
	ds_read2_b32 v[104:105], v69 offset0:16 offset1:24
	ds_read2_b32 v[106:107], v69 offset0:82 offset1:90
	ds_read2_b32 v[108:109], v69 offset0:115 offset1:123
	ds_read2_b32 v[110:111], v69 offset0:148 offset1:156
	ds_read2_b32 v[112:113], v69 offset0:181 offset1:189
	ds_read2_b32 v[114:115], v69 offset0:214 offset1:222
	ds_read2_b32 v[116:117], v69 offset0:247 offset1:255
	s_waitcnt lgkmcnt(14)
	v_cvt_pk_bf16_f32 v74, v80, v78
	s_waitcnt lgkmcnt(12)
	v_cvt_pk_bf16_f32 v75, v82, v84
	s_waitcnt lgkmcnt(10)
	v_cvt_pk_bf16_f32 v76, v86, v88
	s_waitcnt lgkmcnt(8)
	v_cvt_pk_bf16_f32 v77, v98, v100
	v_cvt_pk_bf16_f32 v78, v81, v79
	v_cvt_pk_bf16_f32 v79, v83, v85
	v_cvt_pk_bf16_f32 v80, v87, v89
	v_cvt_pk_bf16_f32 v81, v99, v101
	s_waitcnt lgkmcnt(6)
	v_cvt_pk_bf16_f32 v82, v104, v102
	s_waitcnt lgkmcnt(4)
	v_cvt_pk_bf16_f32 v83, v106, v108
	s_waitcnt lgkmcnt(2)
	v_cvt_pk_bf16_f32 v84, v110, v112
	s_waitcnt lgkmcnt(0)
	v_cvt_pk_bf16_f32 v85, v114, v116
	v_cvt_pk_bf16_f32 v86, v105, v103
	v_cvt_pk_bf16_f32 v87, v107, v109
	v_cvt_pk_bf16_f32 v88, v111, v113
	v_cvt_pk_bf16_f32 v89, v115, v117
	global_store_dwordx4 v[90:91], v[74:77], off
	global_store_dwordx4 v[92:93], v[78:81], off
	global_store_dwordx4 v[94:95], v[82:85], off
	global_store_dwordx4 v[96:97], v[86:89], off
	s_waitcnt lgkmcnt(0)
	s_cbranch_scc1 .LBB0_43

.LBB0_48:
	s_ashr_i32 s0, s15, 6
	s_mul_hi_i32 s1, s0, 0x92492493
	s_add_i32 s1, s1, s0
	s_lshr_b32 s12, s1, 31
	s_ashr_i32 s1, s1, 5
	s_add_i32 s1, s1, s12
	s_mul_i32 s12, s1, 56
	s_sub_i32 s0, s0, s12
	s_lshl_b32 s1, s1, 9
	s_and_b32 s12, s18, 0x1c0
	s_or_b32 s12, s1, s12
	s_lshl_b32 s0, s0, 8
	s_and_b32 s1, s16, 0xe0
	s_or_b32 s25, s0, s1
	v_or_b32_e32 v2, s25, v1
	s_ashr_i32 s13, s12, 31
	s_mul_i32 s0, s12, 0xe040
	v_cmp_gt_i32_e32 vcc, s20, v2
	s_mul_hi_i32 s1, s12, 0xe040
	s_add_u32 s0, s8, s0
	v_cndmask_b32_e32 v2, 0, v2, vcc
	s_addc_u32 s1, s9, s1
	v_ashrrev_i32_e32 v3, 31, v2
	v_lshl_add_u64 v[2:3], v[2:3], 2, s[0:1]
	v_lshl_add_u64 v[4:5], v[2:3], 0, v[16:17]
	v_add_co_u32_e64 v6, s[0:1], s21, v4
	v_lshl_add_u64 v[80:81], v[2:3], 0, v[18:19]
	s_nop 0
	v_addc_co_u32_e64 v7, s[0:1], 0, v5, s[0:1]
	v_add_co_u32_e64 v8, s[0:1], s22, v4
	v_lshl_add_u64 v[82:83], v[2:3], 0, v[20:21]
	s_nop 0
	v_addc_co_u32_e64 v9, s[0:1], 0, v5, s[0:1]
	v_add_co_u32_e64 v78, s[0:1], s24, v4
	v_lshl_add_u64 v[84:85], v[2:3], 0, v[22:23]
	s_nop 0
	v_addc_co_u32_e64 v79, s[0:1], 0, v5, s[0:1]
	v_lshl_add_u64 v[86:87], v[2:3], 0, v[24:25]
	global_load_dword v88, v[4:5], off nt
	global_load_dword v89, v[6:7], off offset:128
	global_load_dword v90, v[8:9], off offset:256
	global_load_dword v91, v[78:79], off offset:384
	global_load_dword v92, v[80:81], off nt
	global_load_dword v93, v[82:83], off nt
	global_load_dword v94, v[84:85], off nt
	global_load_dword v95, v[86:87], off nt
	v_lshl_add_u64 v[4:5], v[2:3], 0, v[26:27]
	v_lshl_add_u64 v[6:7], v[2:3], 0, v[28:29]
	v_lshl_add_u64 v[8:9], v[2:3], 0, v[30:31]
	v_lshl_add_u64 v[78:79], v[2:3], 0, v[32:33]
	v_lshl_add_u64 v[80:81], v[2:3], 0, v[34:35]
	v_lshl_add_u64 v[82:83], v[2:3], 0, v[36:37]
	v_lshl_add_u64 v[84:85], v[2:3], 0, v[38:39]
	v_lshl_add_u64 v[86:87], v[2:3], 0, v[40:41]
	global_load_dword v96, v[4:5], off nt
	global_load_dword v97, v[6:7], off nt
	global_load_dword v98, v[8:9], off nt
	global_load_dword v99, v[78:79], off nt
	global_load_dword v100, v[80:81], off nt
	global_load_dword v101, v[82:83], off nt
	global_load_dword v102, v[84:85], off nt
	global_load_dword v103, v[86:87], off nt
	v_lshl_add_u64 v[4:5], v[2:3], 0, v[42:43]
	v_lshl_add_u64 v[80:81], v[2:3], 0, v[50:51]
	v_lshl_add_u64 v[82:83], v[2:3], 0, v[10:11]
	v_mov_b32_e32 v53, v11
	v_mov_b32_e32 v55, v11
	v_mov_b32_e32 v57, v11
	v_lshl_add_u64 v[6:7], v[2:3], 0, v[44:45]
	v_lshl_add_u64 v[8:9], v[2:3], 0, v[46:47]
	v_lshl_add_u64 v[78:79], v[2:3], 0, v[48:49]
	v_lshl_add_u64 v[84:85], v[2:3], 0, v[52:53]
	v_lshl_add_u64 v[86:87], v[2:3], 0, v[54:55]
	global_load_dword v53, v[4:5], off nt
	global_load_dword v55, v[6:7], off nt
	global_load_dword v104, v[8:9], off nt
	global_load_dword v105, v[78:79], off nt
	s_nop 0
	global_load_dword v80, v[80:81], off nt
	s_nop 0
	global_load_dword v81, v[82:83], off nt
	s_nop 0
	global_load_dword v82, v[84:85], off nt
	global_load_dword v83, v[86:87], off nt
	v_lshl_add_u64 v[4:5], v[2:3], 0, v[56:57]
	v_mov_b32_e32 v59, v11
	v_lshl_add_u64 v[6:7], v[2:3], 0, v[58:59]
	global_load_dword v57, v[4:5], off nt
	global_load_dword v59, v[6:7], off nt
	v_mov_b32_e32 v61, v11
	v_mov_b32_e32 v63, v11
	v_mov_b32_e32 v65, v11
	v_lshl_add_u64 v[4:5], v[2:3], 0, v[60:61]
	v_lshl_add_u64 v[6:7], v[2:3], 0, v[62:63]
	v_lshl_add_u64 v[8:9], v[2:3], 0, v[64:65]
	v_mov_b32_e32 v67, v11
	v_mov_b32_e32 v69, v11
	v_mov_b32_e32 v71, v11
	v_lshl_add_u64 v[78:79], v[2:3], 0, v[66:67]
	global_load_dword v61, v[4:5], off nt
	s_nop 0
	global_load_dword v6, v[6:7], off nt
	s_nop 0
	global_load_dword v7, v[8:9], off nt
	s_nop 0
	global_load_dword v8, v[78:79], off nt
	v_lshl_add_u64 v[4:5], v[2:3], 0, v[68:69]
	v_lshl_add_u64 v[2:3], v[2:3], 0, v[70:71]
	global_load_dword v4, v[4:5], off nt
	s_nop 0
	global_load_dword v2, v[2:3], off nt
	v_add_u32_e32 v9, 0x400, v77
	s_waitcnt vmcnt(31)
	v_cndmask_b32_e32 v3, 0, v88, vcc
	s_waitcnt vmcnt(30)
	v_cndmask_b32_e32 v5, 0, v89, vcc
	ds_write2_b32 v77, v3, v5 offset1:66
	s_waitcnt vmcnt(29)
	v_cndmask_b32_e32 v3, 0, v90, vcc
	s_waitcnt vmcnt(28)
	v_cndmask_b32_e32 v5, 0, v91, vcc
	ds_write2_b32 v77, v3, v5 offset0:132 offset1:198
	s_waitcnt vmcnt(27)
	v_cndmask_b32_e32 v3, 0, v92, vcc
	s_waitcnt vmcnt(26)
	v_cndmask_b32_e32 v5, 0, v93, vcc
	ds_write2_b32 v9, v3, v5 offset0:8 offset1:74
	s_waitcnt vmcnt(25)
	v_cndmask_b32_e32 v3, 0, v94, vcc
	s_waitcnt vmcnt(24)
	v_cndmask_b32_e32 v5, 0, v95, vcc
	ds_write2_b32 v9, v3, v5 offset0:140 offset1:206
	s_waitcnt vmcnt(23)
	v_cndmask_b32_e32 v3, 0, v96, vcc
	s_waitcnt vmcnt(22)
	v_cndmask_b32_e32 v5, 0, v97, vcc
	v_add_u32_e32 v9, 0x800, v77
	ds_write2_b32 v9, v3, v5 offset0:16 offset1:82
	s_waitcnt vmcnt(21)
	v_cndmask_b32_e32 v3, 0, v98, vcc
	s_waitcnt vmcnt(20)
	v_cndmask_b32_e32 v5, 0, v99, vcc
	ds_write2_b32 v9, v3, v5 offset0:148 offset1:214
	s_waitcnt vmcnt(19)
	v_cndmask_b32_e32 v3, 0, v100, vcc
	s_waitcnt vmcnt(18)
	v_cndmask_b32_e32 v5, 0, v101, vcc
	v_add_u32_e32 v9, 0xc00, v77
	ds_write2_b32 v9, v3, v5 offset0:24 offset1:90
	s_waitcnt vmcnt(17)
	v_cndmask_b32_e32 v3, 0, v102, vcc
	s_waitcnt vmcnt(16)
	v_cndmask_b32_e32 v5, 0, v103, vcc
	ds_write2_b32 v9, v3, v5 offset0:156 offset1:222
	s_waitcnt vmcnt(15)
	v_cndmask_b32_e32 v3, 0, v53, vcc
	s_waitcnt vmcnt(14)
	v_cndmask_b32_e32 v5, 0, v55, vcc
	v_add_u32_e32 v9, 0x1000, v77
	ds_write2_b32 v9, v3, v5 offset0:32 offset1:98
	s_waitcnt vmcnt(13)
	v_cndmask_b32_e32 v3, 0, v104, vcc
	s_waitcnt vmcnt(12)
	v_cndmask_b32_e32 v5, 0, v105, vcc
	ds_write2_b32 v9, v3, v5 offset0:164 offset1:230
	s_waitcnt vmcnt(11)
	v_cndmask_b32_e32 v3, 0, v80, vcc
	s_waitcnt vmcnt(10)
	v_cndmask_b32_e32 v5, 0, v81, vcc
	v_add_u32_e32 v9, 0x1400, v77
	ds_write2_b32 v9, v3, v5 offset0:40 offset1:106
	s_waitcnt vmcnt(9)
	v_cndmask_b32_e32 v3, 0, v82, vcc
	s_waitcnt vmcnt(8)
	v_cndmask_b32_e32 v5, 0, v83, vcc
	ds_write2_b32 v9, v3, v5 offset0:172 offset1:238
	s_waitcnt vmcnt(7)
	v_cndmask_b32_e32 v3, 0, v57, vcc
	s_waitcnt vmcnt(6)
	v_cndmask_b32_e32 v5, 0, v59, vcc
	v_add_u32_e32 v9, 0x1800, v77
	ds_write2_b32 v9, v3, v5 offset0:48 offset1:114
	s_waitcnt vmcnt(5)
	v_cndmask_b32_e32 v3, 0, v61, vcc
	s_waitcnt vmcnt(4)
	v_cndmask_b32_e32 v5, 0, v6, vcc
	ds_write2_b32 v9, v3, v5 offset0:180 offset1:246
	s_waitcnt vmcnt(3)
	v_cndmask_b32_e32 v3, 0, v7, vcc
	s_waitcnt vmcnt(2)
	v_cndmask_b32_e32 v5, 0, v8, vcc
	v_add_u32_e32 v6, 0x1c00, v77
	ds_write2_b32 v6, v3, v5 offset0:56 offset1:122
	s_waitcnt vmcnt(1)
	v_cndmask_b32_e32 v3, 0, v4, vcc
	s_waitcnt vmcnt(0)
	v_cndmask_b32_e32 v2, 0, v2, vcc
	ds_write2_b32 v6, v3, v2 offset0:188 offset1:254
	s_waitcnt lgkmcnt(0)
	s_andn2_b64 vcc, exec, s[10:11]
	s_cbranch_vccz .LBB0_46
	v_mov_b32_e32 v2, 1.0
	v_mov_b32_e32 v3, v2
	v_mov_b32_e32 v4, v2
	v_mov_b32_e32 v5, v2
	v_mov_b32_e32 v6, v2
	v_mov_b32_e32 v7, v2
	v_mov_b32_e32 v8, v2
	v_mov_b32_e32 v9, v2
	s_branch .LBB0_47

.LBB0_53:
	v_ashrrev_i32_e32 v12, 4, v8
	v_mad_i64_i32 v[16:17], s[20:21], v12, s18, v[6:7]
	v_ashrrev_i32_e32 v14, 4, v9
	v_lshl_add_u64 v[16:17], v[16:17], 0, v[2:3]
	v_mad_i64_i32 v[18:19], s[20:21], v14, s18, v[6:7]
	v_add_co_u32_e32 v16, vcc, 0xe000, v16
	v_ashrrev_i32_e32 v13, 31, v12
	v_lshl_add_u64 v[18:19], v[18:19], 0, v[2:3]
	v_addc_co_u32_e32 v17, vcc, 0, v17, vcc
	v_ashrrev_i32_e32 v15, 31, v14
	v_lshl_add_u64 v[20:21], v[12:13], 2, s[4:5]
	v_add_co_u32_e32 v18, vcc, 0xe000, v18
	v_lshl_add_u64 v[24:25], v[14:15], 2, s[4:5]
	global_load_dword v20, v[20:21], off nt
	s_nop 0
	global_load_dword v21, v[24:25], off nt
	v_addc_co_u32_e32 v19, vcc, 0, v19, vcc
	global_load_dword v16, v[16:17], off nt
	s_nop 0
	global_load_dword v17, v[18:19], off nt
	v_add_u32_e32 v11, -2, v11
	v_cmp_eq_u32_e32 vcc, 0, v11
	v_add_u32_e32 v9, s17, v9
	v_add_u32_e32 v8, s16, v8
	v_lshl_add_u64 v[12:13], v[12:13], 1, v[4:5]
	s_or_b64 s[12:13], vcc, s[12:13]
	v_lshl_add_u64 v[14:15], v[14:15], 1, v[4:5]
	s_waitcnt vmcnt(0)
	v_pk_mul_f32 v[16:17], v[16:17], v[20:21]
	s_nop 0
	v_cvt_pk_bf16_f32 v16, v16, v17
	global_store_short v[12:13], v16, off
	global_store_short_d16_hi v[14:15], v16, off
	s_andn2_b64 exec, exec, s[12:13]
	s_cbranch_execnz .LBB0_53
	s_or_b64 exec, exec, s[12:13]
	v_mad_u64_u32 v[6:7], s[12:13], v10, s15, v[22:23]
	v_cmp_ne_u32_e32 vcc, v1, v10
	s_orn2_b64 s[12:13], vcc, exec

.LBB0_57:
	v_ashrrev_i32_e32 v10, 4, v6
	v_mad_i64_i32 v[12:13], s[16:17], v10, s12, v[8:9]
	v_lshl_add_u64 v[12:13], v[12:13], 0, v[2:3]
	v_ashrrev_i32_e32 v11, 31, v10
	v_add_co_u32_e32 v12, vcc, 0xe000, v12
	v_lshl_add_u64 v[14:15], v[10:11], 2, s[4:5]
	s_nop 0
	v_addc_co_u32_e32 v13, vcc, 0, v13, vcc
	global_load_dword v1, v[14:15], off nt
	global_load_dword v7, v[12:13], off nt
	v_add_u32_e32 v6, s15, v6
	v_cmp_lt_i32_e32 vcc, s8, v6
	s_or_b64 s[0:1], vcc, s[0:1]
	v_lshl_add_u64 v[10:11], v[10:11], 1, v[4:5]
	s_waitcnt vmcnt(0)
	v_mul_f32_e32 v1, v7, v1
	v_cvt_pk_bf16_f32 v1, v1, s0
	global_store_short v[10:11], v1, off
	s_andn2_b64 exec, exec, s[0:1]
	s_cbranch_execnz .LBB0_57

.LBB0_64:
	s_ashr_i32 s0, s23, 6
	s_mul_hi_i32 s1, s0, 0x2fa0be83
	s_lshr_b32 s4, s1, 31
	s_ashr_i32 s1, s1, 4
	s_add_i32 s1, s1, s4
	s_mul_i32 s4, s1, 0x56
	s_sub_i32 s0, s0, s4
	s_lshl_b32 s1, s1, 9
	s_and_b32 s4, s43, 0x1c0
	s_or_b32 s4, s1, s4
	s_lshl_b32 s0, s0, 8
	s_and_b32 s1, s42, 0xe0
	s_or_b32 s44, s0, s1
	v_or_b32_e32 v2, s44, v156
	s_ashr_i32 s5, s4, 31
	s_mul_i32 s0, s4, 0x15800
	v_cmp_gt_i32_e32 vcc, s29, v2
	s_mul_hi_i32 s1, s4, 0x15800
	s_add_u32 s0, s40, s0
	v_cndmask_b32_e32 v2, 0, v2, vcc
	s_addc_u32 s1, s41, s1
	v_ashrrev_i32_e32 v3, 31, v2
	v_lshl_add_u64 v[2:3], v[2:3], 2, s[0:1]
	v_lshl_add_u64 v[4:5], v[2:3], 0, v[10:11]
	v_add_co_u32_e64 v6, s[0:1], s30, v4
	v_mov_b32_e32 v29, v11
	s_nop 0
	v_addc_co_u32_e64 v7, s[0:1], 0, v5, s[0:1]
	v_add_co_u32_e64 v8, s[0:1], s31, v4
	v_mov_b32_e32 v31, v11
	s_nop 0
	v_addc_co_u32_e64 v9, s[0:1], 0, v5, s[0:1]
	v_add_co_u32_e64 v194, s[0:1], s33, v4
	v_mov_b32_e32 v33, v11
	v_mov_b32_e32 v35, v11
	v_addc_co_u32_e64 v195, s[0:1], 0, v5, s[0:1]
	v_lshl_add_u64 v[196:197], v[2:3], 0, v[28:29]
	v_lshl_add_u64 v[198:199], v[2:3], 0, v[30:31]
	v_lshl_add_u64 v[200:201], v[2:3], 0, v[32:33]
	v_lshl_add_u64 v[202:203], v[2:3], 0, v[34:35]
	global_load_dword v29, v[4:5], off nt
	global_load_dword v31, v[6:7], off nt
	global_load_dword v33, v[8:9], off nt
	global_load_dword v35, v[194:195], off nt
	global_load_dword v85, v[196:197], off nt
	global_load_dword v87, v[198:199], off nt
	global_load_dword v89, v[200:201], off nt
	global_load_dword v91, v[202:203], off nt
	v_mov_b32_e32 v37, v11
	v_lshl_add_u64 v[4:5], v[2:3], 0, v[36:37]
	v_mov_b32_e32 v39, v11
	v_mov_b32_e32 v41, v11
	v_mov_b32_e32 v43, v11
	v_mov_b32_e32 v45, v11
	v_mov_b32_e32 v47, v11
	v_mov_b32_e32 v49, v11
	v_mov_b32_e32 v51, v11
	v_lshl_add_u64 v[6:7], v[2:3], 0, v[38:39]
	v_lshl_add_u64 v[8:9], v[2:3], 0, v[40:41]
	v_lshl_add_u64 v[194:195], v[2:3], 0, v[42:43]
	v_lshl_add_u64 v[196:197], v[2:3], 0, v[44:45]
	v_lshl_add_u64 v[198:199], v[2:3], 0, v[46:47]
	v_lshl_add_u64 v[200:201], v[2:3], 0, v[48:49]
	v_lshl_add_u64 v[202:203], v[2:3], 0, v[50:51]
	global_load_dword v37, v[4:5], off nt
	global_load_dword v39, v[6:7], off nt
	global_load_dword v41, v[8:9], off nt
	global_load_dword v43, v[194:195], off nt
	global_load_dword v45, v[196:197], off nt
	global_load_dword v47, v[198:199], off nt
	global_load_dword v49, v[200:201], off nt
	global_load_dword v51, v[202:203], off nt
	v_mov_b32_e32 v53, v11
	v_lshl_add_u64 v[4:5], v[2:3], 0, v[52:53]
	v_mov_b32_e32 v55, v11
	v_mov_b32_e32 v57, v11
	v_mov_b32_e32 v59, v11
	v_mov_b32_e32 v61, v11
	v_mov_b32_e32 v63, v11
	v_mov_b32_e32 v65, v11
	v_mov_b32_e32 v67, v11
	v_mov_b32_e32 v69, v11
	v_lshl_add_u64 v[6:7], v[2:3], 0, v[54:55]
	v_lshl_add_u64 v[8:9], v[2:3], 0, v[56:57]
	v_lshl_add_u64 v[194:195], v[2:3], 0, v[58:59]
	v_lshl_add_u64 v[196:197], v[2:3], 0, v[60:61]
	v_lshl_add_u64 v[198:199], v[2:3], 0, v[62:63]
	v_lshl_add_u64 v[200:201], v[2:3], 0, v[64:65]
	v_lshl_add_u64 v[202:203], v[2:3], 0, v[66:67]
	global_load_dword v53, v[4:5], off nt
	global_load_dword v55, v[6:7], off nt
	global_load_dword v57, v[8:9], off nt
	global_load_dword v59, v[194:195], off nt
	global_load_dword v61, v[196:197], off nt
	global_load_dword v63, v[198:199], off nt
	global_load_dword v65, v[200:201], off nt
	global_load_dword v67, v[202:203], off nt
	v_lshl_add_u64 v[4:5], v[2:3], 0, v[68:69]
	global_load_dword v69, v[4:5], off nt
	v_mov_b32_e32 v71, v11
	v_mov_b32_e32 v73, v11
	v_mov_b32_e32 v75, v11
	v_lshl_add_u64 v[4:5], v[2:3], 0, v[70:71]
	v_lshl_add_u64 v[6:7], v[2:3], 0, v[72:73]
	v_lshl_add_u64 v[8:9], v[2:3], 0, v[74:75]
	v_mov_b32_e32 v77, v11
	v_mov_b32_e32 v79, v11
	v_mov_b32_e32 v81, v11
	v_mov_b32_e32 v83, v11
	v_lshl_add_u64 v[194:195], v[2:3], 0, v[76:77]
	v_lshl_add_u64 v[196:197], v[2:3], 0, v[78:79]
	global_load_dword v71, v[4:5], off nt
	s_nop 0
	global_load_dword v6, v[6:7], off nt
	s_nop 0
	global_load_dword v7, v[8:9], off nt
	s_nop 0
	global_load_dword v8, v[194:195], off nt
	global_load_dword v9, v[196:197], off nt
	v_lshl_add_u64 v[4:5], v[2:3], 0, v[80:81]
	v_lshl_add_u64 v[2:3], v[2:3], 0, v[82:83]
	global_load_dword v4, v[4:5], off nt
	s_nop 0
	global_load_dword v2, v[2:3], off nt
	v_add_u32_e32 v5, v157, v158
	s_waitcnt vmcnt(31)
	v_cndmask_b32_e32 v3, 0, v29, vcc
	s_waitcnt vmcnt(30)
	v_cndmask_b32_e32 v29, 0, v31, vcc
	ds_write2_b32 v5, v3, v29 offset1:66
	s_waitcnt vmcnt(29)
	v_cndmask_b32_e32 v3, 0, v33, vcc
	s_waitcnt vmcnt(28)
	v_cndmask_b32_e32 v29, 0, v35, vcc
	ds_write2_b32 v5, v3, v29 offset0:132 offset1:198
	s_waitcnt vmcnt(27)
	v_cndmask_b32_e32 v3, 0, v85, vcc
	s_waitcnt vmcnt(26)
	v_cndmask_b32_e32 v29, 0, v87, vcc
	v_add_u32_e32 v5, 0x400, v5
	ds_write2_b32 v5, v3, v29 offset0:8 offset1:74
	s_waitcnt vmcnt(25)
	v_cndmask_b32_e32 v3, 0, v89, vcc
	v_add_u32_e32 v5, v157, v152
	s_waitcnt vmcnt(24)
	v_cndmask_b32_e32 v29, 0, v91, vcc
	ds_write2_b32 v5, v3, v29 offset1:66
	s_waitcnt vmcnt(23)
	v_cndmask_b32_e32 v3, 0, v37, vcc
	s_waitcnt vmcnt(22)
	v_cndmask_b32_e32 v29, 0, v39, vcc
	ds_write2_b32 v5, v3, v29 offset0:132 offset1:198
	s_waitcnt vmcnt(21)
	v_cndmask_b32_e32 v3, 0, v41, vcc
	s_waitcnt vmcnt(20)
	v_cndmask_b32_e32 v29, 0, v43, vcc
	v_add_u32_e32 v5, 0x400, v5
	ds_write2_b32 v5, v3, v29 offset0:8 offset1:74
	s_waitcnt vmcnt(19)
	v_cndmask_b32_e32 v3, 0, v45, vcc
	v_add_u32_e32 v5, v157, v153
	s_waitcnt vmcnt(18)
	v_cndmask_b32_e32 v29, 0, v47, vcc
	ds_write2_b32 v5, v3, v29 offset1:66
	s_waitcnt vmcnt(17)
	v_cndmask_b32_e32 v3, 0, v49, vcc
	s_waitcnt vmcnt(16)
	v_cndmask_b32_e32 v29, 0, v51, vcc
	ds_write2_b32 v5, v3, v29 offset0:132 offset1:198
	v_add_u32_e32 v5, 0x400, v5
	s_waitcnt vmcnt(15)
	v_cndmask_b32_e32 v3, 0, v53, vcc
	s_waitcnt vmcnt(14)
	v_cndmask_b32_e32 v29, 0, v55, vcc
	ds_write2_b32 v5, v3, v29 offset0:8 offset1:74
	s_waitcnt vmcnt(13)
	v_cndmask_b32_e32 v3, 0, v57, vcc
	v_add_u32_e32 v5, v157, v154
	s_waitcnt vmcnt(12)
	v_cndmask_b32_e32 v29, 0, v59, vcc
	ds_write2_b32 v5, v3, v29 offset1:66
	s_waitcnt vmcnt(11)
	v_cndmask_b32_e32 v3, 0, v61, vcc
	s_waitcnt vmcnt(10)
	v_cndmask_b32_e32 v29, 0, v63, vcc
	ds_write2_b32 v5, v3, v29 offset0:132 offset1:198
	s_waitcnt vmcnt(9)
	v_cndmask_b32_e32 v3, 0, v65, vcc
	s_waitcnt vmcnt(8)
	v_cndmask_b32_e32 v29, 0, v67, vcc
	v_add_u32_e32 v5, 0x400, v5
	ds_write2_b32 v5, v3, v29 offset0:8 offset1:74
	s_waitcnt vmcnt(7)
	v_cndmask_b32_e32 v3, 0, v69, vcc
	v_add_u32_e32 v5, v157, v155
	s_waitcnt vmcnt(6)
	v_cndmask_b32_e32 v29, 0, v71, vcc
	ds_write2_b32 v5, v3, v29 offset1:66
	s_waitcnt vmcnt(5)
	v_cndmask_b32_e32 v3, 0, v6, vcc
	s_waitcnt vmcnt(4)
	v_cndmask_b32_e32 v6, 0, v7, vcc
	ds_write2_b32 v5, v3, v6 offset0:132 offset1:198
	s_waitcnt vmcnt(3)
	v_cndmask_b32_e32 v3, 0, v8, vcc
	s_waitcnt vmcnt(2)
	v_cndmask_b32_e32 v6, 0, v9, vcc
	v_add_u32_e32 v5, 0x400, v5
	ds_write2_b32 v5, v3, v6 offset0:8 offset1:74
	s_waitcnt vmcnt(1)
	v_cndmask_b32_e32 v3, 0, v4, vcc
	s_waitcnt vmcnt(0)
	v_cndmask_b32_e32 v2, 0, v2, vcc
	ds_write2_b32 v5, v3, v2 offset0:140 offset1:206
	s_waitcnt lgkmcnt(0)
	s_andn2_b64 vcc, exec, s[18:19]
	s_cbranch_vccz .LBB0_62
	v_mov_b32_e32 v2, 1.0
	v_mov_b32_e32 v3, v2
	v_mov_b32_e32 v4, v2
	v_mov_b32_e32 v5, v2
	v_mov_b32_e32 v6, v2
	v_mov_b32_e32 v7, v2
	v_mov_b32_e32 v8, v2
	v_mov_b32_e32 v9, v2
	s_branch .LBB0_63

.LBB0_69:
	s_ashr_i32 s0, s40, 6
	s_lshr_b32 s1, s0, 29
	s_add_i32 s1, s0, s1
	s_and_b32 s45, s1, 0x7ffff8
	s_sub_i32 s45, s0, s45
	s_lshl_b32 s0, s1, 5
	s_and_b32 s0, s0, 0xffffff00
	s_and_b32 s1, s44, 0xc0
	s_or_b32 s0, s0, s1
	s_lshl_b32 s1, s45, 9
	s_and_b32 s45, s43, 0x1e0
	s_or_b32 s45, s1, s45
	v_or_b32_e32 v4, s45, v156
	s_ashr_i32 s1, s0, 31
	v_cmp_gt_i32_e32 vcc, s37, v4
	s_lshl_b64 s[46:47], s[0:1], 14
	s_add_u32 s46, s41, s46
	v_cndmask_b32_e32 v4, 0, v4, vcc
	s_addc_u32 s47, s42, s47
	v_ashrrev_i32_e32 v5, 31, v4
	v_lshl_add_u64 v[4:5], v[4:5], 2, s[46:47]
	v_mov_b32_e32 v85, v11
	v_lshl_add_u64 v[6:7], v[4:5], 0, v[84:85]
	v_mov_b32_e32 v87, v11
	global_load_dword v8, v[6:7], off nt
	v_lshl_add_u64 v[6:7], v[4:5], 0, v[86:87]
	v_mov_b32_e32 v89, v11
	global_load_dword v9, v[6:7], off nt
	v_lshl_add_u64 v[6:7], v[4:5], 0, v[88:89]
	v_mov_b32_e32 v91, v11
	global_load_dword v29, v[6:7], off nt
	v_lshl_add_u64 v[6:7], v[4:5], 0, v[90:91]
	v_mov_b32_e32 v93, v11
	global_load_dword v31, v[6:7], off nt
	v_lshl_add_u64 v[6:7], v[4:5], 0, v[92:93]
	v_mov_b32_e32 v95, v11
	global_load_dword v33, v[6:7], off nt
	v_lshl_add_u64 v[6:7], v[4:5], 0, v[94:95]
	v_mov_b32_e32 v97, v11
	global_load_dword v35, v[6:7], off nt
	v_lshl_add_u64 v[6:7], v[4:5], 0, v[96:97]
	v_mov_b32_e32 v99, v11
	global_load_dword v37, v[6:7], off nt
	v_lshl_add_u64 v[6:7], v[4:5], 0, v[98:99]
	v_mov_b32_e32 v101, v11
	global_load_dword v39, v[6:7], off nt
	v_lshl_add_u64 v[6:7], v[4:5], 0, v[100:101]
	v_mov_b32_e32 v103, v11
	global_load_dword v41, v[6:7], off nt
	v_lshl_add_u64 v[6:7], v[4:5], 0, v[102:103]
	v_mov_b32_e32 v105, v11
	global_load_dword v43, v[6:7], off nt
	v_lshl_add_u64 v[6:7], v[4:5], 0, v[104:105]
	v_mov_b32_e32 v107, v11
	global_load_dword v45, v[6:7], off nt
	v_lshl_add_u64 v[6:7], v[4:5], 0, v[106:107]
	v_mov_b32_e32 v109, v11
	global_load_dword v47, v[6:7], off nt
	v_lshl_add_u64 v[6:7], v[4:5], 0, v[108:109]
	v_mov_b32_e32 v111, v11
	global_load_dword v49, v[6:7], off nt
	v_lshl_add_u64 v[6:7], v[4:5], 0, v[110:111]
	v_mov_b32_e32 v113, v11
	global_load_dword v51, v[6:7], off nt
	v_lshl_add_u64 v[6:7], v[4:5], 0, v[112:113]
	v_mov_b32_e32 v115, v11
	global_load_dword v53, v[6:7], off nt
	v_lshl_add_u64 v[6:7], v[4:5], 0, v[114:115]
	v_mov_b32_e32 v117, v11
	global_load_dword v55, v[6:7], off nt
	v_lshl_add_u64 v[6:7], v[4:5], 0, v[116:117]
	v_mov_b32_e32 v119, v11
	global_load_dword v57, v[6:7], off nt
	v_lshl_add_u64 v[6:7], v[4:5], 0, v[118:119]
	v_mov_b32_e32 v121, v11
	global_load_dword v59, v[6:7], off nt
	v_lshl_add_u64 v[6:7], v[4:5], 0, v[120:121]
	v_mov_b32_e32 v123, v11
	global_load_dword v61, v[6:7], off nt
	v_lshl_add_u64 v[6:7], v[4:5], 0, v[122:123]
	v_mov_b32_e32 v125, v11
	global_load_dword v63, v[6:7], off nt
	v_lshl_add_u64 v[6:7], v[4:5], 0, v[124:125]
	v_mov_b32_e32 v127, v11
	global_load_dword v65, v[6:7], off nt
	v_lshl_add_u64 v[6:7], v[4:5], 0, v[126:127]
	v_mov_b32_e32 v129, v11
	global_load_dword v67, v[6:7], off nt
	v_lshl_add_u64 v[6:7], v[4:5], 0, v[128:129]
	v_mov_b32_e32 v131, v11
	global_load_dword v69, v[6:7], off nt
	v_lshl_add_u64 v[6:7], v[4:5], 0, v[130:131]
	v_mov_b32_e32 v133, v11
	global_load_dword v71, v[6:7], off nt
	v_lshl_add_u64 v[6:7], v[4:5], 0, v[132:133]
	v_mov_b32_e32 v135, v11
	global_load_dword v73, v[6:7], off nt
	v_lshl_add_u64 v[6:7], v[4:5], 0, v[134:135]
	v_mov_b32_e32 v137, v11
	global_load_dword v75, v[6:7], off nt
	v_lshl_add_u64 v[6:7], v[4:5], 0, v[136:137]
	v_mov_b32_e32 v139, v11
	global_load_dword v77, v[6:7], off nt
	v_lshl_add_u64 v[6:7], v[4:5], 0, v[138:139]
	v_mov_b32_e32 v141, v11
	global_load_dword v79, v[6:7], off nt
	v_lshl_add_u64 v[6:7], v[4:5], 0, v[140:141]
	v_mov_b32_e32 v143, v11
	global_load_dword v81, v[6:7], off nt
	v_lshl_add_u64 v[6:7], v[4:5], 0, v[142:143]
	v_mov_b32_e32 v145, v11
	v_mov_b32_e32 v147, v11
	global_load_dword v83, v[6:7], off nt
	v_lshl_add_u64 v[6:7], v[4:5], 0, v[144:145]
	v_lshl_add_u64 v[4:5], v[4:5], 0, v[146:147]
	global_load_dword v6, v[6:7], off nt
	s_add_i32 s40, s40, s84
	global_load_dword v4, v[4:5], off nt
	s_waitcnt vmcnt(31)
	v_cndmask_b32_e32 v5, 0, v8, vcc
	v_add_u32_e32 v7, v157, v158
	s_waitcnt vmcnt(30)
	v_cndmask_b32_e32 v8, 0, v9, vcc
	ds_write2_b32 v7, v5, v8 offset1:66
	s_waitcnt vmcnt(29)
	v_cndmask_b32_e32 v5, 0, v29, vcc
	s_waitcnt vmcnt(28)
	v_cndmask_b32_e32 v8, 0, v31, vcc
	ds_write2_b32 v7, v5, v8 offset0:132 offset1:198
	s_waitcnt vmcnt(27)
	v_cndmask_b32_e32 v5, 0, v33, vcc
	s_waitcnt vmcnt(26)
	v_cndmask_b32_e32 v8, 0, v35, vcc
	v_add_u32_e32 v7, 0x400, v7
	ds_write2_b32 v7, v5, v8 offset0:8 offset1:74
	s_waitcnt vmcnt(25)
	v_cndmask_b32_e32 v5, 0, v37, vcc
	v_add_u32_e32 v7, v157, v152
	s_waitcnt vmcnt(24)
	v_cndmask_b32_e32 v8, 0, v39, vcc
	ds_write2_b32 v7, v5, v8 offset1:66
	s_waitcnt vmcnt(23)
	v_cndmask_b32_e32 v5, 0, v41, vcc
	s_waitcnt vmcnt(22)
	v_cndmask_b32_e32 v8, 0, v43, vcc
	ds_write2_b32 v7, v5, v8 offset0:132 offset1:198
	s_waitcnt vmcnt(21)
	v_cndmask_b32_e32 v5, 0, v45, vcc
	s_waitcnt vmcnt(20)
	v_cndmask_b32_e32 v8, 0, v47, vcc
	v_add_u32_e32 v7, 0x400, v7
	ds_write2_b32 v7, v5, v8 offset0:8 offset1:74
	s_waitcnt vmcnt(19)
	v_cndmask_b32_e32 v5, 0, v49, vcc
	v_add_u32_e32 v7, v157, v153
	v_or_b32_e32 v29, s45, v1
	s_waitcnt vmcnt(18)
	v_cndmask_b32_e32 v8, 0, v51, vcc
	ds_write2_b32 v7, v5, v8 offset1:66
	v_mul_lo_u32 v206, v29, s38
	s_waitcnt vmcnt(17)
	v_cndmask_b32_e32 v5, 0, v53, vcc
	v_ashrrev_i32_e32 v207, 31, v206
	v_or_b32_e32 v29, s45, v191
	s_waitcnt vmcnt(16)
	v_cndmask_b32_e32 v8, 0, v55, vcc
	ds_write2_b32 v7, v5, v8 offset0:132 offset1:198
	v_add_u32_e32 v7, 0x400, v7
	s_waitcnt vmcnt(15)
	v_cndmask_b32_e32 v5, 0, v57, vcc
	s_add_i32 s43, s43, s34
	s_add_i32 s44, s44, s36
	s_waitcnt vmcnt(14)
	v_cndmask_b32_e32 v8, 0, v59, vcc
	ds_write2_b32 v7, v5, v8 offset0:8 offset1:74
	v_add_u32_e32 v7, v157, v154
	s_waitcnt vmcnt(13)
	v_cndmask_b32_e32 v5, 0, v61, vcc
	s_cmpk_lt_i32 s40, 0x5600
	s_waitcnt vmcnt(12)
	v_cndmask_b32_e32 v8, 0, v63, vcc
	ds_write2_b32 v7, v5, v8 offset1:66
	s_waitcnt vmcnt(11)
	v_cndmask_b32_e32 v5, 0, v65, vcc
	s_waitcnt vmcnt(10)
	v_cndmask_b32_e32 v8, 0, v67, vcc
	ds_write2_b32 v7, v5, v8 offset0:132 offset1:198
	v_add_u32_e32 v7, 0x400, v7
	s_waitcnt vmcnt(9)
	v_cndmask_b32_e32 v5, 0, v69, vcc
	s_waitcnt vmcnt(8)
	v_cndmask_b32_e32 v8, 0, v71, vcc
	ds_write2_b32 v7, v5, v8 offset0:8 offset1:74
	v_add_u32_e32 v7, v157, v155
	s_waitcnt vmcnt(7)
	v_cndmask_b32_e32 v5, 0, v73, vcc
	s_waitcnt vmcnt(6)
	v_cndmask_b32_e32 v8, 0, v75, vcc
	ds_write2_b32 v7, v5, v8 offset1:66
	s_waitcnt vmcnt(5)
	v_cndmask_b32_e32 v5, 0, v77, vcc
	s_waitcnt vmcnt(4)
	v_cndmask_b32_e32 v8, 0, v79, vcc
	ds_write2_b32 v7, v5, v8 offset0:132 offset1:198
	v_add_u32_e32 v7, 0x400, v7
	s_waitcnt vmcnt(3)
	v_cndmask_b32_e32 v5, 0, v81, vcc
	s_waitcnt vmcnt(2)
	v_cndmask_b32_e32 v8, 0, v83, vcc
	ds_write2_b32 v7, v5, v8 offset0:8 offset1:74
	v_lshl_add_u64 v[8:9], s[0:1], 1, v[2:3]
	s_waitcnt vmcnt(1)
	v_cndmask_b32_e32 v5, 0, v6, vcc
	v_lshl_add_u64 v[206:207], v[206:207], 1, v[8:9]
	s_waitcnt vmcnt(0)
	v_cndmask_b32_e32 v4, 0, v4, vcc
	ds_write2_b32 v7, v5, v4 offset0:140 offset1:206
	s_waitcnt lgkmcnt(0)
	ds_read2_b32 v[148:149], v23 offset0:33 offset1:41
	ds_read2_b32 v[150:151], v23 offset1:8
	ds_read2_b32 v[194:195], v23 offset0:66 offset1:74
	ds_read2_b32 v[196:197], v23 offset0:99 offset1:107
	ds_read2_b32 v[198:199], v23 offset0:132 offset1:140
	ds_read2_b32 v[200:201], v23 offset0:165 offset1:173
	ds_read2_b32 v[202:203], v23 offset0:198 offset1:206
	ds_read2_b32 v[204:205], v23 offset0:231 offset1:239
	s_waitcnt lgkmcnt(6)
	v_cvt_pk_bf16_f32 v4, v150, v148
	s_waitcnt lgkmcnt(4)
	v_cvt_pk_bf16_f32 v5, v194, v196
	s_waitcnt lgkmcnt(2)
	v_cvt_pk_bf16_f32 v6, v198, v200
	s_waitcnt lgkmcnt(0)
	v_cvt_pk_bf16_f32 v7, v202, v204
	v_mul_lo_u32 v148, v29, s38
	global_store_dwordx4 v[206:207], v[4:7], off
	v_or_b32_e32 v29, s45, v192
	v_mul_lo_u32 v206, v29, s38
	v_cvt_pk_bf16_f32 v4, v151, v149
	v_ashrrev_i32_e32 v149, 31, v148
	v_cvt_pk_bf16_f32 v5, v195, v197
	v_cvt_pk_bf16_f32 v6, v199, v201
	v_cvt_pk_bf16_f32 v7, v203, v205
	v_lshl_add_u64 v[148:149], v[148:149], 1, v[8:9]
	global_store_dwordx4 v[148:149], v[4:7], off
	ds_read2_b32 v[148:149], v23 offset0:49 offset1:57
	ds_read2_b32 v[150:151], v23 offset0:16 offset1:24
	ds_read2_b32 v[194:195], v23 offset0:82 offset1:90
	ds_read2_b32 v[196:197], v23 offset0:115 offset1:123
	ds_read2_b32 v[198:199], v23 offset0:148 offset1:156
	ds_read2_b32 v[200:201], v23 offset0:181 offset1:189
	ds_read2_b32 v[202:203], v23 offset0:214 offset1:222
	ds_read2_b32 v[204:205], v23 offset0:247 offset1:255
	v_ashrrev_i32_e32 v207, 31, v206
	v_or_b32_e32 v29, s45, v193
	s_waitcnt lgkmcnt(6)
	v_cvt_pk_bf16_f32 v4, v150, v148
	s_waitcnt lgkmcnt(4)
	v_cvt_pk_bf16_f32 v5, v194, v196
	s_waitcnt lgkmcnt(2)
	v_cvt_pk_bf16_f32 v6, v198, v200
	s_waitcnt lgkmcnt(0)
	v_cvt_pk_bf16_f32 v7, v202, v204
	v_lshl_add_u64 v[206:207], v[206:207], 1, v[8:9]
	v_mul_lo_u32 v148, v29, s38
	global_store_dwordx4 v[206:207], v[4:7], off
	s_nop 1
	v_cvt_pk_bf16_f32 v4, v151, v149
	v_ashrrev_i32_e32 v149, 31, v148
	v_cvt_pk_bf16_f32 v5, v195, v197
	v_cvt_pk_bf16_f32 v6, v199, v201
	v_cvt_pk_bf16_f32 v7, v203, v205
	v_lshl_add_u64 v[8:9], v[148:149], 1, v[8:9]
	global_store_dwordx4 v[8:9], v[4:7], off
	s_waitcnt lgkmcnt(0)
	s_cbranch_scc1 .LBB0_69

.LBB0_76:
	s_ashr_i32 s4, s24, 6
	s_lshr_b32 s5, s4, 28
	s_add_i32 s5, s4, s5
	s_and_b32 s40, s5, 0xfffff0
	s_sub_i32 s40, s4, s40
	s_lshl_b32 s4, s5, 5
	s_and_b32 s4, s4, 0xfffffe00
	s_and_b32 s5, s25, 0x1c0
	s_or_b32 s4, s4, s5
	s_lshl_b32 s5, s40, 8
	s_and_b32 s40, s12, 0xe0
	s_or_b32 s40, s5, s40
	v_or_b32_e32 v2, s40, v156
	s_ashr_i32 s5, s4, 31
	s_lshl_b64 s[42:43], s[4:5], 14
	v_cmp_gt_i32_e32 vcc, s37, v2
	s_add_u32 s42, s14, s42
	s_addc_u32 s43, s15, s43
	v_cndmask_b32_e32 v2, 0, v2, vcc
	v_ashrrev_i32_e32 v3, 31, v2
	v_lshl_add_u64 v[2:3], v[2:3], 2, s[42:43]
	v_mov_b32_e32 v85, v11
	v_lshl_add_u64 v[4:5], v[2:3], 0, v[84:85]
	v_mov_b32_e32 v87, v11
	v_mov_b32_e32 v89, v11
	v_mov_b32_e32 v91, v11
	v_mov_b32_e32 v93, v11
	v_mov_b32_e32 v95, v11
	v_mov_b32_e32 v97, v11
	v_mov_b32_e32 v99, v11
	v_lshl_add_u64 v[6:7], v[2:3], 0, v[86:87]
	v_lshl_add_u64 v[8:9], v[2:3], 0, v[88:89]
	v_lshl_add_u64 v[150:151], v[2:3], 0, v[90:91]
	v_lshl_add_u64 v[194:195], v[2:3], 0, v[92:93]
	v_lshl_add_u64 v[196:197], v[2:3], 0, v[94:95]
	v_lshl_add_u64 v[198:199], v[2:3], 0, v[96:97]
	v_lshl_add_u64 v[200:201], v[2:3], 0, v[98:99]
	global_load_dword v29, v[4:5], off nt
	global_load_dword v31, v[6:7], off nt
	global_load_dword v33, v[8:9], off nt
	global_load_dword v35, v[150:151], off nt
	global_load_dword v37, v[194:195], off nt
	global_load_dword v39, v[196:197], off nt
	global_load_dword v41, v[198:199], off nt
	global_load_dword v43, v[200:201], off nt
	v_mov_b32_e32 v101, v11
	v_lshl_add_u64 v[4:5], v[2:3], 0, v[100:101]
	v_mov_b32_e32 v103, v11
	v_mov_b32_e32 v105, v11
	v_mov_b32_e32 v107, v11
	v_mov_b32_e32 v109, v11
	v_mov_b32_e32 v111, v11
	v_mov_b32_e32 v113, v11
	v_mov_b32_e32 v115, v11
	v_lshl_add_u64 v[6:7], v[2:3], 0, v[102:103]
	v_lshl_add_u64 v[8:9], v[2:3], 0, v[104:105]
	v_lshl_add_u64 v[150:151], v[2:3], 0, v[106:107]
	v_lshl_add_u64 v[194:195], v[2:3], 0, v[108:109]
	v_lshl_add_u64 v[196:197], v[2:3], 0, v[110:111]
	v_lshl_add_u64 v[198:199], v[2:3], 0, v[112:113]
	v_lshl_add_u64 v[200:201], v[2:3], 0, v[114:115]
	global_load_dword v45, v[4:5], off nt
	global_load_dword v47, v[6:7], off nt
	global_load_dword v49, v[8:9], off nt
	global_load_dword v51, v[150:151], off nt
	global_load_dword v53, v[194:195], off nt
	global_load_dword v55, v[196:197], off nt
	global_load_dword v57, v[198:199], off nt
	global_load_dword v59, v[200:201], off nt
	v_mov_b32_e32 v117, v11
	v_lshl_add_u64 v[4:5], v[2:3], 0, v[116:117]
	v_mov_b32_e32 v119, v11
	v_mov_b32_e32 v121, v11
	v_mov_b32_e32 v123, v11
	v_mov_b32_e32 v125, v11
	v_mov_b32_e32 v127, v11
	v_mov_b32_e32 v129, v11
	v_mov_b32_e32 v131, v11
	v_mov_b32_e32 v133, v11
	v_lshl_add_u64 v[6:7], v[2:3], 0, v[118:119]
	v_lshl_add_u64 v[8:9], v[2:3], 0, v[120:121]
	v_lshl_add_u64 v[150:151], v[2:3], 0, v[122:123]
	v_lshl_add_u64 v[194:195], v[2:3], 0, v[124:125]
	v_lshl_add_u64 v[196:197], v[2:3], 0, v[126:127]
	v_lshl_add_u64 v[198:199], v[2:3], 0, v[128:129]
	v_lshl_add_u64 v[200:201], v[2:3], 0, v[130:131]
	global_load_dword v61, v[4:5], off nt
	global_load_dword v63, v[6:7], off nt
	global_load_dword v65, v[8:9], off nt
	global_load_dword v67, v[150:151], off nt
	global_load_dword v69, v[194:195], off nt
	global_load_dword v71, v[196:197], off nt
	global_load_dword v73, v[198:199], off nt
	global_load_dword v75, v[200:201], off nt
	v_lshl_add_u64 v[4:5], v[2:3], 0, v[132:133]
	global_load_dword v77, v[4:5], off nt
	v_mov_b32_e32 v135, v11
	v_mov_b32_e32 v137, v11
	v_mov_b32_e32 v139, v11
	v_lshl_add_u64 v[4:5], v[2:3], 0, v[134:135]
	v_lshl_add_u64 v[6:7], v[2:3], 0, v[136:137]
	v_lshl_add_u64 v[8:9], v[2:3], 0, v[138:139]
	v_mov_b32_e32 v141, v11
	v_mov_b32_e32 v143, v11
	v_mov_b32_e32 v145, v11
	v_mov_b32_e32 v147, v11
	v_lshl_add_u64 v[150:151], v[2:3], 0, v[140:141]
	v_lshl_add_u64 v[194:195], v[2:3], 0, v[142:143]
	global_load_dword v79, v[4:5], off nt
	s_nop 0
	global_load_dword v6, v[6:7], off nt
	s_nop 0
	global_load_dword v7, v[8:9], off nt
	s_nop 0
	global_load_dword v8, v[150:151], off nt
	global_load_dword v9, v[194:195], off nt
	v_lshl_add_u64 v[4:5], v[2:3], 0, v[144:145]
	v_lshl_add_u64 v[2:3], v[2:3], 0, v[146:147]
	global_load_dword v4, v[4:5], off nt
	s_nop 0
	global_load_dword v2, v[2:3], off nt
	v_add_u32_e32 v5, v157, v158
	s_waitcnt vmcnt(31)
	v_cndmask_b32_e32 v3, 0, v29, vcc
	s_waitcnt vmcnt(30)
	v_cndmask_b32_e32 v29, 0, v31, vcc
	ds_write2_b32 v5, v3, v29 offset1:66
	s_waitcnt vmcnt(29)
	v_cndmask_b32_e32 v3, 0, v33, vcc
	s_waitcnt vmcnt(28)
	v_cndmask_b32_e32 v29, 0, v35, vcc
	ds_write2_b32 v5, v3, v29 offset0:132 offset1:198
	s_waitcnt vmcnt(27)
	v_cndmask_b32_e32 v3, 0, v37, vcc
	s_waitcnt vmcnt(26)
	v_cndmask_b32_e32 v29, 0, v39, vcc
	v_add_u32_e32 v5, 0x400, v5
	ds_write2_b32 v5, v3, v29 offset0:8 offset1:74
	s_waitcnt vmcnt(25)
	v_cndmask_b32_e32 v3, 0, v41, vcc
	v_add_u32_e32 v5, v157, v152
	s_waitcnt vmcnt(24)
	v_cndmask_b32_e32 v29, 0, v43, vcc
	ds_write2_b32 v5, v3, v29 offset1:66
	s_waitcnt vmcnt(23)
	v_cndmask_b32_e32 v3, 0, v45, vcc
	s_waitcnt vmcnt(22)
	v_cndmask_b32_e32 v29, 0, v47, vcc
	ds_write2_b32 v5, v3, v29 offset0:132 offset1:198
	s_waitcnt vmcnt(21)
	v_cndmask_b32_e32 v3, 0, v49, vcc
	s_waitcnt vmcnt(20)
	v_cndmask_b32_e32 v29, 0, v51, vcc
	v_add_u32_e32 v5, 0x400, v5
	ds_write2_b32 v5, v3, v29 offset0:8 offset1:74
	s_waitcnt vmcnt(19)
	v_cndmask_b32_e32 v3, 0, v53, vcc
	v_add_u32_e32 v5, v157, v153
	s_waitcnt vmcnt(18)
	v_cndmask_b32_e32 v29, 0, v55, vcc
	ds_write2_b32 v5, v3, v29 offset1:66
	s_waitcnt vmcnt(17)
	v_cndmask_b32_e32 v3, 0, v57, vcc
	s_waitcnt vmcnt(16)
	v_cndmask_b32_e32 v29, 0, v59, vcc
	ds_write2_b32 v5, v3, v29 offset0:132 offset1:198
	v_add_u32_e32 v5, 0x400, v5
	s_waitcnt vmcnt(15)
	v_cndmask_b32_e32 v3, 0, v61, vcc
	s_waitcnt vmcnt(14)
	v_cndmask_b32_e32 v29, 0, v63, vcc
	ds_write2_b32 v5, v3, v29 offset0:8 offset1:74
	s_waitcnt vmcnt(13)
	v_cndmask_b32_e32 v3, 0, v65, vcc
	v_add_u32_e32 v5, v157, v154
	s_waitcnt vmcnt(12)
	v_cndmask_b32_e32 v29, 0, v67, vcc
	ds_write2_b32 v5, v3, v29 offset1:66
	s_waitcnt vmcnt(11)
	v_cndmask_b32_e32 v3, 0, v69, vcc
	s_waitcnt vmcnt(10)
	v_cndmask_b32_e32 v29, 0, v71, vcc
	ds_write2_b32 v5, v3, v29 offset0:132 offset1:198
	s_waitcnt vmcnt(9)
	v_cndmask_b32_e32 v3, 0, v73, vcc
	s_waitcnt vmcnt(8)
	v_cndmask_b32_e32 v29, 0, v75, vcc
	v_add_u32_e32 v5, 0x400, v5
	ds_write2_b32 v5, v3, v29 offset0:8 offset1:74
	s_waitcnt vmcnt(7)
	v_cndmask_b32_e32 v3, 0, v77, vcc
	v_add_u32_e32 v5, v157, v155
	s_waitcnt vmcnt(6)
	v_cndmask_b32_e32 v29, 0, v79, vcc
	ds_write2_b32 v5, v3, v29 offset1:66
	s_waitcnt vmcnt(5)
	v_cndmask_b32_e32 v3, 0, v6, vcc
	s_waitcnt vmcnt(4)
	v_cndmask_b32_e32 v6, 0, v7, vcc
	ds_write2_b32 v5, v3, v6 offset0:132 offset1:198
	s_waitcnt vmcnt(3)
	v_cndmask_b32_e32 v3, 0, v8, vcc
	s_waitcnt vmcnt(2)
	v_cndmask_b32_e32 v6, 0, v9, vcc
	v_add_u32_e32 v5, 0x400, v5
	ds_write2_b32 v5, v3, v6 offset0:8 offset1:74
	s_waitcnt vmcnt(1)
	v_cndmask_b32_e32 v3, 0, v4, vcc
	s_waitcnt vmcnt(0)
	v_cndmask_b32_e32 v2, 0, v2, vcc
	ds_write2_b32 v5, v3, v2 offset0:140 offset1:206
	s_waitcnt lgkmcnt(0)
	s_andn2_b64 vcc, exec, s[20:21]
	s_cbranch_vccz .LBB0_74
	v_mov_b32_e32 v2, 1.0
	v_mov_b32_e32 v3, v2
	v_mov_b32_e32 v4, v2
	v_mov_b32_e32 v5, v2
	v_mov_b32_e32 v6, v2
	v_mov_b32_e32 v7, v2
	v_mov_b32_e32 v8, v2
	v_mov_b32_e32 v9, v2
	s_branch .LBB0_75

.LBB0_81:
	s_ashr_i32 s4, s12, 6
	s_lshr_b32 s5, s4, 29
	s_add_i32 s5, s4, s5
	s_and_b32 s40, s5, 0x7ffff8
	s_sub_i32 s40, s4, s40
	s_lshl_b32 s4, s5, 5
	s_and_b32 s4, s4, 0xffffff00
	s_and_b32 s5, s23, 0xc0
	s_or_b32 s4, s4, s5
	s_lshl_b32 s5, s40, 9
	s_and_b32 s40, s22, 0x1e0
	s_or_b32 s40, s5, s40
	v_or_b32_e32 v4, s40, v156
	s_ashr_i32 s5, s4, 31
	v_cmp_gt_i32_e32 vcc, s37, v4
	s_lshl_b64 s[42:43], s[4:5], 14
	s_add_u32 s42, s24, s42
	v_cndmask_b32_e32 v4, 0, v4, vcc
	s_addc_u32 s43, s25, s43
	v_ashrrev_i32_e32 v5, 31, v4
	v_lshl_add_u64 v[4:5], v[4:5], 2, s[42:43]
	v_mov_b32_e32 v85, v11
	v_lshl_add_u64 v[6:7], v[4:5], 0, v[84:85]
	v_mov_b32_e32 v87, v11
	global_load_dword v8, v[6:7], off nt
	v_lshl_add_u64 v[6:7], v[4:5], 0, v[86:87]
	v_mov_b32_e32 v89, v11
	global_load_dword v9, v[6:7], off nt
	v_lshl_add_u64 v[6:7], v[4:5], 0, v[88:89]
	v_mov_b32_e32 v91, v11
	global_load_dword v29, v[6:7], off nt
	v_lshl_add_u64 v[6:7], v[4:5], 0, v[90:91]
	v_mov_b32_e32 v93, v11
	global_load_dword v31, v[6:7], off nt
	v_lshl_add_u64 v[6:7], v[4:5], 0, v[92:93]
	v_mov_b32_e32 v95, v11
	global_load_dword v33, v[6:7], off nt
	v_lshl_add_u64 v[6:7], v[4:5], 0, v[94:95]
	v_mov_b32_e32 v97, v11
	global_load_dword v35, v[6:7], off nt
	v_lshl_add_u64 v[6:7], v[4:5], 0, v[96:97]
	v_mov_b32_e32 v99, v11
	global_load_dword v37, v[6:7], off nt
	v_lshl_add_u64 v[6:7], v[4:5], 0, v[98:99]
	v_mov_b32_e32 v101, v11
	global_load_dword v39, v[6:7], off nt
	v_lshl_add_u64 v[6:7], v[4:5], 0, v[100:101]
	v_mov_b32_e32 v103, v11
	global_load_dword v41, v[6:7], off nt
	v_lshl_add_u64 v[6:7], v[4:5], 0, v[102:103]
	v_mov_b32_e32 v105, v11
	global_load_dword v43, v[6:7], off nt
	v_lshl_add_u64 v[6:7], v[4:5], 0, v[104:105]
	v_mov_b32_e32 v107, v11
	global_load_dword v45, v[6:7], off nt
	v_lshl_add_u64 v[6:7], v[4:5], 0, v[106:107]
	v_mov_b32_e32 v109, v11
	global_load_dword v47, v[6:7], off nt
	v_lshl_add_u64 v[6:7], v[4:5], 0, v[108:109]
	v_mov_b32_e32 v111, v11
	global_load_dword v49, v[6:7], off nt
	v_lshl_add_u64 v[6:7], v[4:5], 0, v[110:111]
	v_mov_b32_e32 v113, v11
	global_load_dword v51, v[6:7], off nt
	v_lshl_add_u64 v[6:7], v[4:5], 0, v[112:113]
	v_mov_b32_e32 v115, v11
	global_load_dword v53, v[6:7], off nt
	v_lshl_add_u64 v[6:7], v[4:5], 0, v[114:115]
	v_mov_b32_e32 v117, v11
	global_load_dword v55, v[6:7], off nt
	v_lshl_add_u64 v[6:7], v[4:5], 0, v[116:117]
	v_mov_b32_e32 v119, v11
	global_load_dword v57, v[6:7], off nt
	v_lshl_add_u64 v[6:7], v[4:5], 0, v[118:119]
	v_mov_b32_e32 v121, v11
	global_load_dword v59, v[6:7], off nt
	v_lshl_add_u64 v[6:7], v[4:5], 0, v[120:121]
	v_mov_b32_e32 v123, v11
	global_load_dword v61, v[6:7], off nt
	v_lshl_add_u64 v[6:7], v[4:5], 0, v[122:123]
	v_mov_b32_e32 v125, v11
	global_load_dword v63, v[6:7], off nt
	v_lshl_add_u64 v[6:7], v[4:5], 0, v[124:125]
	v_mov_b32_e32 v127, v11
	global_load_dword v65, v[6:7], off nt
	v_lshl_add_u64 v[6:7], v[4:5], 0, v[126:127]
	v_mov_b32_e32 v129, v11
	global_load_dword v67, v[6:7], off nt
	v_lshl_add_u64 v[6:7], v[4:5], 0, v[128:129]
	v_mov_b32_e32 v131, v11
	global_load_dword v69, v[6:7], off nt
	v_lshl_add_u64 v[6:7], v[4:5], 0, v[130:131]
	v_mov_b32_e32 v133, v11
	global_load_dword v71, v[6:7], off nt
	v_lshl_add_u64 v[6:7], v[4:5], 0, v[132:133]
	v_mov_b32_e32 v135, v11
	global_load_dword v73, v[6:7], off nt
	v_lshl_add_u64 v[6:7], v[4:5], 0, v[134:135]
	v_mov_b32_e32 v137, v11
	global_load_dword v75, v[6:7], off nt
	v_lshl_add_u64 v[6:7], v[4:5], 0, v[136:137]
	v_mov_b32_e32 v139, v11
	global_load_dword v77, v[6:7], off nt
	v_lshl_add_u64 v[6:7], v[4:5], 0, v[138:139]
	v_mov_b32_e32 v141, v11
	global_load_dword v79, v[6:7], off nt
	v_lshl_add_u64 v[6:7], v[4:5], 0, v[140:141]
	v_mov_b32_e32 v143, v11
	global_load_dword v81, v[6:7], off nt
	v_lshl_add_u64 v[6:7], v[4:5], 0, v[142:143]
	v_mov_b32_e32 v145, v11
	v_mov_b32_e32 v147, v11
	global_load_dword v83, v[6:7], off nt
	v_lshl_add_u64 v[6:7], v[4:5], 0, v[144:145]
	v_lshl_add_u64 v[4:5], v[4:5], 0, v[146:147]
	global_load_dword v6, v[6:7], off nt
	v_or_b32_e32 v206, s40, v1
	global_load_dword v4, v[4:5], off nt
	s_waitcnt vmcnt(31)
	v_cndmask_b32_e32 v5, 0, v8, vcc
	v_add_u32_e32 v7, v157, v158
	s_waitcnt vmcnt(30)
	v_cndmask_b32_e32 v8, 0, v9, vcc
	ds_write2_b32 v7, v5, v8 offset1:66
	s_waitcnt vmcnt(29)
	v_cndmask_b32_e32 v5, 0, v29, vcc
	s_waitcnt vmcnt(28)
	v_cndmask_b32_e32 v8, 0, v31, vcc
	ds_write2_b32 v7, v5, v8 offset0:132 offset1:198
	s_waitcnt vmcnt(27)
	v_cndmask_b32_e32 v5, 0, v33, vcc
	s_waitcnt vmcnt(26)
	v_cndmask_b32_e32 v8, 0, v35, vcc
	v_add_u32_e32 v7, 0x400, v7
	ds_write2_b32 v7, v5, v8 offset0:8 offset1:74
	s_waitcnt vmcnt(25)
	v_cndmask_b32_e32 v5, 0, v37, vcc
	v_add_u32_e32 v7, v157, v152
	s_waitcnt vmcnt(24)
	v_cndmask_b32_e32 v8, 0, v39, vcc
	ds_write2_b32 v7, v5, v8 offset1:66
	s_waitcnt vmcnt(23)
	v_cndmask_b32_e32 v5, 0, v41, vcc
	s_waitcnt vmcnt(22)
	v_cndmask_b32_e32 v8, 0, v43, vcc
	ds_write2_b32 v7, v5, v8 offset0:132 offset1:198
	s_waitcnt vmcnt(21)
	v_cndmask_b32_e32 v5, 0, v45, vcc
	s_waitcnt vmcnt(20)
	v_cndmask_b32_e32 v8, 0, v47, vcc
	v_add_u32_e32 v7, 0x400, v7
	ds_write2_b32 v7, v5, v8 offset0:8 offset1:74
	s_waitcnt vmcnt(19)
	v_cndmask_b32_e32 v5, 0, v49, vcc
	v_add_u32_e32 v7, v157, v153
	v_ashrrev_i32_e32 v207, 31, v206
	s_waitcnt vmcnt(18)
	v_cndmask_b32_e32 v8, 0, v51, vcc
	ds_write2_b32 v7, v5, v8 offset1:66
	v_lshlrev_b64 v[206:207], 9, v[206:207]
	s_waitcnt vmcnt(17)
	v_cndmask_b32_e32 v5, 0, v53, vcc
	s_add_i32 s12, s12, s84
	s_add_i32 s22, s22, s34
	s_waitcnt vmcnt(16)
	v_cndmask_b32_e32 v8, 0, v55, vcc
	ds_write2_b32 v7, v5, v8 offset0:132 offset1:198
	v_add_u32_e32 v7, 0x400, v7
	s_waitcnt vmcnt(15)
	v_cndmask_b32_e32 v5, 0, v57, vcc
	s_add_i32 s23, s23, s36
	s_cmpk_lt_i32 s12, 0x200
	s_waitcnt vmcnt(14)
	v_cndmask_b32_e32 v8, 0, v59, vcc
	ds_write2_b32 v7, v5, v8 offset0:8 offset1:74
	v_add_u32_e32 v7, v157, v154
	s_waitcnt vmcnt(13)
	v_cndmask_b32_e32 v5, 0, v61, vcc
	s_waitcnt vmcnt(12)
	v_cndmask_b32_e32 v8, 0, v63, vcc
	ds_write2_b32 v7, v5, v8 offset1:66
	s_waitcnt vmcnt(11)
	v_cndmask_b32_e32 v5, 0, v65, vcc
	s_waitcnt vmcnt(10)
	v_cndmask_b32_e32 v8, 0, v67, vcc
	ds_write2_b32 v7, v5, v8 offset0:132 offset1:198
	v_add_u32_e32 v7, 0x400, v7
	s_waitcnt vmcnt(9)
	v_cndmask_b32_e32 v5, 0, v69, vcc
	s_waitcnt vmcnt(8)
	v_cndmask_b32_e32 v8, 0, v71, vcc
	ds_write2_b32 v7, v5, v8 offset0:8 offset1:74
	v_add_u32_e32 v7, v157, v155
	s_waitcnt vmcnt(7)
	v_cndmask_b32_e32 v5, 0, v73, vcc
	s_waitcnt vmcnt(6)
	v_cndmask_b32_e32 v8, 0, v75, vcc
	ds_write2_b32 v7, v5, v8 offset1:66
	s_waitcnt vmcnt(5)
	v_cndmask_b32_e32 v5, 0, v77, vcc
	s_waitcnt vmcnt(4)
	v_cndmask_b32_e32 v8, 0, v79, vcc
	ds_write2_b32 v7, v5, v8 offset0:132 offset1:198
	v_add_u32_e32 v7, 0x400, v7
	s_waitcnt vmcnt(3)
	v_cndmask_b32_e32 v5, 0, v81, vcc
	s_waitcnt vmcnt(2)
	v_cndmask_b32_e32 v8, 0, v83, vcc
	ds_write2_b32 v7, v5, v8 offset0:8 offset1:74
	v_lshl_add_u64 v[8:9], s[4:5], 1, v[2:3]
	s_waitcnt vmcnt(1)
	v_cndmask_b32_e32 v5, 0, v6, vcc
	v_lshl_add_u64 v[206:207], v[8:9], 0, v[206:207]
	s_waitcnt vmcnt(0)
	v_cndmask_b32_e32 v4, 0, v4, vcc
	ds_write2_b32 v7, v5, v4 offset0:140 offset1:206
	s_waitcnt lgkmcnt(0)
	ds_read2_b32 v[148:149], v23 offset0:33 offset1:41
	ds_read2_b32 v[150:151], v23 offset1:8
	ds_read2_b32 v[194:195], v23 offset0:66 offset1:74
	ds_read2_b32 v[196:197], v23 offset0:99 offset1:107
	ds_read2_b32 v[198:199], v23 offset0:132 offset1:140
	ds_read2_b32 v[200:201], v23 offset0:165 offset1:173
	ds_read2_b32 v[202:203], v23 offset0:198 offset1:206
	ds_read2_b32 v[204:205], v23 offset0:231 offset1:239
	s_waitcnt lgkmcnt(6)
	v_cvt_pk_bf16_f32 v4, v150, v148
	s_waitcnt lgkmcnt(4)
	v_cvt_pk_bf16_f32 v5, v194, v196
	s_waitcnt lgkmcnt(2)
	v_cvt_pk_bf16_f32 v6, v198, v200
	s_waitcnt lgkmcnt(0)
	v_cvt_pk_bf16_f32 v7, v202, v204
	v_or_b32_e32 v148, s40, v191
	global_store_dwordx4 v[206:207], v[4:7], off
	v_or_b32_e32 v206, s40, v192
	v_ashrrev_i32_e32 v207, 31, v206
	v_cvt_pk_bf16_f32 v4, v151, v149
	v_ashrrev_i32_e32 v149, 31, v148
	v_lshlrev_b64 v[148:149], 9, v[148:149]
	v_cvt_pk_bf16_f32 v5, v195, v197
	v_cvt_pk_bf16_f32 v6, v199, v201
	v_cvt_pk_bf16_f32 v7, v203, v205
	v_lshl_add_u64 v[148:149], v[8:9], 0, v[148:149]
	global_store_dwordx4 v[148:149], v[4:7], off
	ds_read2_b32 v[148:149], v23 offset0:49 offset1:57
	ds_read2_b32 v[150:151], v23 offset0:16 offset1:24
	ds_read2_b32 v[194:195], v23 offset0:82 offset1:90
	ds_read2_b32 v[196:197], v23 offset0:115 offset1:123
	ds_read2_b32 v[198:199], v23 offset0:148 offset1:156
	ds_read2_b32 v[200:201], v23 offset0:181 offset1:189
	ds_read2_b32 v[202:203], v23 offset0:214 offset1:222
	ds_read2_b32 v[204:205], v23 offset0:247 offset1:255
	v_lshlrev_b64 v[206:207], 9, v[206:207]
	s_waitcnt lgkmcnt(6)
	v_cvt_pk_bf16_f32 v4, v150, v148
	s_waitcnt lgkmcnt(4)
	v_cvt_pk_bf16_f32 v5, v194, v196
	s_waitcnt lgkmcnt(2)
	v_cvt_pk_bf16_f32 v6, v198, v200
	s_waitcnt lgkmcnt(0)
	v_cvt_pk_bf16_f32 v7, v202, v204
	v_lshl_add_u64 v[206:207], v[8:9], 0, v[206:207]
	v_or_b32_e32 v148, s40, v193
	global_store_dwordx4 v[206:207], v[4:7], off
	s_nop 1
	v_cvt_pk_bf16_f32 v4, v151, v149
	v_ashrrev_i32_e32 v149, 31, v148
	v_lshlrev_b64 v[148:149], 9, v[148:149]
	v_cvt_pk_bf16_f32 v5, v195, v197
	v_cvt_pk_bf16_f32 v6, v199, v201
	v_cvt_pk_bf16_f32 v7, v203, v205
	v_lshl_add_u64 v[8:9], v[8:9], 0, v[148:149]
	global_store_dwordx4 v[8:9], v[4:7], off
	s_waitcnt lgkmcnt(0)
	s_cbranch_scc1 .LBB0_81
	s_branch .LBB0_59

.LBB0_89:
	s_ashr_i32 s10, s4, 31
	s_lshr_b32 s10, s10, 30
	s_add_i32 s10, s4, s10
	s_ashr_i32 s11, s10, 2
	s_lshl_b32 s10, s11, 6
	s_lshl_b32 s11, s11, 7
	s_sub_i32 s14, s5, s11
	s_ashr_i32 s11, s10, 31
	v_add_u32_e32 v25, s14, v156
	s_lshl_b64 s[12:13], s[10:11], 9
	v_cmp_gt_i32_e32 vcc, s9, v25
	v_lshl_add_u64 v[136:137], s[10:11], 1, v[72:73]
	v_add_u32_e32 v138, s14, v1
	s_add_u32 s10, s0, s12
	v_cndmask_b32_e32 v140, 0, v25, vcc
	v_ashrrev_i32_e32 v139, 31, v138
	v_add_u32_e32 v142, 8, v138
	v_add_u32_e32 v144, 16, v138
	s_addc_u32 s11, s1, s13
	v_ashrrev_i32_e32 v141, 31, v140
	v_add_u32_e32 v146, 24, v138
	v_lshlrev_b64 v[138:139], 13, v[138:139]
	v_ashrrev_i32_e32 v143, 31, v142
	v_ashrrev_i32_e32 v145, 31, v144
	v_lshl_add_u64 v[140:141], v[140:141], 2, s[10:11]
	v_mov_b32_e32 v75, v71
	v_mov_b32_e32 v77, v71
	v_mov_b32_e32 v79, v71
	v_mov_b32_e32 v81, v71
	v_mov_b32_e32 v83, v71
	v_mov_b32_e32 v85, v71
	v_mov_b32_e32 v87, v71
	v_mov_b32_e32 v89, v71
	v_mov_b32_e32 v91, v71
	v_mov_b32_e32 v93, v71
	v_mov_b32_e32 v95, v71
	v_mov_b32_e32 v97, v71
	v_mov_b32_e32 v99, v71
	v_mov_b32_e32 v101, v71
	v_mov_b32_e32 v103, v71
	v_mov_b32_e32 v105, v71
	v_mov_b32_e32 v107, v71
	v_mov_b32_e32 v109, v71
	v_mov_b32_e32 v111, v71
	v_mov_b32_e32 v113, v71
	v_mov_b32_e32 v115, v71
	v_mov_b32_e32 v117, v71
	v_mov_b32_e32 v119, v71
	v_mov_b32_e32 v121, v71
	v_mov_b32_e32 v123, v71
	v_mov_b32_e32 v125, v71
	v_mov_b32_e32 v127, v71
	v_mov_b32_e32 v129, v71
	v_mov_b32_e32 v131, v71
	v_mov_b32_e32 v133, v71
	v_mov_b32_e32 v135, v71
	v_lshl_add_u64 v[160:161], v[136:137], 0, v[138:139]
	v_lshlrev_b64 v[138:139], 13, v[142:143]
	v_lshlrev_b64 v[142:143], 13, v[144:145]
	v_lshl_add_u64 v[144:145], v[140:141], 0, v[70:71]
	v_lshl_add_u64 v[148:149], v[140:141], 0, v[74:75]
	v_lshl_add_u64 v[150:151], v[140:141], 0, v[76:77]
	v_lshl_add_u64 v[164:165], v[140:141], 0, v[78:79]
	v_lshl_add_u64 v[166:167], v[140:141], 0, v[80:81]
	v_lshl_add_u64 v[168:169], v[140:141], 0, v[82:83]
	v_lshl_add_u64 v[170:171], v[140:141], 0, v[84:85]
	v_lshl_add_u64 v[172:173], v[140:141], 0, v[86:87]
	v_lshl_add_u64 v[174:175], v[140:141], 0, v[88:89]
	v_lshl_add_u64 v[176:177], v[140:141], 0, v[90:91]
	v_lshl_add_u64 v[178:179], v[140:141], 0, v[92:93]
	v_lshl_add_u64 v[180:181], v[140:141], 0, v[94:95]
	v_lshl_add_u64 v[182:183], v[140:141], 0, v[96:97]
	v_lshl_add_u64 v[184:185], v[140:141], 0, v[98:99]
	v_lshl_add_u64 v[186:187], v[140:141], 0, v[100:101]
	v_lshl_add_u64 v[188:189], v[140:141], 0, v[102:103]
	v_lshl_add_u64 v[190:191], v[140:141], 0, v[104:105]
	v_lshl_add_u64 v[192:193], v[140:141], 0, v[106:107]
	v_lshl_add_u64 v[194:195], v[140:141], 0, v[108:109]
	v_lshl_add_u64 v[196:197], v[140:141], 0, v[110:111]
	v_lshl_add_u64 v[198:199], v[140:141], 0, v[112:113]
	v_lshl_add_u64 v[200:201], v[140:141], 0, v[114:115]
	v_lshl_add_u64 v[202:203], v[140:141], 0, v[116:117]
	v_lshl_add_u64 v[204:205], v[140:141], 0, v[118:119]
	v_lshl_add_u64 v[206:207], v[140:141], 0, v[120:121]
	v_lshl_add_u64 v[208:209], v[140:141], 0, v[122:123]
	v_lshl_add_u64 v[210:211], v[140:141], 0, v[124:125]
	v_lshl_add_u64 v[212:213], v[140:141], 0, v[126:127]
	v_lshl_add_u64 v[214:215], v[140:141], 0, v[128:129]
	v_lshl_add_u64 v[216:217], v[140:141], 0, v[130:131]
	v_lshl_add_u64 v[218:219], v[140:141], 0, v[132:133]
	v_lshl_add_u64 v[140:141], v[140:141], 0, v[134:135]
	global_load_dword v25, v[144:145], off nt
	global_load_dword v27, v[148:149], off nt
	global_load_dword v29, v[150:151], off nt
	global_load_dword v31, v[164:165], off nt
	global_load_dword v33, v[166:167], off nt
	global_load_dword v35, v[168:169], off nt
	global_load_dword v37, v[170:171], off nt
	global_load_dword v39, v[172:173], off nt
	global_load_dword v41, v[174:175], off nt
	global_load_dword v43, v[176:177], off nt
	global_load_dword v45, v[178:179], off nt
	global_load_dword v47, v[180:181], off nt
	global_load_dword v49, v[182:183], off nt
	global_load_dword v51, v[184:185], off nt
	global_load_dword v53, v[186:187], off nt
	global_load_dword v55, v[188:189], off nt
	global_load_dword v57, v[190:191], off nt
	global_load_dword v59, v[192:193], off nt
	global_load_dword v61, v[194:195], off nt
	global_load_dword v63, v[196:197], off nt
	global_load_dword v65, v[198:199], off nt
	global_load_dword v67, v[200:201], off nt
	global_load_dword v69, v[202:203], off nt
	global_load_dword v75, v[204:205], off nt
	global_load_dword v77, v[206:207], off nt
	global_load_dword v79, v[208:209], off nt
	global_load_dword v81, v[210:211], off nt
	global_load_dword v83, v[212:213], off nt
	global_load_dword v85, v[214:215], off nt
	global_load_dword v87, v[216:217], off nt
	global_load_dword v89, v[218:219], off nt
	global_load_dword v91, v[140:141], off nt
	v_add_u32_e32 v3, v157, v158
	v_add_u32_e32 v5, v157, v152
	v_add_u32_e32 v7, v157, v153
	v_add_u32_e32 v9, v157, v154
	v_add_u32_e32 v11, v157, v155
	v_add_u32_e32 v13, 0x400, v3
	v_add_u32_e32 v15, 0x400, v5
	v_add_u32_e32 v17, 0x400, v7
	v_add_u32_e32 v19, 0x400, v9
	v_add_u32_e32 v21, 0x400, v11
	v_ashrrev_i32_e32 v147, 31, v146
	v_lshlrev_b64 v[140:141], 13, v[146:147]
	v_lshl_add_u64 v[166:167], v[136:137], 0, v[142:143]
	v_lshl_add_u64 v[168:169], v[136:137], 0, v[140:141]
	v_lshl_add_u64 v[164:165], v[136:137], 0, v[138:139]
	s_add_i32 s4, s4, s84
	s_add_i32 s5, s5, s8
	s_cmpk_lt_i32 s4, 0x100
	s_waitcnt vmcnt(31)
	v_cndmask_b32_e32 v25, 0, v25, vcc
	s_waitcnt vmcnt(30)
	v_cndmask_b32_e32 v27, 0, v27, vcc
	s_waitcnt vmcnt(29)
	v_cndmask_b32_e32 v29, 0, v29, vcc
	s_waitcnt vmcnt(28)
	v_cndmask_b32_e32 v31, 0, v31, vcc
	s_waitcnt vmcnt(27)
	v_cndmask_b32_e32 v33, 0, v33, vcc
	s_waitcnt vmcnt(26)
	v_cndmask_b32_e32 v35, 0, v35, vcc
	s_waitcnt vmcnt(25)
	v_cndmask_b32_e32 v37, 0, v37, vcc
	s_waitcnt vmcnt(24)
	v_cndmask_b32_e32 v39, 0, v39, vcc
	s_waitcnt vmcnt(23)
	v_cndmask_b32_e32 v41, 0, v41, vcc
	s_waitcnt vmcnt(22)
	v_cndmask_b32_e32 v43, 0, v43, vcc
	s_waitcnt vmcnt(21)
	v_cndmask_b32_e32 v45, 0, v45, vcc
	s_waitcnt vmcnt(20)
	v_cndmask_b32_e32 v47, 0, v47, vcc
	s_waitcnt vmcnt(19)
	v_cndmask_b32_e32 v49, 0, v49, vcc
	s_waitcnt vmcnt(18)
	v_cndmask_b32_e32 v51, 0, v51, vcc
	s_waitcnt vmcnt(17)
	v_cndmask_b32_e32 v53, 0, v53, vcc
	s_waitcnt vmcnt(16)
	v_cndmask_b32_e32 v55, 0, v55, vcc
	s_waitcnt vmcnt(15)
	v_cndmask_b32_e32 v57, 0, v57, vcc
	s_waitcnt vmcnt(14)
	v_cndmask_b32_e32 v59, 0, v59, vcc
	s_waitcnt vmcnt(13)
	v_cndmask_b32_e32 v61, 0, v61, vcc
	s_waitcnt vmcnt(12)
	v_cndmask_b32_e32 v63, 0, v63, vcc
	s_waitcnt vmcnt(11)
	v_cndmask_b32_e32 v65, 0, v65, vcc
	s_waitcnt vmcnt(10)
	v_cndmask_b32_e32 v67, 0, v67, vcc
	s_waitcnt vmcnt(9)
	v_cndmask_b32_e32 v69, 0, v69, vcc
	s_waitcnt vmcnt(8)
	v_cndmask_b32_e32 v75, 0, v75, vcc
	s_waitcnt vmcnt(7)
	v_cndmask_b32_e32 v77, 0, v77, vcc
	s_waitcnt vmcnt(6)
	v_cndmask_b32_e32 v79, 0, v79, vcc
	s_waitcnt vmcnt(5)
	v_cndmask_b32_e32 v81, 0, v81, vcc
	s_waitcnt vmcnt(4)
	v_cndmask_b32_e32 v83, 0, v83, vcc
	s_waitcnt vmcnt(3)
	v_cndmask_b32_e32 v85, 0, v85, vcc
	s_waitcnt vmcnt(2)
	v_cndmask_b32_e32 v87, 0, v87, vcc
	s_waitcnt vmcnt(1)
	v_cndmask_b32_e32 v89, 0, v89, vcc
	s_waitcnt vmcnt(0)
	v_cndmask_b32_e32 v91, 0, v91, vcc
	ds_write2_b32 v3, v25, v27 offset1:66
	ds_write2_b32 v3, v29, v31 offset0:132 offset1:198
	ds_write2_b32 v13, v33, v35 offset0:8 offset1:74
	ds_write2_b32 v5, v37, v39 offset1:66
	ds_write2_b32 v5, v41, v43 offset0:132 offset1:198
	ds_write2_b32 v15, v45, v47 offset0:8 offset1:74
	ds_write2_b32 v7, v49, v51 offset1:66
	ds_write2_b32 v7, v53, v55 offset0:132 offset1:198
	ds_write2_b32 v17, v57, v59 offset0:8 offset1:74
	ds_write2_b32 v9, v61, v63 offset1:66
	ds_write2_b32 v9, v65, v67 offset0:132 offset1:198
	ds_write2_b32 v19, v69, v75 offset0:8 offset1:74
	ds_write2_b32 v11, v77, v79 offset1:66
	ds_write2_b32 v11, v81, v83 offset0:132 offset1:198
	ds_write2_b32 v21, v85, v87 offset0:8 offset1:74
	ds_write2_b32 v21, v89, v91 offset0:140 offset1:206
	s_waitcnt lgkmcnt(0)
	ds_read2_b32 v[140:141], v23 offset0:33 offset1:41
	ds_read2_b32 v[142:143], v23 offset1:8
	ds_read2_b32 v[144:145], v23 offset0:66 offset1:74
	ds_read2_b32 v[146:147], v23 offset0:99 offset1:107
	ds_read2_b32 v[148:149], v23 offset0:132 offset1:140
	ds_read2_b32 v[150:151], v23 offset0:165 offset1:173
	ds_read2_b32 v[170:171], v23 offset0:198 offset1:206
	ds_read2_b32 v[172:173], v23 offset0:231 offset1:239
	ds_read2_b32 v[174:175], v23 offset0:49 offset1:57
	ds_read2_b32 v[176:177], v23 offset0:16 offset1:24
	ds_read2_b32 v[178:179], v23 offset0:82 offset1:90
	ds_read2_b32 v[180:181], v23 offset0:115 offset1:123
	ds_read2_b32 v[182:183], v23 offset0:148 offset1:156
	ds_read2_b32 v[184:185], v23 offset0:181 offset1:189
	ds_read2_b32 v[186:187], v23 offset0:214 offset1:222
	ds_read2_b32 v[188:189], v23 offset0:247 offset1:255
	s_waitcnt lgkmcnt(14)
	v_cvt_pk_bf16_f32 v136, v142, v140
	s_waitcnt lgkmcnt(12)
	v_cvt_pk_bf16_f32 v137, v144, v146
	s_waitcnt lgkmcnt(10)
	v_cvt_pk_bf16_f32 v138, v148, v150
	s_waitcnt lgkmcnt(8)
	v_cvt_pk_bf16_f32 v139, v170, v172
	v_cvt_pk_bf16_f32 v140, v143, v141
	v_cvt_pk_bf16_f32 v141, v145, v147
	v_cvt_pk_bf16_f32 v142, v149, v151
	v_cvt_pk_bf16_f32 v143, v171, v173
	s_waitcnt lgkmcnt(6)
	v_cvt_pk_bf16_f32 v144, v176, v174
	s_waitcnt lgkmcnt(4)
	v_cvt_pk_bf16_f32 v145, v178, v180
	s_waitcnt lgkmcnt(2)
	v_cvt_pk_bf16_f32 v146, v182, v184
	s_waitcnt lgkmcnt(0)
	v_cvt_pk_bf16_f32 v147, v186, v188
	v_cvt_pk_bf16_f32 v148, v177, v175
	v_cvt_pk_bf16_f32 v149, v179, v181
	v_cvt_pk_bf16_f32 v150, v183, v185
	v_cvt_pk_bf16_f32 v151, v187, v189
	global_store_dwordx4 v[160:161], v[136:139], off
	global_store_dwordx4 v[164:165], v[140:143], off
	global_store_dwordx4 v[166:167], v[144:147], off
	global_store_dwordx4 v[168:169], v[148:151], off
	s_waitcnt lgkmcnt(0)
	s_cbranch_scc1 .LBB0_89

.LBB0_92:
	s_ashr_i32 s11, s5, 31
	s_lshr_b32 s11, s11, 30
	s_add_i32 s11, s5, s11
	s_ashr_i32 s11, s11, 2
	s_lshl_b32 s12, s11, 6
	s_lshl_b32 s11, s11, 7
	s_sub_i32 s11, s8, s11
	s_ashr_i32 s13, s12, 31
	v_add_u32_e32 v25, s11, v156
	s_lshl_b64 s[14:15], s[12:13], 9
	v_cmp_gt_i32_e32 vcc, s10, v25
	v_lshl_add_u64 v[136:137], s[12:13], 1, v[72:73]
	v_add_u32_e32 v138, s11, v1
	s_add_u32 s12, s0, s14
	v_cndmask_b32_e32 v140, 0, v25, vcc
	v_ashrrev_i32_e32 v139, 31, v138
	v_add_u32_e32 v142, 8, v138
	v_add_u32_e32 v144, 16, v138
	s_addc_u32 s13, s1, s15
	v_ashrrev_i32_e32 v141, 31, v140
	v_add_u32_e32 v146, 24, v138
	v_lshlrev_b64 v[138:139], 13, v[138:139]
	v_ashrrev_i32_e32 v143, 31, v142
	v_ashrrev_i32_e32 v145, 31, v144
	v_lshl_add_u64 v[140:141], v[140:141], 2, s[12:13]
	v_mov_b32_e32 v75, v71
	v_mov_b32_e32 v77, v71
	v_mov_b32_e32 v79, v71
	v_mov_b32_e32 v81, v71
	v_mov_b32_e32 v83, v71
	v_mov_b32_e32 v85, v71
	v_mov_b32_e32 v87, v71
	v_mov_b32_e32 v89, v71
	v_mov_b32_e32 v91, v71
	v_mov_b32_e32 v93, v71
	v_mov_b32_e32 v95, v71
	v_mov_b32_e32 v97, v71
	v_mov_b32_e32 v99, v71
	v_mov_b32_e32 v101, v71
	v_mov_b32_e32 v103, v71
	v_mov_b32_e32 v105, v71
	v_mov_b32_e32 v107, v71
	v_mov_b32_e32 v109, v71
	v_mov_b32_e32 v111, v71
	v_mov_b32_e32 v113, v71
	v_mov_b32_e32 v115, v71
	v_mov_b32_e32 v117, v71
	v_mov_b32_e32 v119, v71
	v_mov_b32_e32 v121, v71
	v_mov_b32_e32 v123, v71
	v_mov_b32_e32 v125, v71
	v_mov_b32_e32 v127, v71
	v_mov_b32_e32 v129, v71
	v_mov_b32_e32 v131, v71
	v_mov_b32_e32 v133, v71
	v_mov_b32_e32 v135, v71
	v_lshl_add_u64 v[160:161], v[136:137], 0, v[138:139]
	v_lshlrev_b64 v[138:139], 13, v[142:143]
	v_lshlrev_b64 v[142:143], 13, v[144:145]
	v_lshl_add_u64 v[144:145], v[140:141], 0, v[70:71]
	v_lshl_add_u64 v[148:149], v[140:141], 0, v[74:75]
	v_lshl_add_u64 v[150:151], v[140:141], 0, v[76:77]
	v_lshl_add_u64 v[164:165], v[140:141], 0, v[78:79]
	v_lshl_add_u64 v[166:167], v[140:141], 0, v[80:81]
	v_lshl_add_u64 v[168:169], v[140:141], 0, v[82:83]
	v_lshl_add_u64 v[170:171], v[140:141], 0, v[84:85]
	v_lshl_add_u64 v[172:173], v[140:141], 0, v[86:87]
	v_lshl_add_u64 v[174:175], v[140:141], 0, v[88:89]
	v_lshl_add_u64 v[176:177], v[140:141], 0, v[90:91]
	v_lshl_add_u64 v[178:179], v[140:141], 0, v[92:93]
	v_lshl_add_u64 v[180:181], v[140:141], 0, v[94:95]
	v_lshl_add_u64 v[182:183], v[140:141], 0, v[96:97]
	v_lshl_add_u64 v[184:185], v[140:141], 0, v[98:99]
	v_lshl_add_u64 v[186:187], v[140:141], 0, v[100:101]
	v_lshl_add_u64 v[188:189], v[140:141], 0, v[102:103]
	v_lshl_add_u64 v[190:191], v[140:141], 0, v[104:105]
	v_lshl_add_u64 v[192:193], v[140:141], 0, v[106:107]
	v_lshl_add_u64 v[194:195], v[140:141], 0, v[108:109]
	v_lshl_add_u64 v[196:197], v[140:141], 0, v[110:111]
	v_lshl_add_u64 v[198:199], v[140:141], 0, v[112:113]
	v_lshl_add_u64 v[200:201], v[140:141], 0, v[114:115]
	v_lshl_add_u64 v[202:203], v[140:141], 0, v[116:117]
	v_lshl_add_u64 v[204:205], v[140:141], 0, v[118:119]
	v_lshl_add_u64 v[206:207], v[140:141], 0, v[120:121]
	v_lshl_add_u64 v[208:209], v[140:141], 0, v[122:123]
	v_lshl_add_u64 v[210:211], v[140:141], 0, v[124:125]
	v_lshl_add_u64 v[212:213], v[140:141], 0, v[126:127]
	v_lshl_add_u64 v[214:215], v[140:141], 0, v[128:129]
	v_lshl_add_u64 v[216:217], v[140:141], 0, v[130:131]
	v_lshl_add_u64 v[218:219], v[140:141], 0, v[132:133]
	v_lshl_add_u64 v[140:141], v[140:141], 0, v[134:135]
	global_load_dword v25, v[144:145], off nt
	global_load_dword v27, v[148:149], off nt
	global_load_dword v29, v[150:151], off nt
	global_load_dword v31, v[164:165], off nt
	global_load_dword v33, v[166:167], off nt
	global_load_dword v35, v[168:169], off nt
	global_load_dword v37, v[170:171], off nt
	global_load_dword v39, v[172:173], off nt
	global_load_dword v41, v[174:175], off nt
	global_load_dword v43, v[176:177], off nt
	global_load_dword v45, v[178:179], off nt
	global_load_dword v47, v[180:181], off nt
	global_load_dword v49, v[182:183], off nt
	global_load_dword v51, v[184:185], off nt
	global_load_dword v53, v[186:187], off nt
	global_load_dword v55, v[188:189], off nt
	global_load_dword v57, v[190:191], off nt
	global_load_dword v59, v[192:193], off nt
	global_load_dword v61, v[194:195], off nt
	global_load_dword v63, v[196:197], off nt
	global_load_dword v65, v[198:199], off nt
	global_load_dword v67, v[200:201], off nt
	global_load_dword v69, v[202:203], off nt
	global_load_dword v75, v[204:205], off nt
	global_load_dword v77, v[206:207], off nt
	global_load_dword v79, v[208:209], off nt
	global_load_dword v81, v[210:211], off nt
	global_load_dword v83, v[212:213], off nt
	global_load_dword v85, v[214:215], off nt
	global_load_dword v87, v[216:217], off nt
	global_load_dword v89, v[218:219], off nt
	global_load_dword v91, v[140:141], off nt
	v_add_u32_e32 v3, v157, v158
	v_add_u32_e32 v5, v157, v152
	v_add_u32_e32 v7, v157, v153
	v_add_u32_e32 v9, v157, v154
	v_add_u32_e32 v11, v157, v155
	v_add_u32_e32 v13, 0x400, v3
	v_add_u32_e32 v15, 0x400, v5
	v_add_u32_e32 v17, 0x400, v7
	v_add_u32_e32 v19, 0x400, v9
	v_add_u32_e32 v21, 0x400, v11
	v_ashrrev_i32_e32 v147, 31, v146
	v_lshlrev_b64 v[140:141], 13, v[146:147]
	v_lshl_add_u64 v[166:167], v[136:137], 0, v[142:143]
	v_lshl_add_u64 v[168:169], v[136:137], 0, v[140:141]
	v_lshl_add_u64 v[164:165], v[136:137], 0, v[138:139]
	s_add_i32 s5, s5, s84
	s_add_i32 s8, s8, s9
	s_cmpk_lt_i32 s5, 0x100
	s_waitcnt vmcnt(31)
	v_cndmask_b32_e32 v25, 0, v25, vcc
	s_waitcnt vmcnt(30)
	v_cndmask_b32_e32 v27, 0, v27, vcc
	s_waitcnt vmcnt(29)
	v_cndmask_b32_e32 v29, 0, v29, vcc
	s_waitcnt vmcnt(28)
	v_cndmask_b32_e32 v31, 0, v31, vcc
	s_waitcnt vmcnt(27)
	v_cndmask_b32_e32 v33, 0, v33, vcc
	s_waitcnt vmcnt(26)
	v_cndmask_b32_e32 v35, 0, v35, vcc
	s_waitcnt vmcnt(25)
	v_cndmask_b32_e32 v37, 0, v37, vcc
	s_waitcnt vmcnt(24)
	v_cndmask_b32_e32 v39, 0, v39, vcc
	s_waitcnt vmcnt(23)
	v_cndmask_b32_e32 v41, 0, v41, vcc
	s_waitcnt vmcnt(22)
	v_cndmask_b32_e32 v43, 0, v43, vcc
	s_waitcnt vmcnt(21)
	v_cndmask_b32_e32 v45, 0, v45, vcc
	s_waitcnt vmcnt(20)
	v_cndmask_b32_e32 v47, 0, v47, vcc
	s_waitcnt vmcnt(19)
	v_cndmask_b32_e32 v49, 0, v49, vcc
	s_waitcnt vmcnt(18)
	v_cndmask_b32_e32 v51, 0, v51, vcc
	s_waitcnt vmcnt(17)
	v_cndmask_b32_e32 v53, 0, v53, vcc
	s_waitcnt vmcnt(16)
	v_cndmask_b32_e32 v55, 0, v55, vcc
	s_waitcnt vmcnt(15)
	v_cndmask_b32_e32 v57, 0, v57, vcc
	s_waitcnt vmcnt(14)
	v_cndmask_b32_e32 v59, 0, v59, vcc
	s_waitcnt vmcnt(13)
	v_cndmask_b32_e32 v61, 0, v61, vcc
	s_waitcnt vmcnt(12)
	v_cndmask_b32_e32 v63, 0, v63, vcc
	s_waitcnt vmcnt(11)
	v_cndmask_b32_e32 v65, 0, v65, vcc
	s_waitcnt vmcnt(10)
	v_cndmask_b32_e32 v67, 0, v67, vcc
	s_waitcnt vmcnt(9)
	v_cndmask_b32_e32 v69, 0, v69, vcc
	s_waitcnt vmcnt(8)
	v_cndmask_b32_e32 v75, 0, v75, vcc
	s_waitcnt vmcnt(7)
	v_cndmask_b32_e32 v77, 0, v77, vcc
	s_waitcnt vmcnt(6)
	v_cndmask_b32_e32 v79, 0, v79, vcc
	s_waitcnt vmcnt(5)
	v_cndmask_b32_e32 v81, 0, v81, vcc
	s_waitcnt vmcnt(4)
	v_cndmask_b32_e32 v83, 0, v83, vcc
	s_waitcnt vmcnt(3)
	v_cndmask_b32_e32 v85, 0, v85, vcc
	s_waitcnt vmcnt(2)
	v_cndmask_b32_e32 v87, 0, v87, vcc
	s_waitcnt vmcnt(1)
	v_cndmask_b32_e32 v89, 0, v89, vcc
	s_waitcnt vmcnt(0)
	v_cndmask_b32_e32 v91, 0, v91, vcc
	ds_write2_b32 v3, v25, v27 offset1:66
	ds_write2_b32 v3, v29, v31 offset0:132 offset1:198
	ds_write2_b32 v13, v33, v35 offset0:8 offset1:74
	ds_write2_b32 v5, v37, v39 offset1:66
	ds_write2_b32 v5, v41, v43 offset0:132 offset1:198
	ds_write2_b32 v15, v45, v47 offset0:8 offset1:74
	ds_write2_b32 v7, v49, v51 offset1:66
	ds_write2_b32 v7, v53, v55 offset0:132 offset1:198
	ds_write2_b32 v17, v57, v59 offset0:8 offset1:74
	ds_write2_b32 v9, v61, v63 offset1:66
	ds_write2_b32 v9, v65, v67 offset0:132 offset1:198
	ds_write2_b32 v19, v69, v75 offset0:8 offset1:74
	ds_write2_b32 v11, v77, v79 offset1:66
	ds_write2_b32 v11, v81, v83 offset0:132 offset1:198
	ds_write2_b32 v21, v85, v87 offset0:8 offset1:74
	ds_write2_b32 v21, v89, v91 offset0:140 offset1:206
	s_waitcnt lgkmcnt(0)
	ds_read2_b32 v[140:141], v23 offset0:33 offset1:41
	ds_read2_b32 v[142:143], v23 offset1:8
	ds_read2_b32 v[144:145], v23 offset0:66 offset1:74
	ds_read2_b32 v[146:147], v23 offset0:99 offset1:107
	ds_read2_b32 v[148:149], v23 offset0:132 offset1:140
	ds_read2_b32 v[150:151], v23 offset0:165 offset1:173
	ds_read2_b32 v[170:171], v23 offset0:198 offset1:206
	ds_read2_b32 v[172:173], v23 offset0:231 offset1:239
	ds_read2_b32 v[174:175], v23 offset0:49 offset1:57
	ds_read2_b32 v[176:177], v23 offset0:16 offset1:24
	ds_read2_b32 v[178:179], v23 offset0:82 offset1:90
	ds_read2_b32 v[180:181], v23 offset0:115 offset1:123
	ds_read2_b32 v[182:183], v23 offset0:148 offset1:156
	ds_read2_b32 v[184:185], v23 offset0:181 offset1:189
	ds_read2_b32 v[186:187], v23 offset0:214 offset1:222
	ds_read2_b32 v[188:189], v23 offset0:247 offset1:255
	s_waitcnt lgkmcnt(14)
	v_cvt_pk_bf16_f32 v136, v142, v140
	s_waitcnt lgkmcnt(12)
	v_cvt_pk_bf16_f32 v137, v144, v146
	s_waitcnt lgkmcnt(10)
	v_cvt_pk_bf16_f32 v138, v148, v150
	s_waitcnt lgkmcnt(8)
	v_cvt_pk_bf16_f32 v139, v170, v172
	v_cvt_pk_bf16_f32 v140, v143, v141
	v_cvt_pk_bf16_f32 v141, v145, v147
	v_cvt_pk_bf16_f32 v142, v149, v151
	v_cvt_pk_bf16_f32 v143, v171, v173
	s_waitcnt lgkmcnt(6)
	v_cvt_pk_bf16_f32 v144, v176, v174
	s_waitcnt lgkmcnt(4)
	v_cvt_pk_bf16_f32 v145, v178, v180
	s_waitcnt lgkmcnt(2)
	v_cvt_pk_bf16_f32 v146, v182, v184
	s_waitcnt lgkmcnt(0)
	v_cvt_pk_bf16_f32 v147, v186, v188
	v_cvt_pk_bf16_f32 v148, v177, v175
	v_cvt_pk_bf16_f32 v149, v179, v181
	v_cvt_pk_bf16_f32 v150, v183, v185
	v_cvt_pk_bf16_f32 v151, v187, v189
	global_store_dwordx4 v[160:161], v[136:139], off
	global_store_dwordx4 v[164:165], v[140:143], off
	global_store_dwordx4 v[166:167], v[144:147], off
	global_store_dwordx4 v[168:169], v[148:151], off
	s_waitcnt lgkmcnt(0)
	s_cbranch_scc1 .LBB0_92

.LBB0_95:
	s_ashr_i32 s11, s5, 31
	s_lshr_b32 s11, s11, 30
	s_add_i32 s11, s5, s11
	s_ashr_i32 s11, s11, 2
	s_lshl_b32 s12, s11, 6
	s_lshl_b32 s11, s11, 7
	s_sub_i32 s11, s8, s11
	s_ashr_i32 s13, s12, 31
	v_add_u32_e32 v25, s11, v156
	s_lshl_b64 s[14:15], s[12:13], 9
	v_cmp_gt_i32_e32 vcc, s10, v25
	v_lshl_add_u64 v[136:137], s[12:13], 1, v[72:73]
	v_add_u32_e32 v138, s11, v1
	s_add_u32 s12, s0, s14
	v_cndmask_b32_e32 v140, 0, v25, vcc
	v_ashrrev_i32_e32 v139, 31, v138
	v_add_u32_e32 v142, 8, v138
	v_add_u32_e32 v144, 16, v138
	s_addc_u32 s13, s1, s15
	v_ashrrev_i32_e32 v141, 31, v140
	v_add_u32_e32 v146, 24, v138
	v_lshlrev_b64 v[138:139], 8, v[138:139]
	v_ashrrev_i32_e32 v143, 31, v142
	v_ashrrev_i32_e32 v145, 31, v144
	v_lshl_add_u64 v[140:141], v[140:141], 2, s[12:13]
	v_mov_b32_e32 v75, v71
	v_mov_b32_e32 v77, v71
	v_mov_b32_e32 v79, v71
	v_mov_b32_e32 v81, v71
	v_mov_b32_e32 v83, v71
	v_mov_b32_e32 v85, v71
	v_mov_b32_e32 v87, v71
	v_mov_b32_e32 v89, v71
	v_mov_b32_e32 v91, v71
	v_mov_b32_e32 v93, v71
	v_mov_b32_e32 v95, v71
	v_mov_b32_e32 v97, v71
	v_mov_b32_e32 v99, v71
	v_mov_b32_e32 v101, v71
	v_mov_b32_e32 v103, v71
	v_mov_b32_e32 v105, v71
	v_mov_b32_e32 v107, v71
	v_mov_b32_e32 v109, v71
	v_mov_b32_e32 v111, v71
	v_mov_b32_e32 v113, v71
	v_mov_b32_e32 v115, v71
	v_mov_b32_e32 v117, v71
	v_mov_b32_e32 v119, v71
	v_mov_b32_e32 v121, v71
	v_mov_b32_e32 v123, v71
	v_mov_b32_e32 v125, v71
	v_mov_b32_e32 v127, v71
	v_mov_b32_e32 v129, v71
	v_mov_b32_e32 v131, v71
	v_mov_b32_e32 v133, v71
	v_mov_b32_e32 v135, v71
	v_lshl_add_u64 v[160:161], v[136:137], 0, v[138:139]
	v_lshlrev_b64 v[138:139], 8, v[142:143]
	v_lshlrev_b64 v[142:143], 8, v[144:145]
	v_lshl_add_u64 v[144:145], v[140:141], 0, v[70:71]
	v_lshl_add_u64 v[148:149], v[140:141], 0, v[74:75]
	v_lshl_add_u64 v[150:151], v[140:141], 0, v[76:77]
	v_lshl_add_u64 v[164:165], v[140:141], 0, v[78:79]
	v_lshl_add_u64 v[166:167], v[140:141], 0, v[80:81]
	v_lshl_add_u64 v[168:169], v[140:141], 0, v[82:83]
	v_lshl_add_u64 v[170:171], v[140:141], 0, v[84:85]
	v_lshl_add_u64 v[172:173], v[140:141], 0, v[86:87]
	v_lshl_add_u64 v[174:175], v[140:141], 0, v[88:89]
	v_lshl_add_u64 v[176:177], v[140:141], 0, v[90:91]
	v_lshl_add_u64 v[178:179], v[140:141], 0, v[92:93]
	v_lshl_add_u64 v[180:181], v[140:141], 0, v[94:95]
	v_lshl_add_u64 v[182:183], v[140:141], 0, v[96:97]
	v_lshl_add_u64 v[184:185], v[140:141], 0, v[98:99]
	v_lshl_add_u64 v[186:187], v[140:141], 0, v[100:101]
	v_lshl_add_u64 v[188:189], v[140:141], 0, v[102:103]
	v_lshl_add_u64 v[190:191], v[140:141], 0, v[104:105]
	v_lshl_add_u64 v[192:193], v[140:141], 0, v[106:107]
	v_lshl_add_u64 v[194:195], v[140:141], 0, v[108:109]
	v_lshl_add_u64 v[196:197], v[140:141], 0, v[110:111]
	v_lshl_add_u64 v[198:199], v[140:141], 0, v[112:113]
	v_lshl_add_u64 v[200:201], v[140:141], 0, v[114:115]
	v_lshl_add_u64 v[202:203], v[140:141], 0, v[116:117]
	v_lshl_add_u64 v[204:205], v[140:141], 0, v[118:119]
	v_lshl_add_u64 v[206:207], v[140:141], 0, v[120:121]
	v_lshl_add_u64 v[208:209], v[140:141], 0, v[122:123]
	v_lshl_add_u64 v[210:211], v[140:141], 0, v[124:125]
	v_lshl_add_u64 v[212:213], v[140:141], 0, v[126:127]
	v_lshl_add_u64 v[214:215], v[140:141], 0, v[128:129]
	v_lshl_add_u64 v[216:217], v[140:141], 0, v[130:131]
	v_lshl_add_u64 v[218:219], v[140:141], 0, v[132:133]
	v_lshl_add_u64 v[140:141], v[140:141], 0, v[134:135]
	global_load_dword v25, v[144:145], off nt
	global_load_dword v27, v[148:149], off nt
	global_load_dword v29, v[150:151], off nt
	global_load_dword v31, v[164:165], off nt
	global_load_dword v33, v[166:167], off nt
	global_load_dword v35, v[168:169], off nt
	global_load_dword v37, v[170:171], off nt
	global_load_dword v39, v[172:173], off nt
	global_load_dword v41, v[174:175], off nt
	global_load_dword v43, v[176:177], off nt
	global_load_dword v45, v[178:179], off nt
	global_load_dword v47, v[180:181], off nt
	global_load_dword v49, v[182:183], off nt
	global_load_dword v51, v[184:185], off nt
	global_load_dword v53, v[186:187], off nt
	global_load_dword v55, v[188:189], off nt
	global_load_dword v57, v[190:191], off nt
	global_load_dword v59, v[192:193], off nt
	global_load_dword v61, v[194:195], off nt
	global_load_dword v63, v[196:197], off nt
	global_load_dword v65, v[198:199], off nt
	global_load_dword v67, v[200:201], off nt
	global_load_dword v69, v[202:203], off nt
	global_load_dword v75, v[204:205], off nt
	global_load_dword v77, v[206:207], off nt
	global_load_dword v79, v[208:209], off nt
	global_load_dword v81, v[210:211], off nt
	global_load_dword v83, v[212:213], off nt
	global_load_dword v85, v[214:215], off nt
	global_load_dword v87, v[216:217], off nt
	global_load_dword v89, v[218:219], off nt
	global_load_dword v91, v[140:141], off nt
	v_add_u32_e32 v3, v157, v158
	v_add_u32_e32 v5, v157, v152
	v_add_u32_e32 v7, v157, v153
	v_add_u32_e32 v9, v157, v154
	v_add_u32_e32 v11, v157, v155
	v_add_u32_e32 v13, 0x400, v3
	v_add_u32_e32 v15, 0x400, v5
	v_add_u32_e32 v17, 0x400, v7
	v_add_u32_e32 v19, 0x400, v9
	v_add_u32_e32 v21, 0x400, v11
	v_ashrrev_i32_e32 v147, 31, v146
	v_lshlrev_b64 v[140:141], 8, v[146:147]
	v_lshl_add_u64 v[166:167], v[136:137], 0, v[142:143]
	v_lshl_add_u64 v[168:169], v[136:137], 0, v[140:141]
	v_lshl_add_u64 v[164:165], v[136:137], 0, v[138:139]
	s_add_i32 s5, s5, s84
	s_add_i32 s8, s8, s9
	s_cmp_lt_i32 s5, 8
	s_waitcnt vmcnt(31)
	v_cndmask_b32_e32 v25, 0, v25, vcc
	s_waitcnt vmcnt(30)
	v_cndmask_b32_e32 v27, 0, v27, vcc
	s_waitcnt vmcnt(29)
	v_cndmask_b32_e32 v29, 0, v29, vcc
	s_waitcnt vmcnt(28)
	v_cndmask_b32_e32 v31, 0, v31, vcc
	s_waitcnt vmcnt(27)
	v_cndmask_b32_e32 v33, 0, v33, vcc
	s_waitcnt vmcnt(26)
	v_cndmask_b32_e32 v35, 0, v35, vcc
	s_waitcnt vmcnt(25)
	v_cndmask_b32_e32 v37, 0, v37, vcc
	s_waitcnt vmcnt(24)
	v_cndmask_b32_e32 v39, 0, v39, vcc
	s_waitcnt vmcnt(23)
	v_cndmask_b32_e32 v41, 0, v41, vcc
	s_waitcnt vmcnt(22)
	v_cndmask_b32_e32 v43, 0, v43, vcc
	s_waitcnt vmcnt(21)
	v_cndmask_b32_e32 v45, 0, v45, vcc
	s_waitcnt vmcnt(20)
	v_cndmask_b32_e32 v47, 0, v47, vcc
	s_waitcnt vmcnt(19)
	v_cndmask_b32_e32 v49, 0, v49, vcc
	s_waitcnt vmcnt(18)
	v_cndmask_b32_e32 v51, 0, v51, vcc
	s_waitcnt vmcnt(17)
	v_cndmask_b32_e32 v53, 0, v53, vcc
	s_waitcnt vmcnt(16)
	v_cndmask_b32_e32 v55, 0, v55, vcc
	s_waitcnt vmcnt(15)
	v_cndmask_b32_e32 v57, 0, v57, vcc
	s_waitcnt vmcnt(14)
	v_cndmask_b32_e32 v59, 0, v59, vcc
	s_waitcnt vmcnt(13)
	v_cndmask_b32_e32 v61, 0, v61, vcc
	s_waitcnt vmcnt(12)
	v_cndmask_b32_e32 v63, 0, v63, vcc
	s_waitcnt vmcnt(11)
	v_cndmask_b32_e32 v65, 0, v65, vcc
	s_waitcnt vmcnt(10)
	v_cndmask_b32_e32 v67, 0, v67, vcc
	s_waitcnt vmcnt(9)
	v_cndmask_b32_e32 v69, 0, v69, vcc
	s_waitcnt vmcnt(8)
	v_cndmask_b32_e32 v75, 0, v75, vcc
	s_waitcnt vmcnt(7)
	v_cndmask_b32_e32 v77, 0, v77, vcc
	s_waitcnt vmcnt(6)
	v_cndmask_b32_e32 v79, 0, v79, vcc
	s_waitcnt vmcnt(5)
	v_cndmask_b32_e32 v81, 0, v81, vcc
	s_waitcnt vmcnt(4)
	v_cndmask_b32_e32 v83, 0, v83, vcc
	s_waitcnt vmcnt(3)
	v_cndmask_b32_e32 v85, 0, v85, vcc
	s_waitcnt vmcnt(2)
	v_cndmask_b32_e32 v87, 0, v87, vcc
	s_waitcnt vmcnt(1)
	v_cndmask_b32_e32 v89, 0, v89, vcc
	s_waitcnt vmcnt(0)
	v_cndmask_b32_e32 v91, 0, v91, vcc
	ds_write2_b32 v3, v25, v27 offset1:66
	ds_write2_b32 v3, v29, v31 offset0:132 offset1:198
	ds_write2_b32 v13, v33, v35 offset0:8 offset1:74
	ds_write2_b32 v5, v37, v39 offset1:66
	ds_write2_b32 v5, v41, v43 offset0:132 offset1:198
	ds_write2_b32 v15, v45, v47 offset0:8 offset1:74
	ds_write2_b32 v7, v49, v51 offset1:66
	ds_write2_b32 v7, v53, v55 offset0:132 offset1:198
	ds_write2_b32 v17, v57, v59 offset0:8 offset1:74
	ds_write2_b32 v9, v61, v63 offset1:66
	ds_write2_b32 v9, v65, v67 offset0:132 offset1:198
	ds_write2_b32 v19, v69, v75 offset0:8 offset1:74
	ds_write2_b32 v11, v77, v79 offset1:66
	ds_write2_b32 v11, v81, v83 offset0:132 offset1:198
	ds_write2_b32 v21, v85, v87 offset0:8 offset1:74
	ds_write2_b32 v21, v89, v91 offset0:140 offset1:206
	s_waitcnt lgkmcnt(0)
	ds_read2_b32 v[140:141], v23 offset0:33 offset1:41
	ds_read2_b32 v[142:143], v23 offset1:8
	ds_read2_b32 v[144:145], v23 offset0:66 offset1:74
	ds_read2_b32 v[146:147], v23 offset0:99 offset1:107
	ds_read2_b32 v[148:149], v23 offset0:132 offset1:140
	ds_read2_b32 v[150:151], v23 offset0:165 offset1:173
	ds_read2_b32 v[170:171], v23 offset0:198 offset1:206
	ds_read2_b32 v[172:173], v23 offset0:231 offset1:239
	ds_read2_b32 v[174:175], v23 offset0:49 offset1:57
	ds_read2_b32 v[176:177], v23 offset0:16 offset1:24
	ds_read2_b32 v[178:179], v23 offset0:82 offset1:90
	ds_read2_b32 v[180:181], v23 offset0:115 offset1:123
	ds_read2_b32 v[182:183], v23 offset0:148 offset1:156
	ds_read2_b32 v[184:185], v23 offset0:181 offset1:189
	ds_read2_b32 v[186:187], v23 offset0:214 offset1:222
	ds_read2_b32 v[188:189], v23 offset0:247 offset1:255
	s_waitcnt lgkmcnt(14)
	v_cvt_pk_bf16_f32 v136, v142, v140
	s_waitcnt lgkmcnt(12)
	v_cvt_pk_bf16_f32 v137, v144, v146
	s_waitcnt lgkmcnt(10)
	v_cvt_pk_bf16_f32 v138, v148, v150
	s_waitcnt lgkmcnt(8)
	v_cvt_pk_bf16_f32 v139, v170, v172
	v_cvt_pk_bf16_f32 v140, v143, v141
	v_cvt_pk_bf16_f32 v141, v145, v147
	v_cvt_pk_bf16_f32 v142, v149, v151
	v_cvt_pk_bf16_f32 v143, v171, v173
	s_waitcnt lgkmcnt(6)
	v_cvt_pk_bf16_f32 v144, v176, v174
	s_waitcnt lgkmcnt(4)
	v_cvt_pk_bf16_f32 v145, v178, v180
	s_waitcnt lgkmcnt(2)
	v_cvt_pk_bf16_f32 v146, v182, v184
	s_waitcnt lgkmcnt(0)
	v_cvt_pk_bf16_f32 v147, v186, v188
	v_cvt_pk_bf16_f32 v148, v177, v175
	v_cvt_pk_bf16_f32 v149, v179, v181
	v_cvt_pk_bf16_f32 v150, v183, v185
	v_cvt_pk_bf16_f32 v151, v187, v189
	global_store_dwordx4 v[160:161], v[136:139], off
	global_store_dwordx4 v[164:165], v[140:143], off
	global_store_dwordx4 v[166:167], v[144:147], off
	global_store_dwordx4 v[168:169], v[148:151], off
	s_waitcnt lgkmcnt(0)
	s_cbranch_scc1 .LBB0_95

.LBB0_98:
	s_ashr_i32 s10, s4, 31
	s_lshr_b32 s10, s10, 30
	s_add_i32 s10, s4, s10
	s_ashr_i32 s11, s10, 2
	s_lshl_b32 s10, s11, 6
	s_lshl_b32 s11, s11, 7
	s_sub_i32 s14, s5, s11
	s_ashr_i32 s11, s10, 31
	v_add_u32_e32 v73, s14, v156
	s_lshl_b64 s[12:13], s[10:11], 9
	v_cmp_gt_i32_e32 vcc, s9, v73
	v_lshl_add_u64 v[68:69], s[10:11], 1, v[70:71]
	v_add_u32_e32 v72, s14, v1
	s_add_u32 s10, s0, s12
	v_cndmask_b32_e32 v74, 0, v73, vcc
	v_ashrrev_i32_e32 v73, 31, v72
	v_add_u32_e32 v76, 8, v72
	v_add_u32_e32 v78, 16, v72
	s_addc_u32 s11, s1, s13
	v_ashrrev_i32_e32 v75, 31, v74
	v_add_u32_e32 v80, 24, v72
	v_lshlrev_b64 v[72:73], 8, v[72:73]
	v_ashrrev_i32_e32 v77, 31, v76
	v_ashrrev_i32_e32 v79, 31, v78
	v_lshl_add_u64 v[74:75], v[74:75], 2, s[10:11]
	v_mov_b32_e32 v67, v3
	v_mov_b32_e32 v65, v3
	v_mov_b32_e32 v63, v3
	v_mov_b32_e32 v61, v3
	v_mov_b32_e32 v59, v3
	v_mov_b32_e32 v57, v3
	v_mov_b32_e32 v55, v3
	v_mov_b32_e32 v53, v3
	v_mov_b32_e32 v51, v3
	v_mov_b32_e32 v49, v3
	v_mov_b32_e32 v47, v3
	v_mov_b32_e32 v45, v3
	v_mov_b32_e32 v43, v3
	v_mov_b32_e32 v41, v3
	v_mov_b32_e32 v39, v3
	v_mov_b32_e32 v37, v3
	v_mov_b32_e32 v35, v3
	v_mov_b32_e32 v33, v3
	v_mov_b32_e32 v31, v3
	v_mov_b32_e32 v29, v3
	v_mov_b32_e32 v27, v3
	v_mov_b32_e32 v25, v3
	v_mov_b32_e32 v21, v3
	v_mov_b32_e32 v19, v3
	v_mov_b32_e32 v17, v3
	v_mov_b32_e32 v15, v3
	v_mov_b32_e32 v13, v3
	v_mov_b32_e32 v11, v3
	v_mov_b32_e32 v9, v3
	v_mov_b32_e32 v7, v3
	v_mov_b32_e32 v5, v3
	v_lshl_add_u64 v[88:89], v[68:69], 0, v[72:73]
	v_lshlrev_b64 v[72:73], 8, v[76:77]
	v_lshlrev_b64 v[76:77], 8, v[78:79]
	v_lshl_add_u64 v[78:79], v[74:75], 0, v[2:3]
	v_lshl_add_u64 v[82:83], v[74:75], 0, v[66:67]
	v_lshl_add_u64 v[84:85], v[74:75], 0, v[64:65]
	v_lshl_add_u64 v[86:87], v[74:75], 0, v[62:63]
	v_lshl_add_u64 v[90:91], v[74:75], 0, v[60:61]
	v_lshl_add_u64 v[92:93], v[74:75], 0, v[58:59]
	v_lshl_add_u64 v[94:95], v[74:75], 0, v[56:57]
	v_lshl_add_u64 v[96:97], v[74:75], 0, v[54:55]
	v_lshl_add_u64 v[98:99], v[74:75], 0, v[52:53]
	v_lshl_add_u64 v[100:101], v[74:75], 0, v[50:51]
	v_lshl_add_u64 v[102:103], v[74:75], 0, v[48:49]
	v_lshl_add_u64 v[104:105], v[74:75], 0, v[46:47]
	v_lshl_add_u64 v[106:107], v[74:75], 0, v[44:45]
	v_lshl_add_u64 v[108:109], v[74:75], 0, v[42:43]
	v_lshl_add_u64 v[110:111], v[74:75], 0, v[40:41]
	v_lshl_add_u64 v[112:113], v[74:75], 0, v[38:39]
	v_lshl_add_u64 v[114:115], v[74:75], 0, v[36:37]
	v_lshl_add_u64 v[116:117], v[74:75], 0, v[34:35]
	v_lshl_add_u64 v[118:119], v[74:75], 0, v[32:33]
	v_lshl_add_u64 v[120:121], v[74:75], 0, v[30:31]
	v_lshl_add_u64 v[122:123], v[74:75], 0, v[28:29]
	v_lshl_add_u64 v[124:125], v[74:75], 0, v[26:27]
	v_lshl_add_u64 v[126:127], v[74:75], 0, v[24:25]
	v_lshl_add_u64 v[128:129], v[74:75], 0, v[20:21]
	v_lshl_add_u64 v[130:131], v[74:75], 0, v[18:19]
	v_lshl_add_u64 v[132:133], v[74:75], 0, v[16:17]
	v_lshl_add_u64 v[134:135], v[74:75], 0, v[14:15]
	v_lshl_add_u64 v[136:137], v[74:75], 0, v[12:13]
	v_lshl_add_u64 v[138:139], v[74:75], 0, v[10:11]
	v_lshl_add_u64 v[140:141], v[74:75], 0, v[8:9]
	v_lshl_add_u64 v[142:143], v[74:75], 0, v[6:7]
	v_lshl_add_u64 v[74:75], v[74:75], 0, v[4:5]
	global_load_dword v5, v[78:79], off nt
	global_load_dword v7, v[82:83], off nt
	global_load_dword v9, v[84:85], off nt
	global_load_dword v11, v[86:87], off nt
	global_load_dword v13, v[90:91], off nt
	global_load_dword v15, v[92:93], off nt
	global_load_dword v17, v[94:95], off nt
	global_load_dword v19, v[96:97], off nt
	global_load_dword v21, v[98:99], off nt
	global_load_dword v25, v[100:101], off nt
	global_load_dword v27, v[102:103], off nt
	global_load_dword v29, v[104:105], off nt
	global_load_dword v31, v[106:107], off nt
	global_load_dword v33, v[108:109], off nt
	global_load_dword v35, v[110:111], off nt
	global_load_dword v37, v[112:113], off nt
	global_load_dword v39, v[114:115], off nt
	global_load_dword v41, v[116:117], off nt
	global_load_dword v43, v[118:119], off nt
	global_load_dword v45, v[120:121], off nt
	global_load_dword v47, v[122:123], off nt
	global_load_dword v49, v[124:125], off nt
	global_load_dword v51, v[126:127], off nt
	global_load_dword v53, v[128:129], off nt
	global_load_dword v55, v[130:131], off nt
	global_load_dword v57, v[132:133], off nt
	global_load_dword v59, v[134:135], off nt
	global_load_dword v61, v[136:137], off nt
	global_load_dword v63, v[138:139], off nt
	global_load_dword v65, v[140:141], off nt
	global_load_dword v67, v[142:143], off nt
	global_load_dword v78, v[74:75], off nt
	v_add_u32_e32 v144, v157, v158
	v_add_u32_e32 v145, v157, v152
	v_add_u32_e32 v146, v157, v153
	v_add_u32_e32 v147, v157, v154
	v_add_u32_e32 v148, v157, v155
	v_add_u32_e32 v149, 0x400, v144
	v_add_u32_e32 v150, 0x400, v145
	v_add_u32_e32 v151, 0x400, v146
	v_add_u32_e32 v159, 0x400, v147
	v_add_u32_e32 v160, 0x400, v148
	v_lshl_add_u64 v[90:91], v[68:69], 0, v[72:73]
	v_ashrrev_i32_e32 v81, 31, v80
	v_lshlrev_b64 v[74:75], 8, v[80:81]
	v_lshl_add_u64 v[92:93], v[68:69], 0, v[76:77]
	v_lshl_add_u64 v[68:69], v[68:69], 0, v[74:75]
	s_add_i32 s4, s4, s84
	s_add_i32 s5, s5, s8
	s_cmp_lt_i32 s4, 8
	s_waitcnt vmcnt(31)
	v_cndmask_b32_e32 v5, 0, v5, vcc
	s_waitcnt vmcnt(30)
	v_cndmask_b32_e32 v7, 0, v7, vcc
	s_waitcnt vmcnt(29)
	v_cndmask_b32_e32 v9, 0, v9, vcc
	s_waitcnt vmcnt(28)
	v_cndmask_b32_e32 v11, 0, v11, vcc
	s_waitcnt vmcnt(27)
	v_cndmask_b32_e32 v13, 0, v13, vcc
	s_waitcnt vmcnt(26)
	v_cndmask_b32_e32 v15, 0, v15, vcc
	s_waitcnt vmcnt(25)
	v_cndmask_b32_e32 v17, 0, v17, vcc
	s_waitcnt vmcnt(24)
	v_cndmask_b32_e32 v19, 0, v19, vcc
	s_waitcnt vmcnt(23)
	v_cndmask_b32_e32 v21, 0, v21, vcc
	s_waitcnt vmcnt(22)
	v_cndmask_b32_e32 v25, 0, v25, vcc
	s_waitcnt vmcnt(21)
	v_cndmask_b32_e32 v27, 0, v27, vcc
	s_waitcnt vmcnt(20)
	v_cndmask_b32_e32 v29, 0, v29, vcc
	s_waitcnt vmcnt(19)
	v_cndmask_b32_e32 v31, 0, v31, vcc
	s_waitcnt vmcnt(18)
	v_cndmask_b32_e32 v33, 0, v33, vcc
	s_waitcnt vmcnt(17)
	v_cndmask_b32_e32 v35, 0, v35, vcc
	s_waitcnt vmcnt(16)
	v_cndmask_b32_e32 v37, 0, v37, vcc
	s_waitcnt vmcnt(15)
	v_cndmask_b32_e32 v39, 0, v39, vcc
	s_waitcnt vmcnt(14)
	v_cndmask_b32_e32 v41, 0, v41, vcc
	s_waitcnt vmcnt(13)
	v_cndmask_b32_e32 v43, 0, v43, vcc
	s_waitcnt vmcnt(12)
	v_cndmask_b32_e32 v45, 0, v45, vcc
	s_waitcnt vmcnt(11)
	v_cndmask_b32_e32 v47, 0, v47, vcc
	s_waitcnt vmcnt(10)
	v_cndmask_b32_e32 v49, 0, v49, vcc
	s_waitcnt vmcnt(9)
	v_cndmask_b32_e32 v51, 0, v51, vcc
	s_waitcnt vmcnt(8)
	v_cndmask_b32_e32 v53, 0, v53, vcc
	s_waitcnt vmcnt(7)
	v_cndmask_b32_e32 v55, 0, v55, vcc
	s_waitcnt vmcnt(6)
	v_cndmask_b32_e32 v57, 0, v57, vcc
	s_waitcnt vmcnt(5)
	v_cndmask_b32_e32 v59, 0, v59, vcc
	s_waitcnt vmcnt(4)
	v_cndmask_b32_e32 v61, 0, v61, vcc
	s_waitcnt vmcnt(3)
	v_cndmask_b32_e32 v63, 0, v63, vcc
	s_waitcnt vmcnt(2)
	v_cndmask_b32_e32 v65, 0, v65, vcc
	s_waitcnt vmcnt(1)
	v_cndmask_b32_e32 v67, 0, v67, vcc
	s_waitcnt vmcnt(0)
	v_cndmask_b32_e32 v72, 0, v78, vcc
	ds_write2_b32 v144, v5, v7 offset1:66
	ds_write2_b32 v144, v9, v11 offset0:132 offset1:198
	ds_write2_b32 v149, v13, v15 offset0:8 offset1:74
	ds_write2_b32 v145, v17, v19 offset1:66
	ds_write2_b32 v145, v21, v25 offset0:132 offset1:198
	ds_write2_b32 v150, v27, v29 offset0:8 offset1:74
	ds_write2_b32 v146, v31, v33 offset1:66
	ds_write2_b32 v146, v35, v37 offset0:132 offset1:198
	ds_write2_b32 v151, v39, v41 offset0:8 offset1:74
	ds_write2_b32 v147, v43, v45 offset1:66
	ds_write2_b32 v147, v47, v49 offset0:132 offset1:198
	ds_write2_b32 v159, v51, v53 offset0:8 offset1:74
	ds_write2_b32 v148, v55, v57 offset1:66
	ds_write2_b32 v148, v59, v61 offset0:132 offset1:198
	ds_write2_b32 v160, v63, v65 offset0:8 offset1:74
	ds_write2_b32 v160, v67, v72 offset0:140 offset1:206
	s_waitcnt lgkmcnt(0)
	ds_read2_b32 v[76:77], v23 offset0:33 offset1:41
	ds_read2_b32 v[78:79], v23 offset1:8
	ds_read2_b32 v[80:81], v23 offset0:66 offset1:74
	ds_read2_b32 v[82:83], v23 offset0:99 offset1:107
	ds_read2_b32 v[84:85], v23 offset0:132 offset1:140
	ds_read2_b32 v[86:87], v23 offset0:165 offset1:173
	ds_read2_b32 v[94:95], v23 offset0:198 offset1:206
	ds_read2_b32 v[96:97], v23 offset0:231 offset1:239
	ds_read2_b32 v[98:99], v23 offset0:49 offset1:57
	ds_read2_b32 v[100:101], v23 offset0:16 offset1:24
	ds_read2_b32 v[102:103], v23 offset0:82 offset1:90
	ds_read2_b32 v[104:105], v23 offset0:115 offset1:123
	ds_read2_b32 v[106:107], v23 offset0:148 offset1:156
	ds_read2_b32 v[108:109], v23 offset0:181 offset1:189
	ds_read2_b32 v[110:111], v23 offset0:214 offset1:222
	ds_read2_b32 v[112:113], v23 offset0:247 offset1:255
	s_waitcnt lgkmcnt(14)
	v_cvt_pk_bf16_f32 v72, v78, v76
	s_waitcnt lgkmcnt(12)
	v_cvt_pk_bf16_f32 v73, v80, v82
	s_waitcnt lgkmcnt(10)
	v_cvt_pk_bf16_f32 v74, v84, v86
	s_waitcnt lgkmcnt(8)
	v_cvt_pk_bf16_f32 v75, v94, v96
	v_cvt_pk_bf16_f32 v76, v79, v77
	v_cvt_pk_bf16_f32 v77, v81, v83
	v_cvt_pk_bf16_f32 v78, v85, v87
	v_cvt_pk_bf16_f32 v79, v95, v97
	s_waitcnt lgkmcnt(6)
	v_cvt_pk_bf16_f32 v80, v100, v98
	s_waitcnt lgkmcnt(4)
	v_cvt_pk_bf16_f32 v81, v102, v104
	s_waitcnt lgkmcnt(2)
	v_cvt_pk_bf16_f32 v82, v106, v108
	s_waitcnt lgkmcnt(0)
	v_cvt_pk_bf16_f32 v83, v110, v112
	v_cvt_pk_bf16_f32 v84, v101, v99
	v_cvt_pk_bf16_f32 v85, v103, v105
	v_cvt_pk_bf16_f32 v86, v107, v109
	v_cvt_pk_bf16_f32 v87, v111, v113
	global_store_dwordx4 v[88:89], v[72:75], off
	global_store_dwordx4 v[90:91], v[76:79], off
	global_store_dwordx4 v[92:93], v[80:83], off
	global_store_dwordx4 v[68:69], v[84:87], off
	s_waitcnt lgkmcnt(0)
	s_cbranch_scc1 .LBB0_98

.LBB0_101:
	global_load_dword v2, v[4:5], off nt
	global_load_dword v8, v[6:7], off nt
	v_add_u32_e32 v1, 64, v1
	v_cmp_lt_u32_e32 vcc, s10, v1
	v_lshl_add_u64 v[4:5], v[4:5], 0, s[4:5]
	v_lshl_add_u64 v[6:7], v[6:7], 0, s[8:9]
	s_or_b64 s[0:1], vcc, s[0:1]
	s_waitcnt vmcnt(0)
	v_fmac_f32_e32 v3, v2, v8
	s_andn2_b64 exec, exec, s[0:1]
	s_cbranch_execnz .LBB0_101
	s_or_b64 exec, exec, s[0:1]
	v_mbcnt_lo_u32_b32 v1, -1, 0
	v_mbcnt_hi_u32_b32 v2, -1, v1
	v_and_b32_e32 v1, 64, v2
	v_add_u32_e32 v4, 64, v1
	v_xor_b32_e32 v1, 1, v2
	v_cmp_lt_i32_e32 vcc, v1, v4
	v_xor_b32_e32 v5, 2, v2
	s_nop 0
	v_cndmask_b32_e32 v1, v2, v1, vcc
	v_lshlrev_b32_e32 v1, 2, v1
	ds_bpermute_b32 v1, v1, v3
	v_cmp_lt_i32_e32 vcc, v5, v4
	s_waitcnt lgkmcnt(0)
	v_add_f32_e32 v1, v3, v1
	v_cndmask_b32_e32 v3, v2, v5, vcc
	v_lshlrev_b32_e32 v3, 2, v3
	ds_bpermute_b32 v3, v3, v1
	v_xor_b32_e32 v5, 4, v2
	v_cmp_lt_i32_e32 vcc, v5, v4
	s_waitcnt lgkmcnt(0)
	v_add_f32_e32 v1, v1, v3
	v_cndmask_b32_e32 v3, v2, v5, vcc
	v_lshlrev_b32_e32 v3, 2, v3
	ds_bpermute_b32 v3, v3, v1
	v_xor_b32_e32 v5, 8, v2
	v_cmp_lt_i32_e32 vcc, v5, v4
	s_waitcnt lgkmcnt(0)
	v_add_f32_e32 v1, v1, v3
	v_cndmask_b32_e32 v3, v2, v5, vcc
	v_lshlrev_b32_e32 v3, 2, v3
	ds_bpermute_b32 v3, v3, v1
	v_xor_b32_e32 v5, 16, v2
	v_cmp_lt_i32_e32 vcc, v5, v4
	s_waitcnt lgkmcnt(0)
	v_add_f32_e32 v1, v1, v3
	v_cndmask_b32_e32 v3, v2, v5, vcc
	v_lshlrev_b32_e32 v3, 2, v3
	ds_bpermute_b32 v3, v3, v1
	v_xor_b32_e32 v5, 32, v2
	v_cmp_lt_i32_e32 vcc, v5, v4
	s_waitcnt lgkmcnt(0)
	v_add_f32_e32 v1, v1, v3
	v_cndmask_b32_e32 v2, v2, v5, vcc
	v_lshlrev_b32_e32 v2, 2, v2
	ds_bpermute_b32 v2, v2, v1
	v_cmp_eq_u32_e32 vcc, 0, v162
	s_and_saveexec_b64 s[0:1], vcc
	s_cbranch_execz .LBB0_104
	s_ashr_i32 s87, s86, 31
	s_lshl_b64 s[4:5], s[86:87], 2
	s_add_u32 s4, s94, s4
	s_addc_u32 s5, s95, s5
	s_waitcnt lgkmcnt(0)
	v_add_f32_e32 v1, v1, v2
	v_mov_b32_e32 v2, 0x81e00000
	global_store_dword v2, v1, s[4:5]
